# v027 minus every s_setprio in the ten K-loops (MFMA half no longer raised over the load half; 8 bytes per block removed)
# speedup vs baseline: 1.0083x; 1.0079x over previous
.LBB0_323:
	s_add_u32 s26, s24, 0xfffc0080
	s_addc_u32 s27, s25, -1
	s_add_i32 s36, 0, 0x10000
	s_cmp_eq_u32 s21, 12
	s_cselect_b32 s57, s17, s27
	s_cselect_b32 s56, s16, s26
	v_add_u32_e32 v142, s36, v161
	s_cselect_b32 s27, s19, s15
	s_cselect_b32 s26, s18, s13
	s_add_i32 s38, 0, 0x14000
	ds_read_b128 v[144:147], v142
	ds_read_b128 v[148:151], v142 offset:1024
	ds_read_b128 v[152:155], v142 offset:2048
	ds_read_b128 v[178:181], v142 offset:3072
	v_add_u32_e32 v142, s38, v161
	ds_read_b128 v[182:185], v142
	ds_read_b128 v[186:189], v142 offset:1024
	ds_read_b128 v[190:193], v142 offset:2048
	ds_read_b128 v[194:197], v142 offset:3072
	v_lshl_add_u64 v[156:157], s[24:25], 0, v[140:141]
	s_add_i32 m0, s68, 0xc000
	ds_read_b128 v[198:201], v177
	ds_read_b128 v[202:205], v177 offset:1024
	ds_read_b128 v[206:209], v177 offset:2048
	ds_read_b128 v[210:213], v177 offset:3072
	ds_read_b128 v[214:217], v177 offset:4096
	ds_read_b128 v[222:225], v177 offset:5120
	ds_read_b128 v[226:229], v177 offset:6144
	ds_read_b128 v[230:233], v177 offset:7168
	global_load_lds_dwordx4 v[156:157], off
	v_lshl_add_u64 v[156:157], s[24:25], 0, v[138:139]
	s_add_i32 m0, s68, 0xe000
	s_nop 0
	global_load_lds_dwordx4 v[156:157], off
	s_waitcnt vmcnt(8)
	s_waitcnt lgkmcnt(0)
	s_barrier
	v_mfma_i32_16x16x64_i8 v[126:129], v[144:147], v[198:201], v[126:129]
	v_mfma_i32_16x16x64_i8 v[118:121], v[152:155], v[198:201], v[118:121]
	v_mfma_i32_16x16x64_i8 v[110:113], v[144:147], v[206:209], v[110:113]
	v_mfma_i32_16x16x64_i8 v[102:105], v[152:155], v[206:209], v[102:105]
	v_mfma_i32_16x16x64_i8 v[94:97], v[144:147], v[214:217], v[94:97]
	v_mfma_i32_16x16x64_i8 v[86:89], v[152:155], v[214:217], v[86:89]
	v_mfma_i32_16x16x64_i8 v[78:81], v[144:147], v[226:229], v[78:81]
	v_mfma_i32_16x16x64_i8 v[70:73], v[152:155], v[226:229], v[70:73]
	v_mfma_i32_16x16x64_i8 v[126:129], v[148:151], v[202:205], v[126:129]
	v_mfma_i32_16x16x64_i8 v[118:121], v[178:181], v[202:205], v[118:121]
	v_mfma_i32_16x16x64_i8 v[110:113], v[148:151], v[210:213], v[110:113]
	v_mfma_i32_16x16x64_i8 v[102:105], v[178:181], v[210:213], v[102:105]
	v_mfma_i32_16x16x64_i8 v[94:97], v[148:151], v[222:225], v[94:97]
	v_mfma_i32_16x16x64_i8 v[86:89], v[178:181], v[222:225], v[86:89]
	v_mfma_i32_16x16x64_i8 v[78:81], v[148:151], v[230:233], v[78:81]
	v_mfma_i32_16x16x64_i8 v[70:73], v[178:181], v[230:233], v[70:73]
	v_mfma_i32_16x16x64_i8 v[122:125], v[182:185], v[198:201], v[122:125]
	v_mfma_i32_16x16x64_i8 v[114:117], v[190:193], v[198:201], v[114:117]
	v_mfma_i32_16x16x64_i8 v[106:109], v[182:185], v[206:209], v[106:109]
	v_mfma_i32_16x16x64_i8 v[98:101], v[190:193], v[206:209], v[98:101]
	v_mfma_i32_16x16x64_i8 v[90:93], v[182:185], v[214:217], v[90:93]
	v_mfma_i32_16x16x64_i8 v[82:85], v[190:193], v[214:217], v[82:85]
	v_mfma_i32_16x16x64_i8 v[74:77], v[182:185], v[226:229], v[74:77]
	v_mfma_i32_16x16x64_i8 v[66:69], v[190:193], v[226:229], v[66:69]
	v_mfma_i32_16x16x64_i8 v[122:125], v[186:189], v[202:205], v[122:125]
	v_mfma_i32_16x16x64_i8 v[114:117], v[194:197], v[202:205], v[114:117]
	v_mfma_i32_16x16x64_i8 v[106:109], v[186:189], v[210:213], v[106:109]
	v_mfma_i32_16x16x64_i8 v[98:101], v[194:197], v[210:213], v[98:101]
	v_mfma_i32_16x16x64_i8 v[90:93], v[186:189], v[222:225], v[90:93]
	v_mfma_i32_16x16x64_i8 v[82:85], v[194:197], v[222:225], v[82:85]
	v_mfma_i32_16x16x64_i8 v[74:77], v[186:189], v[230:233], v[74:77]
	v_mfma_i32_16x16x64_i8 v[66:69], v[194:197], v[230:233], v[66:69]
	s_barrier
	s_add_i32 s36, s36, s23
	v_lshl_add_u64 v[156:157], s[26:27], 0, v[162:163]
	s_mov_b32 m0, s36
	ds_read_b128 v[198:201], v177 offset:16384
	ds_read_b128 v[202:205], v177 offset:17408
	ds_read_b128 v[206:209], v177 offset:18432
	ds_read_b128 v[210:213], v177 offset:19456
	ds_read_b128 v[214:217], v177 offset:20480
	ds_read_b128 v[222:225], v177 offset:21504
	ds_read_b128 v[226:229], v177 offset:22528
	ds_read_b128 v[230:233], v177 offset:23552
	global_load_lds_dwordx4 v[156:157], off
	s_add_i32 m0, s36, 0x2000
	s_add_u32 s36, s26, 0x80000
	v_lshl_add_u64 v[174:175], s[26:27], 0, v[134:135]
	s_addc_u32 s37, s27, 0
	s_add_i32 s38, s38, s23
	global_load_lds_dwordx4 v[174:175], off
	v_lshl_add_u64 v[234:235], s[36:37], 0, v[162:163]
	s_mov_b32 m0, s38
	v_lshl_add_u64 v[236:237], s[56:57], 0, v[132:133]
	global_load_lds_dwordx4 v[234:235], off
	v_lshl_add_u64 v[234:235], s[36:37], 0, v[134:135]
	s_add_i32 m0, s38, 0x2000
	s_nop 0
	global_load_lds_dwordx4 v[234:235], off
	v_lshl_add_u64 v[234:235], s[56:57], 0, v[130:131]
	s_mov_b32 m0, s68
	s_nop 0
	global_load_lds_dwordx4 v[234:235], off
	s_mov_b32 m0, s69
	s_nop 0
	global_load_lds_dwordx4 v[236:237], off
	s_waitcnt vmcnt(8)
	s_waitcnt lgkmcnt(0)
	s_barrier
	v_mfma_i32_16x16x64_i8 v[62:65], v[144:147], v[198:201], v[62:65]
	v_mfma_i32_16x16x64_i8 v[54:57], v[152:155], v[198:201], v[54:57]
	v_mfma_i32_16x16x64_i8 v[46:49], v[144:147], v[206:209], v[46:49]
	v_mfma_i32_16x16x64_i8 v[38:41], v[152:155], v[206:209], v[38:41]
	v_mfma_i32_16x16x64_i8 v[30:33], v[144:147], v[214:217], v[30:33]
	v_mfma_i32_16x16x64_i8 v[22:25], v[152:155], v[214:217], v[22:25]
	v_mfma_i32_16x16x64_i8 v[14:17], v[144:147], v[226:229], v[14:17]
	v_mfma_i32_16x16x64_i8 v[6:9], v[152:155], v[226:229], v[6:9]
	v_mfma_i32_16x16x64_i8 v[62:65], v[148:151], v[202:205], v[62:65]
	v_mfma_i32_16x16x64_i8 v[54:57], v[178:181], v[202:205], v[54:57]
	v_mfma_i32_16x16x64_i8 v[46:49], v[148:151], v[210:213], v[46:49]
	v_mfma_i32_16x16x64_i8 v[38:41], v[178:181], v[210:213], v[38:41]
	v_mfma_i32_16x16x64_i8 v[30:33], v[148:151], v[222:225], v[30:33]
	v_mfma_i32_16x16x64_i8 v[22:25], v[178:181], v[222:225], v[22:25]
	v_mfma_i32_16x16x64_i8 v[14:17], v[148:151], v[230:233], v[14:17]
	v_mfma_i32_16x16x64_i8 v[6:9], v[178:181], v[230:233], v[6:9]
	v_mfma_i32_16x16x64_i8 v[58:61], v[182:185], v[198:201], v[58:61]
	v_mfma_i32_16x16x64_i8 v[50:53], v[190:193], v[198:201], v[50:53]
	v_mfma_i32_16x16x64_i8 v[42:45], v[182:185], v[206:209], v[42:45]
	v_mfma_i32_16x16x64_i8 v[34:37], v[190:193], v[206:209], v[34:37]
	v_mfma_i32_16x16x64_i8 v[26:29], v[182:185], v[214:217], v[26:29]
	v_mfma_i32_16x16x64_i8 v[18:21], v[190:193], v[214:217], v[18:21]
	v_mfma_i32_16x16x64_i8 v[10:13], v[182:185], v[226:229], v[10:13]
	v_mfma_i32_16x16x64_i8 v[2:5], v[190:193], v[226:229], v[2:5]
	v_mfma_i32_16x16x64_i8 v[58:61], v[186:189], v[202:205], v[58:61]
	v_mfma_i32_16x16x64_i8 v[50:53], v[194:197], v[202:205], v[50:53]
	v_mfma_i32_16x16x64_i8 v[42:45], v[186:189], v[210:213], v[42:45]
	v_mfma_i32_16x16x64_i8 v[34:37], v[194:197], v[210:213], v[34:37]
	v_mfma_i32_16x16x64_i8 v[26:29], v[186:189], v[222:225], v[26:29]
	v_mfma_i32_16x16x64_i8 v[18:21], v[194:197], v[222:225], v[18:21]
	v_mfma_i32_16x16x64_i8 v[10:13], v[186:189], v[230:233], v[10:13]
	v_mfma_i32_16x16x64_i8 v[2:5], v[194:197], v[230:233], v[2:5]
	s_barrier
	s_add_i32 s38, 0, 0x18000
	v_add_u32_e32 v142, s38, v161
	s_add_i32 s39, 0, 0x1c000
	ds_read_b128 v[144:147], v142
	ds_read_b128 v[148:151], v142 offset:1024
	ds_read_b128 v[152:155], v142 offset:2048
	ds_read_b128 v[178:181], v142 offset:3072
	v_add_u32_e32 v142, s39, v161
	ds_read_b128 v[182:185], v142
	ds_read_b128 v[186:189], v142 offset:1024
	ds_read_b128 v[190:193], v142 offset:2048
	ds_read_b128 v[194:197], v142 offset:3072
	s_add_u32 s36, s56, 0x40000
	s_addc_u32 s37, s57, 0
	s_mov_b32 m0, s70
	v_lshl_add_u64 v[238:239], s[36:37], 0, v[130:131]
	ds_read_b128 v[198:201], v177 offset:32768
	ds_read_b128 v[202:205], v177 offset:33792
	ds_read_b128 v[206:209], v177 offset:34816
	ds_read_b128 v[210:213], v177 offset:35840
	ds_read_b128 v[214:217], v177 offset:36864
	ds_read_b128 v[222:225], v177 offset:37888
	ds_read_b128 v[226:229], v177 offset:38912
	ds_read_b128 v[230:233], v177 offset:39936
	global_load_lds_dwordx4 v[238:239], off
	v_lshl_add_u64 v[238:239], s[36:37], 0, v[132:133]
	s_mov_b32 m0, s71
	s_nop 0
	global_load_lds_dwordx4 v[238:239], off
	s_waitcnt vmcnt(8)
	s_waitcnt lgkmcnt(0)
	s_barrier
	v_mfma_i32_16x16x64_i8 v[126:129], v[144:147], v[198:201], v[126:129]
	v_mfma_i32_16x16x64_i8 v[118:121], v[152:155], v[198:201], v[118:121]
	v_mfma_i32_16x16x64_i8 v[110:113], v[144:147], v[206:209], v[110:113]
	v_mfma_i32_16x16x64_i8 v[102:105], v[152:155], v[206:209], v[102:105]
	v_mfma_i32_16x16x64_i8 v[94:97], v[144:147], v[214:217], v[94:97]
	v_mfma_i32_16x16x64_i8 v[86:89], v[152:155], v[214:217], v[86:89]
	v_mfma_i32_16x16x64_i8 v[78:81], v[144:147], v[226:229], v[78:81]
	v_mfma_i32_16x16x64_i8 v[70:73], v[152:155], v[226:229], v[70:73]
	v_mfma_i32_16x16x64_i8 v[126:129], v[148:151], v[202:205], v[126:129]
	v_mfma_i32_16x16x64_i8 v[118:121], v[178:181], v[202:205], v[118:121]
	v_mfma_i32_16x16x64_i8 v[110:113], v[148:151], v[210:213], v[110:113]
	v_mfma_i32_16x16x64_i8 v[102:105], v[178:181], v[210:213], v[102:105]
	v_mfma_i32_16x16x64_i8 v[94:97], v[148:151], v[222:225], v[94:97]
	v_mfma_i32_16x16x64_i8 v[86:89], v[178:181], v[222:225], v[86:89]
	v_mfma_i32_16x16x64_i8 v[78:81], v[148:151], v[230:233], v[78:81]
	v_mfma_i32_16x16x64_i8 v[70:73], v[178:181], v[230:233], v[70:73]
	v_mfma_i32_16x16x64_i8 v[122:125], v[182:185], v[198:201], v[122:125]
	v_mfma_i32_16x16x64_i8 v[114:117], v[190:193], v[198:201], v[114:117]
	v_mfma_i32_16x16x64_i8 v[106:109], v[182:185], v[206:209], v[106:109]
	v_mfma_i32_16x16x64_i8 v[98:101], v[190:193], v[206:209], v[98:101]
	v_mfma_i32_16x16x64_i8 v[90:93], v[182:185], v[214:217], v[90:93]
	v_mfma_i32_16x16x64_i8 v[82:85], v[190:193], v[214:217], v[82:85]
	v_mfma_i32_16x16x64_i8 v[74:77], v[182:185], v[226:229], v[74:77]
	v_mfma_i32_16x16x64_i8 v[66:69], v[190:193], v[226:229], v[66:69]
	v_mfma_i32_16x16x64_i8 v[122:125], v[186:189], v[202:205], v[122:125]
	v_mfma_i32_16x16x64_i8 v[114:117], v[194:197], v[202:205], v[114:117]
	v_mfma_i32_16x16x64_i8 v[106:109], v[186:189], v[210:213], v[106:109]
	v_mfma_i32_16x16x64_i8 v[98:101], v[194:197], v[210:213], v[98:101]
	v_mfma_i32_16x16x64_i8 v[90:93], v[186:189], v[222:225], v[90:93]
	v_mfma_i32_16x16x64_i8 v[82:85], v[194:197], v[222:225], v[82:85]
	v_mfma_i32_16x16x64_i8 v[74:77], v[186:189], v[230:233], v[74:77]
	v_mfma_i32_16x16x64_i8 v[66:69], v[194:197], v[230:233], v[66:69]
	s_barrier
	s_add_i32 s36, s38, s23
	v_lshl_add_u64 v[156:157], v[156:157], 0, s[44:45]
	s_mov_b32 m0, s36
	ds_read_b128 v[198:201], v177 offset:49152
	ds_read_b128 v[202:205], v177 offset:50176
	ds_read_b128 v[206:209], v177 offset:51200
	ds_read_b128 v[210:213], v177 offset:52224
	ds_read_b128 v[214:217], v177 offset:53248
	ds_read_b128 v[222:225], v177 offset:54272
	ds_read_b128 v[226:229], v177 offset:55296
	ds_read_b128 v[230:233], v177 offset:56320
	global_load_lds_dwordx4 v[156:157], off
	s_add_i32 m0, s36, 0x2000
	s_add_u32 s26, s26, 0x80080
	v_lshl_add_u64 v[156:157], v[174:175], 0, s[44:45]
	s_addc_u32 s27, s27, 0
	s_add_i32 s36, s39, s23
	global_load_lds_dwordx4 v[156:157], off
	v_lshl_add_u64 v[156:157], s[26:27], 0, v[162:163]
	s_mov_b32 m0, s36
	s_nop 0
	global_load_lds_dwordx4 v[156:157], off
	v_lshl_add_u64 v[156:157], s[26:27], 0, v[134:135]
	s_add_i32 m0, s36, 0x2000
	s_nop 0
	global_load_lds_dwordx4 v[156:157], off
	v_lshl_add_u64 v[156:157], v[234:235], 0, s[44:45]
	s_mov_b32 m0, s72
	s_nop 0
	global_load_lds_dwordx4 v[156:157], off
	v_lshl_add_u64 v[156:157], v[236:237], 0, s[44:45]
	s_mov_b32 m0, s73
	s_nop 0
	global_load_lds_dwordx4 v[156:157], off
	s_waitcnt vmcnt(8)
	s_waitcnt lgkmcnt(0)
	s_barrier
	v_mfma_i32_16x16x64_i8 v[62:65], v[144:147], v[198:201], v[62:65]
	v_mfma_i32_16x16x64_i8 v[54:57], v[152:155], v[198:201], v[54:57]
	v_mfma_i32_16x16x64_i8 v[46:49], v[144:147], v[206:209], v[46:49]
	v_mfma_i32_16x16x64_i8 v[38:41], v[152:155], v[206:209], v[38:41]
	v_mfma_i32_16x16x64_i8 v[30:33], v[144:147], v[214:217], v[30:33]
	v_mfma_i32_16x16x64_i8 v[22:25], v[152:155], v[214:217], v[22:25]
	v_mfma_i32_16x16x64_i8 v[14:17], v[144:147], v[226:229], v[14:17]
	v_mfma_i32_16x16x64_i8 v[6:9], v[152:155], v[226:229], v[6:9]
	v_mfma_i32_16x16x64_i8 v[62:65], v[148:151], v[202:205], v[62:65]
	v_mfma_i32_16x16x64_i8 v[54:57], v[178:181], v[202:205], v[54:57]
	v_mfma_i32_16x16x64_i8 v[46:49], v[148:151], v[210:213], v[46:49]
	v_mfma_i32_16x16x64_i8 v[38:41], v[178:181], v[210:213], v[38:41]
	v_mfma_i32_16x16x64_i8 v[30:33], v[148:151], v[222:225], v[30:33]
	v_mfma_i32_16x16x64_i8 v[22:25], v[178:181], v[222:225], v[22:25]
	v_mfma_i32_16x16x64_i8 v[14:17], v[148:151], v[230:233], v[14:17]
	v_mfma_i32_16x16x64_i8 v[6:9], v[178:181], v[230:233], v[6:9]
	v_mfma_i32_16x16x64_i8 v[58:61], v[182:185], v[198:201], v[58:61]
	v_mfma_i32_16x16x64_i8 v[50:53], v[190:193], v[198:201], v[50:53]
	v_mfma_i32_16x16x64_i8 v[42:45], v[182:185], v[206:209], v[42:45]
	v_mfma_i32_16x16x64_i8 v[34:37], v[190:193], v[206:209], v[34:37]
	v_mfma_i32_16x16x64_i8 v[26:29], v[182:185], v[214:217], v[26:29]
	v_mfma_i32_16x16x64_i8 v[18:21], v[190:193], v[214:217], v[18:21]
	v_mfma_i32_16x16x64_i8 v[10:13], v[182:185], v[226:229], v[10:13]
	v_mfma_i32_16x16x64_i8 v[2:5], v[190:193], v[226:229], v[2:5]
	v_mfma_i32_16x16x64_i8 v[58:61], v[186:189], v[202:205], v[58:61]
	v_mfma_i32_16x16x64_i8 v[50:53], v[194:197], v[202:205], v[50:53]
	v_mfma_i32_16x16x64_i8 v[42:45], v[186:189], v[210:213], v[42:45]
	v_mfma_i32_16x16x64_i8 v[34:37], v[194:197], v[210:213], v[34:37]
	v_mfma_i32_16x16x64_i8 v[26:29], v[186:189], v[222:225], v[26:29]
	v_mfma_i32_16x16x64_i8 v[18:21], v[194:197], v[222:225], v[18:21]
	v_mfma_i32_16x16x64_i8 v[10:13], v[186:189], v[230:233], v[10:13]
	v_mfma_i32_16x16x64_i8 v[2:5], v[194:197], v[230:233], v[2:5]
	s_barrier
	s_add_i32 s21, s21, 2
	s_add_u32 s13, s13, 0x100
	s_addc_u32 s15, s15, 0
	s_add_u32 s24, s24, 0x100
	s_addc_u32 s25, s25, 0
	s_cmp_gt_u32 s21, 13
	s_cbranch_scc0 .LBB0_323
	s_and_b64 vcc, exec, s[10:11]
	s_cbranch_vccz .LBB0_326
	s_barrier

.LBB0_437:
	s_add_u32 s26, s24, 0x4000
	s_addc_u32 s27, s25, 0
	s_cmpk_eq_i32 s82, 0x54
	s_cselect_b32 s58, s20, s26
	s_cselect_b32 s59, s21, s27
	s_cselect_b32 s56, s22, s80
	s_cselect_b32 s57, s23, s81
	s_add_u32 s26, s58, 0x8000
	s_addc_u32 s27, s59, 0
	s_add_i32 s36, 0, 0x10000
	s_add_i32 s38, 0, 0x14000
	v_add_u32_e32 v126, s36, v197
	v_add_u32_e32 v168, s38, v197
	ds_read_b128 v[114:117], v126
	ds_read_b128 v[118:121], v126 offset:1024
	ds_read_b128 v[122:125], v126 offset:2048
	ds_read_b128 v[126:129], v126 offset:3072
	ds_read_b128 v[138:141], v168
	ds_read_b128 v[142:145], v168 offset:1024
	ds_read_b128 v[154:157], v168 offset:2048
	ds_read_b128 v[178:181], v168 offset:3072
	v_lshl_add_u64 v[194:195], s[24:25], 0, v[176:177]
	s_add_i32 m0, s63, 0xc000
	ds_read_b128 v[182:185], v199
	ds_read_b128 v[186:189], v199 offset:1024
	ds_read_b128 v[190:193], v199 offset:2048
	ds_read_b128 v[200:203], v199 offset:3072
	ds_read_b128 v[204:207], v199 offset:4096
	ds_read_b128 v[208:211], v199 offset:5120
	ds_read_b128 v[212:215], v199 offset:6144
	ds_read_b128 v[222:225], v199 offset:7168
	global_load_lds_dwordx4 v[194:195], off
	v_lshl_add_u64 v[194:195], s[24:25], 0, v[174:175]
	s_add_i32 m0, s63, 0xe000
	s_nop 0
	global_load_lds_dwordx4 v[194:195], off
	s_waitcnt vmcnt(8)
	s_waitcnt lgkmcnt(0)
	s_barrier
	v_mfma_f32_16x16x32_bf16 v[150:153], v[114:117], v[182:185], v[150:153]
	v_mfma_f32_16x16x32_bf16 v[146:149], v[122:125], v[182:185], v[146:149]
	v_mfma_f32_16x16x32_bf16 v[110:113], v[114:117], v[190:193], v[110:113]
	v_mfma_f32_16x16x32_bf16 v[106:109], v[122:125], v[190:193], v[106:109]
	v_mfma_f32_16x16x32_bf16 v[94:97], v[114:117], v[204:207], v[94:97]
	v_mfma_f32_16x16x32_bf16 v[90:93], v[122:125], v[204:207], v[90:93]
	v_mfma_f32_16x16x32_bf16 v[78:81], v[114:117], v[212:215], v[78:81]
	v_mfma_f32_16x16x32_bf16 v[74:77], v[122:125], v[212:215], v[74:77]
	v_mfma_f32_16x16x32_bf16 v[150:153], v[118:121], v[186:189], v[150:153]
	v_mfma_f32_16x16x32_bf16 v[146:149], v[126:129], v[186:189], v[146:149]
	v_mfma_f32_16x16x32_bf16 v[110:113], v[118:121], v[200:203], v[110:113]
	v_mfma_f32_16x16x32_bf16 v[106:109], v[126:129], v[200:203], v[106:109]
	v_mfma_f32_16x16x32_bf16 v[94:97], v[118:121], v[208:211], v[94:97]
	v_mfma_f32_16x16x32_bf16 v[90:93], v[126:129], v[208:211], v[90:93]
	v_mfma_f32_16x16x32_bf16 v[78:81], v[118:121], v[222:225], v[78:81]
	v_mfma_f32_16x16x32_bf16 v[74:77], v[126:129], v[222:225], v[74:77]
	v_mfma_f32_16x16x32_bf16 v[134:137], v[138:141], v[182:185], v[134:137]
	v_mfma_f32_16x16x32_bf16 v[130:133], v[154:157], v[182:185], v[130:133]
	v_mfma_f32_16x16x32_bf16 v[102:105], v[138:141], v[190:193], v[102:105]
	v_mfma_f32_16x16x32_bf16 v[98:101], v[154:157], v[190:193], v[98:101]
	v_mfma_f32_16x16x32_bf16 v[86:89], v[138:141], v[204:207], v[86:89]
	v_mfma_f32_16x16x32_bf16 v[82:85], v[154:157], v[204:207], v[82:85]
	v_mfma_f32_16x16x32_bf16 v[70:73], v[138:141], v[212:215], v[70:73]
	v_mfma_f32_16x16x32_bf16 v[66:69], v[154:157], v[212:215], v[66:69]
	v_mfma_f32_16x16x32_bf16 v[134:137], v[142:145], v[186:189], v[134:137]
	v_mfma_f32_16x16x32_bf16 v[130:133], v[178:181], v[186:189], v[130:133]
	v_mfma_f32_16x16x32_bf16 v[102:105], v[142:145], v[200:203], v[102:105]
	v_mfma_f32_16x16x32_bf16 v[98:101], v[178:181], v[200:203], v[98:101]
	v_mfma_f32_16x16x32_bf16 v[86:89], v[142:145], v[208:211], v[86:89]
	v_mfma_f32_16x16x32_bf16 v[82:85], v[178:181], v[208:211], v[82:85]
	v_mfma_f32_16x16x32_bf16 v[70:73], v[142:145], v[222:225], v[70:73]
	v_mfma_f32_16x16x32_bf16 v[66:69], v[178:181], v[222:225], v[66:69]
	s_barrier
	s_add_i32 s36, s36, s62
	v_lshl_add_u64 v[194:195], s[56:57], 0, v[162:163]
	s_mov_b32 m0, s36
	ds_read_b128 v[182:185], v199 offset:16384
	ds_read_b128 v[186:189], v199 offset:17408
	ds_read_b128 v[190:193], v199 offset:18432
	ds_read_b128 v[200:203], v199 offset:19456
	ds_read_b128 v[204:207], v199 offset:20480
	ds_read_b128 v[208:211], v199 offset:21504
	ds_read_b128 v[212:215], v199 offset:22528
	ds_read_b128 v[222:225], v199 offset:23552
	global_load_lds_dwordx4 v[194:195], off
	s_add_i32 m0, s36, 0x2000
	s_add_u32 s36, s56, 0x160000
	v_lshl_add_u64 v[216:217], s[56:57], 0, v[172:173]
	s_addc_u32 s37, s57, 0
	s_add_i32 s38, s38, s62
	global_load_lds_dwordx4 v[216:217], off
	v_lshl_add_u64 v[226:227], s[36:37], 0, v[162:163]
	s_mov_b32 m0, s38
	s_nop 0
	global_load_lds_dwordx4 v[226:227], off
	v_lshl_add_u64 v[226:227], s[36:37], 0, v[172:173]
	s_add_i32 m0, s38, 0x2000
	s_nop 0
	global_load_lds_dwordx4 v[226:227], off
	v_lshl_add_u64 v[226:227], s[58:59], 0, v[158:159]
	s_mov_b32 m0, s63
	s_nop 0
	global_load_lds_dwordx4 v[226:227], off
	v_lshl_add_u64 v[226:227], s[58:59], 0, v[160:161]
	s_mov_b32 m0, s64
	s_nop 0
	global_load_lds_dwordx4 v[226:227], off
	s_waitcnt vmcnt(8)
	s_waitcnt lgkmcnt(0)
	s_barrier
	v_mfma_f32_16x16x32_bf16 v[62:65], v[114:117], v[182:185], v[62:65]
	v_mfma_f32_16x16x32_bf16 v[58:61], v[122:125], v[182:185], v[58:61]
	v_mfma_f32_16x16x32_bf16 v[46:49], v[114:117], v[190:193], v[46:49]
	v_mfma_f32_16x16x32_bf16 v[42:45], v[122:125], v[190:193], v[42:45]
	v_mfma_f32_16x16x32_bf16 v[30:33], v[114:117], v[204:207], v[30:33]
	v_mfma_f32_16x16x32_bf16 v[26:29], v[122:125], v[204:207], v[26:29]
	v_mfma_f32_16x16x32_bf16 v[14:17], v[114:117], v[212:215], v[14:17]
	v_mfma_f32_16x16x32_bf16 v[10:13], v[122:125], v[212:215], v[10:13]
	v_mfma_f32_16x16x32_bf16 v[62:65], v[118:121], v[186:189], v[62:65]
	v_mfma_f32_16x16x32_bf16 v[58:61], v[126:129], v[186:189], v[58:61]
	v_mfma_f32_16x16x32_bf16 v[46:49], v[118:121], v[200:203], v[46:49]
	v_mfma_f32_16x16x32_bf16 v[42:45], v[126:129], v[200:203], v[42:45]
	v_mfma_f32_16x16x32_bf16 v[30:33], v[118:121], v[208:211], v[30:33]
	v_mfma_f32_16x16x32_bf16 v[26:29], v[126:129], v[208:211], v[26:29]
	v_mfma_f32_16x16x32_bf16 v[14:17], v[118:121], v[222:225], v[14:17]
	v_mfma_f32_16x16x32_bf16 v[10:13], v[126:129], v[222:225], v[10:13]
	v_mfma_f32_16x16x32_bf16 v[54:57], v[138:141], v[182:185], v[54:57]
	v_mfma_f32_16x16x32_bf16 v[50:53], v[154:157], v[182:185], v[50:53]
	v_mfma_f32_16x16x32_bf16 v[38:41], v[138:141], v[190:193], v[38:41]
	v_mfma_f32_16x16x32_bf16 v[34:37], v[154:157], v[190:193], v[34:37]
	v_mfma_f32_16x16x32_bf16 v[22:25], v[138:141], v[204:207], v[22:25]
	v_mfma_f32_16x16x32_bf16 v[18:21], v[154:157], v[204:207], v[18:21]
	v_mfma_f32_16x16x32_bf16 v[6:9], v[138:141], v[212:215], v[6:9]
	v_mfma_f32_16x16x32_bf16 v[2:5], v[154:157], v[212:215], v[2:5]
	v_mfma_f32_16x16x32_bf16 v[54:57], v[142:145], v[186:189], v[54:57]
	v_mfma_f32_16x16x32_bf16 v[50:53], v[178:181], v[186:189], v[50:53]
	v_mfma_f32_16x16x32_bf16 v[38:41], v[142:145], v[200:203], v[38:41]
	v_mfma_f32_16x16x32_bf16 v[34:37], v[178:181], v[200:203], v[34:37]
	v_mfma_f32_16x16x32_bf16 v[22:25], v[142:145], v[208:211], v[22:25]
	v_mfma_f32_16x16x32_bf16 v[18:21], v[178:181], v[208:211], v[18:21]
	v_mfma_f32_16x16x32_bf16 v[6:9], v[142:145], v[222:225], v[6:9]
	v_mfma_f32_16x16x32_bf16 v[2:5], v[178:181], v[222:225], v[2:5]
	s_barrier
	s_add_i32 s38, 0, 0x18000
	s_add_i32 s39, 0, 0x1c000
	v_add_u32_e32 v126, s38, v197
	v_add_u32_e32 v168, s39, v197
	ds_read_b128 v[114:117], v126
	ds_read_b128 v[118:121], v126 offset:1024
	ds_read_b128 v[122:125], v126 offset:2048
	ds_read_b128 v[126:129], v126 offset:3072
	ds_read_b128 v[138:141], v168
	ds_read_b128 v[142:145], v168 offset:1024
	ds_read_b128 v[154:157], v168 offset:2048
	ds_read_b128 v[178:181], v168 offset:3072
	s_add_u32 s36, s58, 0x4000
	s_addc_u32 s37, s59, 0
	s_mov_b32 m0, s65
	v_lshl_add_u64 v[226:227], s[36:37], 0, v[158:159]
	ds_read_b128 v[182:185], v199 offset:32768
	ds_read_b128 v[186:189], v199 offset:33792
	ds_read_b128 v[190:193], v199 offset:34816
	ds_read_b128 v[200:203], v199 offset:35840
	ds_read_b128 v[204:207], v199 offset:36864
	ds_read_b128 v[208:211], v199 offset:37888
	ds_read_b128 v[212:215], v199 offset:38912
	ds_read_b128 v[222:225], v199 offset:39936
	global_load_lds_dwordx4 v[226:227], off
	v_lshl_add_u64 v[226:227], s[36:37], 0, v[160:161]
	s_mov_b32 m0, s66
	s_nop 0
	global_load_lds_dwordx4 v[226:227], off
	s_waitcnt vmcnt(8)
	s_waitcnt lgkmcnt(0)
	s_barrier
	v_mfma_f32_16x16x32_bf16 v[150:153], v[114:117], v[182:185], v[150:153]
	v_mfma_f32_16x16x32_bf16 v[146:149], v[122:125], v[182:185], v[146:149]
	v_mfma_f32_16x16x32_bf16 v[110:113], v[114:117], v[190:193], v[110:113]
	v_mfma_f32_16x16x32_bf16 v[106:109], v[122:125], v[190:193], v[106:109]
	v_mfma_f32_16x16x32_bf16 v[94:97], v[114:117], v[204:207], v[94:97]
	v_mfma_f32_16x16x32_bf16 v[90:93], v[122:125], v[204:207], v[90:93]
	v_mfma_f32_16x16x32_bf16 v[78:81], v[114:117], v[212:215], v[78:81]
	v_mfma_f32_16x16x32_bf16 v[74:77], v[122:125], v[212:215], v[74:77]
	v_mfma_f32_16x16x32_bf16 v[150:153], v[118:121], v[186:189], v[150:153]
	v_mfma_f32_16x16x32_bf16 v[146:149], v[126:129], v[186:189], v[146:149]
	v_mfma_f32_16x16x32_bf16 v[110:113], v[118:121], v[200:203], v[110:113]
	v_mfma_f32_16x16x32_bf16 v[106:109], v[126:129], v[200:203], v[106:109]
	v_mfma_f32_16x16x32_bf16 v[94:97], v[118:121], v[208:211], v[94:97]
	v_mfma_f32_16x16x32_bf16 v[90:93], v[126:129], v[208:211], v[90:93]
	v_mfma_f32_16x16x32_bf16 v[78:81], v[118:121], v[222:225], v[78:81]
	v_mfma_f32_16x16x32_bf16 v[74:77], v[126:129], v[222:225], v[74:77]
	v_mfma_f32_16x16x32_bf16 v[134:137], v[138:141], v[182:185], v[134:137]
	v_mfma_f32_16x16x32_bf16 v[130:133], v[154:157], v[182:185], v[130:133]
	v_mfma_f32_16x16x32_bf16 v[102:105], v[138:141], v[190:193], v[102:105]
	v_mfma_f32_16x16x32_bf16 v[98:101], v[154:157], v[190:193], v[98:101]
	v_mfma_f32_16x16x32_bf16 v[86:89], v[138:141], v[204:207], v[86:89]
	v_mfma_f32_16x16x32_bf16 v[82:85], v[154:157], v[204:207], v[82:85]
	v_mfma_f32_16x16x32_bf16 v[70:73], v[138:141], v[212:215], v[70:73]
	v_mfma_f32_16x16x32_bf16 v[66:69], v[154:157], v[212:215], v[66:69]
	v_mfma_f32_16x16x32_bf16 v[134:137], v[142:145], v[186:189], v[134:137]
	v_mfma_f32_16x16x32_bf16 v[130:133], v[178:181], v[186:189], v[130:133]
	v_mfma_f32_16x16x32_bf16 v[102:105], v[142:145], v[200:203], v[102:105]
	v_mfma_f32_16x16x32_bf16 v[98:101], v[178:181], v[200:203], v[98:101]
	v_mfma_f32_16x16x32_bf16 v[86:89], v[142:145], v[208:211], v[86:89]
	v_mfma_f32_16x16x32_bf16 v[82:85], v[178:181], v[208:211], v[82:85]
	v_mfma_f32_16x16x32_bf16 v[70:73], v[142:145], v[222:225], v[70:73]
	v_mfma_f32_16x16x32_bf16 v[66:69], v[178:181], v[222:225], v[66:69]
	s_barrier
	s_add_i32 s36, s38, s62
	v_lshl_add_u64 v[194:195], v[194:195], 0, s[44:45]
	s_mov_b32 m0, s36
	ds_read_b128 v[182:185], v199 offset:49152
	ds_read_b128 v[186:189], v199 offset:50176
	ds_read_b128 v[190:193], v199 offset:51200
	ds_read_b128 v[200:203], v199 offset:52224
	ds_read_b128 v[204:207], v199 offset:53248
	ds_read_b128 v[208:211], v199 offset:54272
	ds_read_b128 v[212:215], v199 offset:55296
	ds_read_b128 v[222:225], v199 offset:56320
	global_load_lds_dwordx4 v[194:195], off
	s_add_i32 m0, s36, 0x2000
	s_add_u32 s36, s56, 0x160080
	v_lshl_add_u64 v[194:195], v[216:217], 0, s[44:45]
	s_addc_u32 s37, s57, 0
	s_add_i32 s38, s39, s62
	global_load_lds_dwordx4 v[194:195], off
	v_lshl_add_u64 v[194:195], s[36:37], 0, v[162:163]
	s_mov_b32 m0, s38
	s_nop 0
	global_load_lds_dwordx4 v[194:195], off
	v_lshl_add_u64 v[194:195], s[36:37], 0, v[172:173]
	s_add_i32 m0, s38, 0x2000
	s_nop 0
	global_load_lds_dwordx4 v[194:195], off
	v_lshl_add_u64 v[194:195], s[26:27], 0, v[158:159]
	s_mov_b32 m0, s67
	s_nop 0
	global_load_lds_dwordx4 v[194:195], off
	v_lshl_add_u64 v[194:195], s[26:27], 0, v[160:161]
	s_mov_b32 m0, s68
	s_nop 0
	global_load_lds_dwordx4 v[194:195], off
	s_waitcnt vmcnt(8)
	s_waitcnt lgkmcnt(0)
	s_barrier
	v_mfma_f32_16x16x32_bf16 v[62:65], v[114:117], v[182:185], v[62:65]
	v_mfma_f32_16x16x32_bf16 v[58:61], v[122:125], v[182:185], v[58:61]
	v_mfma_f32_16x16x32_bf16 v[46:49], v[114:117], v[190:193], v[46:49]
	v_mfma_f32_16x16x32_bf16 v[42:45], v[122:125], v[190:193], v[42:45]
	v_mfma_f32_16x16x32_bf16 v[30:33], v[114:117], v[204:207], v[30:33]
	v_mfma_f32_16x16x32_bf16 v[26:29], v[122:125], v[204:207], v[26:29]
	v_mfma_f32_16x16x32_bf16 v[14:17], v[114:117], v[212:215], v[14:17]
	v_mfma_f32_16x16x32_bf16 v[10:13], v[122:125], v[212:215], v[10:13]
	v_mfma_f32_16x16x32_bf16 v[62:65], v[118:121], v[186:189], v[62:65]
	v_mfma_f32_16x16x32_bf16 v[58:61], v[126:129], v[186:189], v[58:61]
	v_mfma_f32_16x16x32_bf16 v[46:49], v[118:121], v[200:203], v[46:49]
	v_mfma_f32_16x16x32_bf16 v[42:45], v[126:129], v[200:203], v[42:45]
	v_mfma_f32_16x16x32_bf16 v[30:33], v[118:121], v[208:211], v[30:33]
	v_mfma_f32_16x16x32_bf16 v[26:29], v[126:129], v[208:211], v[26:29]
	v_mfma_f32_16x16x32_bf16 v[14:17], v[118:121], v[222:225], v[14:17]
	v_mfma_f32_16x16x32_bf16 v[10:13], v[126:129], v[222:225], v[10:13]
	v_mfma_f32_16x16x32_bf16 v[54:57], v[138:141], v[182:185], v[54:57]
	v_mfma_f32_16x16x32_bf16 v[50:53], v[154:157], v[182:185], v[50:53]
	v_mfma_f32_16x16x32_bf16 v[38:41], v[138:141], v[190:193], v[38:41]
	v_mfma_f32_16x16x32_bf16 v[34:37], v[154:157], v[190:193], v[34:37]
	v_mfma_f32_16x16x32_bf16 v[22:25], v[138:141], v[204:207], v[22:25]
	v_mfma_f32_16x16x32_bf16 v[18:21], v[154:157], v[204:207], v[18:21]
	v_mfma_f32_16x16x32_bf16 v[6:9], v[138:141], v[212:215], v[6:9]
	v_mfma_f32_16x16x32_bf16 v[2:5], v[154:157], v[212:215], v[2:5]
	v_mfma_f32_16x16x32_bf16 v[54:57], v[142:145], v[186:189], v[54:57]
	v_mfma_f32_16x16x32_bf16 v[50:53], v[178:181], v[186:189], v[50:53]
	v_mfma_f32_16x16x32_bf16 v[38:41], v[142:145], v[200:203], v[38:41]
	v_mfma_f32_16x16x32_bf16 v[34:37], v[178:181], v[200:203], v[34:37]
	v_mfma_f32_16x16x32_bf16 v[22:25], v[142:145], v[208:211], v[22:25]
	v_mfma_f32_16x16x32_bf16 v[18:21], v[178:181], v[208:211], v[18:21]
	v_mfma_f32_16x16x32_bf16 v[6:9], v[142:145], v[222:225], v[6:9]
	v_mfma_f32_16x16x32_bf16 v[2:5], v[178:181], v[222:225], v[2:5]
	s_barrier
	s_add_i32 s82, s82, 2
	s_add_u32 s24, s24, 0x10000
	s_addc_u32 s25, s25, 0
	s_add_u32 s80, s80, 0x100
	s_addc_u32 s81, s81, 0
	s_cmpk_gt_u32 s82, 0x55
	s_cbranch_scc0 .LBB0_437
	s_and_b64 vcc, exec, s[18:19]
	s_cbranch_vccz .LBB0_440
	s_barrier

.LBB0_643:
	s_add_u32 s36, s58, 0xfff80080
	s_addc_u32 s37, s59, -1
	s_add_i32 s38, 0, 0x10000
	s_cmp_eq_u32 s64, 28
	s_cselect_b32 s63, s23, s37
	s_cselect_b32 s62, s22, s36
	s_cselect_b32 s61, s25, s57
	s_cselect_b32 s60, s24, s21
	s_add_i32 s39, 0, 0x14000
	v_add_u32_e32 v152, s38, v161
	v_add_u32_e32 v156, s39, v161
	ds_read_b128 v[140:143], v152
	ds_read_b128 v[144:147], v152 offset:1024
	ds_read_b128 v[148:151], v152 offset:2048
	ds_read_b128 v[152:155], v152 offset:3072
	ds_read_b128 v[180:183], v156
	ds_read_b128 v[184:187], v156 offset:1024
	ds_read_b128 v[188:191], v156 offset:2048
	ds_read_b128 v[192:195], v156 offset:3072
	v_lshl_add_u64 v[172:173], s[58:59], 0, v[138:139]
	s_add_i32 m0, s41, 0xc000
	ds_read_b128 v[196:199], v179
	ds_read_b128 v[200:203], v179 offset:1024
	ds_read_b128 v[204:207], v179 offset:2048
	ds_read_b128 v[208:211], v179 offset:3072
	ds_read_b128 v[212:215], v179 offset:4096
	ds_read_b128 v[222:225], v179 offset:5120
	ds_read_b128 v[226:229], v179 offset:6144
	ds_read_b128 v[230:233], v179 offset:7168
	global_load_lds_dwordx4 v[172:173], off
	v_lshl_add_u64 v[172:173], s[58:59], 0, v[136:137]
	s_add_i32 m0, s41, 0xe000
	s_nop 0
	global_load_lds_dwordx4 v[172:173], off
	s_waitcnt vmcnt(8)
	s_waitcnt lgkmcnt(0)
	s_barrier
	v_mfma_f32_16x16x32_bf16 v[126:129], v[140:143], v[196:199], v[126:129]
	v_mfma_f32_16x16x32_bf16 v[86:89], v[148:151], v[196:199], v[86:89]
	v_mfma_f32_16x16x32_bf16 v[118:121], v[140:143], v[204:207], v[118:121]
	v_mfma_f32_16x16x32_bf16 v[94:97], v[148:151], v[204:207], v[94:97]
	v_mfma_f32_16x16x32_bf16 v[106:109], v[140:143], v[212:215], v[106:109]
	v_mfma_f32_16x16x32_bf16 v[102:105], v[148:151], v[212:215], v[102:105]
	v_mfma_f32_16x16x32_bf16 v[78:81], v[140:143], v[226:229], v[78:81]
	v_mfma_f32_16x16x32_bf16 v[74:77], v[148:151], v[226:229], v[74:77]
	v_mfma_f32_16x16x32_bf16 v[126:129], v[144:147], v[200:203], v[126:129]
	v_mfma_f32_16x16x32_bf16 v[86:89], v[152:155], v[200:203], v[86:89]
	v_mfma_f32_16x16x32_bf16 v[118:121], v[144:147], v[208:211], v[118:121]
	v_mfma_f32_16x16x32_bf16 v[94:97], v[152:155], v[208:211], v[94:97]
	v_mfma_f32_16x16x32_bf16 v[106:109], v[144:147], v[222:225], v[106:109]
	v_mfma_f32_16x16x32_bf16 v[102:105], v[152:155], v[222:225], v[102:105]
	v_mfma_f32_16x16x32_bf16 v[78:81], v[144:147], v[230:233], v[78:81]
	v_mfma_f32_16x16x32_bf16 v[74:77], v[152:155], v[230:233], v[74:77]
	v_mfma_f32_16x16x32_bf16 v[122:125], v[180:183], v[196:199], v[122:125]
	v_mfma_f32_16x16x32_bf16 v[98:101], v[188:191], v[196:199], v[98:101]
	v_mfma_f32_16x16x32_bf16 v[114:117], v[180:183], v[204:207], v[114:117]
	v_mfma_f32_16x16x32_bf16 v[110:113], v[188:191], v[204:207], v[110:113]
	v_mfma_f32_16x16x32_bf16 v[90:93], v[180:183], v[212:215], v[90:93]
	v_mfma_f32_16x16x32_bf16 v[82:85], v[188:191], v[212:215], v[82:85]
	v_mfma_f32_16x16x32_bf16 v[70:73], v[180:183], v[226:229], v[70:73]
	v_mfma_f32_16x16x32_bf16 v[66:69], v[188:191], v[226:229], v[66:69]
	v_mfma_f32_16x16x32_bf16 v[122:125], v[184:187], v[200:203], v[122:125]
	v_mfma_f32_16x16x32_bf16 v[98:101], v[192:195], v[200:203], v[98:101]
	v_mfma_f32_16x16x32_bf16 v[114:117], v[184:187], v[208:211], v[114:117]
	v_mfma_f32_16x16x32_bf16 v[110:113], v[192:195], v[208:211], v[110:113]
	v_mfma_f32_16x16x32_bf16 v[90:93], v[184:187], v[222:225], v[90:93]
	v_mfma_f32_16x16x32_bf16 v[82:85], v[192:195], v[222:225], v[82:85]
	v_mfma_f32_16x16x32_bf16 v[70:73], v[184:187], v[230:233], v[70:73]
	v_mfma_f32_16x16x32_bf16 v[66:69], v[192:195], v[230:233], v[66:69]
	s_barrier
	s_add_i32 s36, s38, s72
	v_lshl_add_u64 v[172:173], s[60:61], 0, v[162:163]
	s_mov_b32 m0, s36
	ds_read_b128 v[196:199], v179 offset:16384
	ds_read_b128 v[200:203], v179 offset:17408
	ds_read_b128 v[204:207], v179 offset:18432
	ds_read_b128 v[208:211], v179 offset:19456
	ds_read_b128 v[212:215], v179 offset:20480
	ds_read_b128 v[222:225], v179 offset:21504
	ds_read_b128 v[226:229], v179 offset:22528
	ds_read_b128 v[230:233], v179 offset:23552
	global_load_lds_dwordx4 v[172:173], off
	s_add_i32 m0, s36, 0x2000
	s_add_u32 s36, s60, 0x80000
	v_lshl_add_u64 v[216:217], s[60:61], 0, v[134:135]
	s_addc_u32 s37, s61, 0
	s_add_i32 s38, s39, s72
	global_load_lds_dwordx4 v[216:217], off
	v_lshl_add_u64 v[234:235], s[36:37], 0, v[162:163]
	s_mov_b32 m0, s38
	v_lshl_add_u64 v[236:237], s[62:63], 0, v[132:133]
	global_load_lds_dwordx4 v[234:235], off
	v_lshl_add_u64 v[234:235], s[36:37], 0, v[134:135]
	s_add_i32 m0, s38, 0x2000
	s_nop 0
	global_load_lds_dwordx4 v[234:235], off
	v_lshl_add_u64 v[234:235], s[62:63], 0, v[130:131]
	s_mov_b32 m0, s41
	s_nop 0
	global_load_lds_dwordx4 v[234:235], off
	s_mov_b32 m0, s66
	s_nop 0
	global_load_lds_dwordx4 v[236:237], off
	s_waitcnt vmcnt(8)
	s_waitcnt lgkmcnt(0)
	s_barrier
	v_mfma_f32_16x16x32_bf16 v[62:65], v[140:143], v[196:199], v[62:65]
	v_mfma_f32_16x16x32_bf16 v[58:61], v[148:151], v[196:199], v[58:61]
	v_mfma_f32_16x16x32_bf16 v[46:49], v[140:143], v[204:207], v[46:49]
	v_mfma_f32_16x16x32_bf16 v[42:45], v[148:151], v[204:207], v[42:45]
	v_mfma_f32_16x16x32_bf16 v[30:33], v[140:143], v[212:215], v[30:33]
	v_mfma_f32_16x16x32_bf16 v[26:29], v[148:151], v[212:215], v[26:29]
	v_mfma_f32_16x16x32_bf16 v[14:17], v[140:143], v[226:229], v[14:17]
	v_mfma_f32_16x16x32_bf16 v[10:13], v[148:151], v[226:229], v[10:13]
	v_mfma_f32_16x16x32_bf16 v[62:65], v[144:147], v[200:203], v[62:65]
	v_mfma_f32_16x16x32_bf16 v[58:61], v[152:155], v[200:203], v[58:61]
	v_mfma_f32_16x16x32_bf16 v[46:49], v[144:147], v[208:211], v[46:49]
	v_mfma_f32_16x16x32_bf16 v[42:45], v[152:155], v[208:211], v[42:45]
	v_mfma_f32_16x16x32_bf16 v[30:33], v[144:147], v[222:225], v[30:33]
	v_mfma_f32_16x16x32_bf16 v[26:29], v[152:155], v[222:225], v[26:29]
	v_mfma_f32_16x16x32_bf16 v[14:17], v[144:147], v[230:233], v[14:17]
	v_mfma_f32_16x16x32_bf16 v[10:13], v[152:155], v[230:233], v[10:13]
	v_mfma_f32_16x16x32_bf16 v[54:57], v[180:183], v[196:199], v[54:57]
	v_mfma_f32_16x16x32_bf16 v[50:53], v[188:191], v[196:199], v[50:53]
	v_mfma_f32_16x16x32_bf16 v[38:41], v[180:183], v[204:207], v[38:41]
	v_mfma_f32_16x16x32_bf16 v[34:37], v[188:191], v[204:207], v[34:37]
	v_mfma_f32_16x16x32_bf16 v[22:25], v[180:183], v[212:215], v[22:25]
	v_mfma_f32_16x16x32_bf16 v[18:21], v[188:191], v[212:215], v[18:21]
	v_mfma_f32_16x16x32_bf16 v[6:9], v[180:183], v[226:229], v[6:9]
	v_mfma_f32_16x16x32_bf16 v[2:5], v[188:191], v[226:229], v[2:5]
	v_mfma_f32_16x16x32_bf16 v[54:57], v[184:187], v[200:203], v[54:57]
	v_mfma_f32_16x16x32_bf16 v[50:53], v[192:195], v[200:203], v[50:53]
	v_mfma_f32_16x16x32_bf16 v[38:41], v[184:187], v[208:211], v[38:41]
	v_mfma_f32_16x16x32_bf16 v[34:37], v[192:195], v[208:211], v[34:37]
	v_mfma_f32_16x16x32_bf16 v[22:25], v[184:187], v[222:225], v[22:25]
	v_mfma_f32_16x16x32_bf16 v[18:21], v[192:195], v[222:225], v[18:21]
	v_mfma_f32_16x16x32_bf16 v[6:9], v[184:187], v[230:233], v[6:9]
	v_mfma_f32_16x16x32_bf16 v[2:5], v[192:195], v[230:233], v[2:5]
	s_barrier
	s_add_i32 s38, 0, 0x18000
	s_add_i32 s39, 0, 0x1c000
	v_add_u32_e32 v152, s38, v161
	v_add_u32_e32 v156, s39, v161
	ds_read_b128 v[140:143], v152
	ds_read_b128 v[144:147], v152 offset:1024
	ds_read_b128 v[148:151], v152 offset:2048
	ds_read_b128 v[152:155], v152 offset:3072
	ds_read_b128 v[180:183], v156
	ds_read_b128 v[184:187], v156 offset:1024
	ds_read_b128 v[188:191], v156 offset:2048
	ds_read_b128 v[192:195], v156 offset:3072
	s_add_u32 s36, s62, 0x80000
	s_addc_u32 s37, s63, 0
	s_mov_b32 m0, s74
	v_lshl_add_u64 v[238:239], s[36:37], 0, v[130:131]
	ds_read_b128 v[196:199], v179 offset:32768
	ds_read_b128 v[200:203], v179 offset:33792
	ds_read_b128 v[204:207], v179 offset:34816
	ds_read_b128 v[208:211], v179 offset:35840
	ds_read_b128 v[212:215], v179 offset:36864
	ds_read_b128 v[222:225], v179 offset:37888
	ds_read_b128 v[226:229], v179 offset:38912
	ds_read_b128 v[230:233], v179 offset:39936
	global_load_lds_dwordx4 v[238:239], off
	v_lshl_add_u64 v[238:239], s[36:37], 0, v[132:133]
	s_mov_b32 m0, s75
	s_nop 0
	global_load_lds_dwordx4 v[238:239], off
	s_waitcnt vmcnt(8)
	s_waitcnt lgkmcnt(0)
	s_barrier
	v_mfma_f32_16x16x32_bf16 v[126:129], v[140:143], v[196:199], v[126:129]
	v_mfma_f32_16x16x32_bf16 v[86:89], v[148:151], v[196:199], v[86:89]
	v_mfma_f32_16x16x32_bf16 v[118:121], v[140:143], v[204:207], v[118:121]
	v_mfma_f32_16x16x32_bf16 v[94:97], v[148:151], v[204:207], v[94:97]
	v_mfma_f32_16x16x32_bf16 v[106:109], v[140:143], v[212:215], v[106:109]
	v_mfma_f32_16x16x32_bf16 v[102:105], v[148:151], v[212:215], v[102:105]
	v_mfma_f32_16x16x32_bf16 v[78:81], v[140:143], v[226:229], v[78:81]
	v_mfma_f32_16x16x32_bf16 v[74:77], v[148:151], v[226:229], v[74:77]
	v_mfma_f32_16x16x32_bf16 v[126:129], v[144:147], v[200:203], v[126:129]
	v_mfma_f32_16x16x32_bf16 v[86:89], v[152:155], v[200:203], v[86:89]
	v_mfma_f32_16x16x32_bf16 v[118:121], v[144:147], v[208:211], v[118:121]
	v_mfma_f32_16x16x32_bf16 v[94:97], v[152:155], v[208:211], v[94:97]
	v_mfma_f32_16x16x32_bf16 v[106:109], v[144:147], v[222:225], v[106:109]
	v_mfma_f32_16x16x32_bf16 v[102:105], v[152:155], v[222:225], v[102:105]
	v_mfma_f32_16x16x32_bf16 v[78:81], v[144:147], v[230:233], v[78:81]
	v_mfma_f32_16x16x32_bf16 v[74:77], v[152:155], v[230:233], v[74:77]
	v_mfma_f32_16x16x32_bf16 v[122:125], v[180:183], v[196:199], v[122:125]
	v_mfma_f32_16x16x32_bf16 v[98:101], v[188:191], v[196:199], v[98:101]
	v_mfma_f32_16x16x32_bf16 v[114:117], v[180:183], v[204:207], v[114:117]
	v_mfma_f32_16x16x32_bf16 v[110:113], v[188:191], v[204:207], v[110:113]
	v_mfma_f32_16x16x32_bf16 v[90:93], v[180:183], v[212:215], v[90:93]
	v_mfma_f32_16x16x32_bf16 v[82:85], v[188:191], v[212:215], v[82:85]
	v_mfma_f32_16x16x32_bf16 v[70:73], v[180:183], v[226:229], v[70:73]
	v_mfma_f32_16x16x32_bf16 v[66:69], v[188:191], v[226:229], v[66:69]
	v_mfma_f32_16x16x32_bf16 v[122:125], v[184:187], v[200:203], v[122:125]
	v_mfma_f32_16x16x32_bf16 v[98:101], v[192:195], v[200:203], v[98:101]
	v_mfma_f32_16x16x32_bf16 v[114:117], v[184:187], v[208:211], v[114:117]
	v_mfma_f32_16x16x32_bf16 v[110:113], v[192:195], v[208:211], v[110:113]
	v_mfma_f32_16x16x32_bf16 v[90:93], v[184:187], v[222:225], v[90:93]
	v_mfma_f32_16x16x32_bf16 v[82:85], v[192:195], v[222:225], v[82:85]
	v_mfma_f32_16x16x32_bf16 v[70:73], v[184:187], v[230:233], v[70:73]
	v_mfma_f32_16x16x32_bf16 v[66:69], v[192:195], v[230:233], v[66:69]
	s_barrier
	s_add_i32 s36, s38, s72
	v_lshl_add_u64 v[172:173], v[172:173], 0, s[44:45]
	s_mov_b32 m0, s36
	ds_read_b128 v[196:199], v179 offset:49152
	ds_read_b128 v[200:203], v179 offset:50176
	ds_read_b128 v[204:207], v179 offset:51200
	ds_read_b128 v[208:211], v179 offset:52224
	ds_read_b128 v[212:215], v179 offset:53248
	ds_read_b128 v[222:225], v179 offset:54272
	ds_read_b128 v[226:229], v179 offset:55296
	ds_read_b128 v[230:233], v179 offset:56320
	global_load_lds_dwordx4 v[172:173], off
	s_add_i32 m0, s36, 0x2000
	s_add_u32 s36, s60, 0x80080
	v_lshl_add_u64 v[172:173], v[216:217], 0, s[44:45]
	s_addc_u32 s37, s61, 0
	s_add_i32 s38, s39, s72
	global_load_lds_dwordx4 v[172:173], off
	v_lshl_add_u64 v[172:173], s[36:37], 0, v[162:163]
	s_mov_b32 m0, s38
	s_nop 0
	global_load_lds_dwordx4 v[172:173], off
	v_lshl_add_u64 v[172:173], s[36:37], 0, v[134:135]
	s_add_i32 m0, s38, 0x2000
	s_nop 0
	global_load_lds_dwordx4 v[172:173], off
	v_lshl_add_u64 v[172:173], v[234:235], 0, s[44:45]
	s_mov_b32 m0, s76
	s_nop 0
	global_load_lds_dwordx4 v[172:173], off
	v_lshl_add_u64 v[172:173], v[236:237], 0, s[44:45]
	s_mov_b32 m0, s77
	s_nop 0
	global_load_lds_dwordx4 v[172:173], off
	s_waitcnt vmcnt(8)
	s_waitcnt lgkmcnt(0)
	s_barrier
	v_mfma_f32_16x16x32_bf16 v[62:65], v[140:143], v[196:199], v[62:65]
	v_mfma_f32_16x16x32_bf16 v[58:61], v[148:151], v[196:199], v[58:61]
	v_mfma_f32_16x16x32_bf16 v[46:49], v[140:143], v[204:207], v[46:49]
	v_mfma_f32_16x16x32_bf16 v[42:45], v[148:151], v[204:207], v[42:45]
	v_mfma_f32_16x16x32_bf16 v[30:33], v[140:143], v[212:215], v[30:33]
	v_mfma_f32_16x16x32_bf16 v[26:29], v[148:151], v[212:215], v[26:29]
	v_mfma_f32_16x16x32_bf16 v[14:17], v[140:143], v[226:229], v[14:17]
	v_mfma_f32_16x16x32_bf16 v[10:13], v[148:151], v[226:229], v[10:13]
	v_mfma_f32_16x16x32_bf16 v[62:65], v[144:147], v[200:203], v[62:65]
	v_mfma_f32_16x16x32_bf16 v[58:61], v[152:155], v[200:203], v[58:61]
	v_mfma_f32_16x16x32_bf16 v[46:49], v[144:147], v[208:211], v[46:49]
	v_mfma_f32_16x16x32_bf16 v[42:45], v[152:155], v[208:211], v[42:45]
	v_mfma_f32_16x16x32_bf16 v[30:33], v[144:147], v[222:225], v[30:33]
	v_mfma_f32_16x16x32_bf16 v[26:29], v[152:155], v[222:225], v[26:29]
	v_mfma_f32_16x16x32_bf16 v[14:17], v[144:147], v[230:233], v[14:17]
	v_mfma_f32_16x16x32_bf16 v[10:13], v[152:155], v[230:233], v[10:13]
	v_mfma_f32_16x16x32_bf16 v[54:57], v[180:183], v[196:199], v[54:57]
	v_mfma_f32_16x16x32_bf16 v[50:53], v[188:191], v[196:199], v[50:53]
	v_mfma_f32_16x16x32_bf16 v[38:41], v[180:183], v[204:207], v[38:41]
	v_mfma_f32_16x16x32_bf16 v[34:37], v[188:191], v[204:207], v[34:37]
	v_mfma_f32_16x16x32_bf16 v[22:25], v[180:183], v[212:215], v[22:25]
	v_mfma_f32_16x16x32_bf16 v[18:21], v[188:191], v[212:215], v[18:21]
	v_mfma_f32_16x16x32_bf16 v[6:9], v[180:183], v[226:229], v[6:9]
	v_mfma_f32_16x16x32_bf16 v[2:5], v[188:191], v[226:229], v[2:5]
	v_mfma_f32_16x16x32_bf16 v[54:57], v[184:187], v[200:203], v[54:57]
	v_mfma_f32_16x16x32_bf16 v[50:53], v[192:195], v[200:203], v[50:53]
	v_mfma_f32_16x16x32_bf16 v[38:41], v[184:187], v[208:211], v[38:41]
	v_mfma_f32_16x16x32_bf16 v[34:37], v[192:195], v[208:211], v[34:37]
	v_mfma_f32_16x16x32_bf16 v[22:25], v[184:187], v[222:225], v[22:25]
	v_mfma_f32_16x16x32_bf16 v[18:21], v[192:195], v[222:225], v[18:21]
	v_mfma_f32_16x16x32_bf16 v[6:9], v[184:187], v[230:233], v[6:9]
	v_mfma_f32_16x16x32_bf16 v[2:5], v[192:195], v[230:233], v[2:5]
	s_barrier
	s_add_i32 s64, s64, 2
	s_add_u32 s21, s21, 0x100
	s_addc_u32 s57, s57, 0
	s_add_u32 s58, s58, 0x100
	s_addc_u32 s59, s59, 0
	s_cmp_gt_u32 s64, 29
	s_cbranch_scc0 .LBB0_643
	s_and_b64 vcc, exec, s[16:17]
	s_cbranch_vccz .LBB0_646
	s_barrier

.LBB0_696:
	s_add_u32 s36, s26, 0xfffc0080
	s_addc_u32 s37, s27, -1
	s_add_i32 s38, 0, 0x10000
	s_cmp_eq_u32 s60, 12
	s_cselect_b32 s59, s19, s37
	s_cselect_b32 s58, s18, s36
	v_add_u32_e32 v140, s38, v149
	s_cselect_b32 s57, s21, s17
	s_cselect_b32 s56, s20, s15
	s_add_i32 s39, 0, 0x14000
	ds_read_b128 v[156:159], v140
	ds_read_b128 v[172:175], v140 offset:1024
	ds_read_b128 v[190:193], v140 offset:2048
	ds_read_b128 v[194:197], v140 offset:3072
	v_add_u32_e32 v140, s39, v149
	ds_read_b128 v[198:201], v140
	ds_read_b128 v[202:205], v140 offset:1024
	ds_read_b128 v[206:209], v140 offset:2048
	ds_read_b128 v[210:213], v140 offset:3072
	v_lshl_add_u64 v[160:161], s[26:27], 0, v[138:139]
	s_add_i32 m0, s25, 0xc000
	ds_read_b128 v[214:217], v189
	ds_read_b128 v[222:225], v189 offset:1024
	ds_read_b128 v[226:229], v189 offset:2048
	ds_read_b128 v[230:233], v189 offset:3072
	ds_read_b128 v[234:237], v189 offset:4096
	ds_read_b128 v[238:241], v189 offset:5120
	ds_read_b128 v[242:245], v189 offset:6144
	ds_read_b128 v[246:249], v189 offset:7168
	global_load_lds_dwordx4 v[160:161], off
	v_lshl_add_u64 v[160:161], s[26:27], 0, v[136:137]
	s_add_i32 m0, s25, 0xe000
	s_nop 0
	global_load_lds_dwordx4 v[160:161], off
	s_waitcnt vmcnt(8)
	s_waitcnt lgkmcnt(0)
	s_barrier
	v_mfma_i32_16x16x64_i8 v[126:129], v[156:159], v[214:217], v[126:129]
	v_mfma_i32_16x16x64_i8 v[122:125], v[190:193], v[214:217], v[122:125]
	v_mfma_i32_16x16x64_i8 v[118:121], v[156:159], v[226:229], v[118:121]
	v_mfma_i32_16x16x64_i8 v[114:117], v[190:193], v[226:229], v[114:117]
	v_mfma_i32_16x16x64_i8 v[110:113], v[156:159], v[234:237], v[110:113]
	v_mfma_i32_16x16x64_i8 v[106:109], v[190:193], v[234:237], v[106:109]
	v_mfma_i32_16x16x64_i8 v[102:105], v[156:159], v[242:245], v[102:105]
	v_mfma_i32_16x16x64_i8 v[98:101], v[190:193], v[242:245], v[98:101]
	v_mfma_i32_16x16x64_i8 v[126:129], v[172:175], v[222:225], v[126:129]
	v_mfma_i32_16x16x64_i8 v[122:125], v[194:197], v[222:225], v[122:125]
	v_mfma_i32_16x16x64_i8 v[118:121], v[172:175], v[230:233], v[118:121]
	v_mfma_i32_16x16x64_i8 v[114:117], v[194:197], v[230:233], v[114:117]
	v_mfma_i32_16x16x64_i8 v[110:113], v[172:175], v[238:241], v[110:113]
	v_mfma_i32_16x16x64_i8 v[106:109], v[194:197], v[238:241], v[106:109]
	v_mfma_i32_16x16x64_i8 v[102:105], v[172:175], v[246:249], v[102:105]
	v_mfma_i32_16x16x64_i8 v[98:101], v[194:197], v[246:249], v[98:101]
	v_mfma_i32_16x16x64_i8 v[62:65], v[198:201], v[214:217], v[62:65]
	v_mfma_i32_16x16x64_i8 v[58:61], v[206:209], v[214:217], v[58:61]
	v_mfma_i32_16x16x64_i8 v[54:57], v[198:201], v[226:229], v[54:57]
	v_mfma_i32_16x16x64_i8 v[50:53], v[206:209], v[226:229], v[50:53]
	v_mfma_i32_16x16x64_i8 v[46:49], v[198:201], v[234:237], v[46:49]
	v_mfma_i32_16x16x64_i8 v[42:45], v[206:209], v[234:237], v[42:45]
	v_mfma_i32_16x16x64_i8 v[38:41], v[198:201], v[242:245], v[38:41]
	v_mfma_i32_16x16x64_i8 v[34:37], v[206:209], v[242:245], v[34:37]
	v_mfma_i32_16x16x64_i8 v[62:65], v[202:205], v[222:225], v[62:65]
	v_mfma_i32_16x16x64_i8 v[58:61], v[210:213], v[222:225], v[58:61]
	v_mfma_i32_16x16x64_i8 v[54:57], v[202:205], v[230:233], v[54:57]
	v_mfma_i32_16x16x64_i8 v[50:53], v[210:213], v[230:233], v[50:53]
	v_mfma_i32_16x16x64_i8 v[46:49], v[202:205], v[238:241], v[46:49]
	v_mfma_i32_16x16x64_i8 v[42:45], v[210:213], v[238:241], v[42:45]
	v_mfma_i32_16x16x64_i8 v[38:41], v[202:205], v[246:249], v[38:41]
	v_mfma_i32_16x16x64_i8 v[34:37], v[210:213], v[246:249], v[34:37]
	s_barrier
	s_add_i32 s36, s38, s23
	v_lshl_add_u64 v[160:161], s[56:57], 0, v[162:163]
	s_mov_b32 m0, s36
	ds_read_b128 v[214:217], v189 offset:16384
	ds_read_b128 v[222:225], v189 offset:17408
	ds_read_b128 v[226:229], v189 offset:18432
	ds_read_b128 v[230:233], v189 offset:19456
	ds_read_b128 v[234:237], v189 offset:20480
	ds_read_b128 v[238:241], v189 offset:21504
	ds_read_b128 v[242:245], v189 offset:22528
	ds_read_b128 v[246:249], v189 offset:23552
	global_load_lds_dwordx4 v[160:161], off
	s_add_i32 m0, s36, 0x2000
	s_add_u32 s36, s56, 0x80000
	v_lshl_add_u64 v[250:251], s[56:57], 0, v[134:135]
	s_addc_u32 s37, s57, 0
	s_add_i32 s38, s39, s23
	global_load_lds_dwordx4 v[250:251], off
	v_lshl_add_u64 v[252:253], s[36:37], 0, v[162:163]
	s_mov_b32 m0, s38
	v_lshl_add_u64 v[168:169], s[58:59], 0, v[132:133]
	global_load_lds_dwordx4 v[252:253], off
	v_lshl_add_u64 v[252:253], s[36:37], 0, v[134:135]
	s_add_i32 m0, s38, 0x2000
	s_nop 0
	global_load_lds_dwordx4 v[252:253], off
	v_lshl_add_u64 v[252:253], s[58:59], 0, v[130:131]
	s_mov_b32 m0, s25
	s_nop 0
	global_load_lds_dwordx4 v[252:253], off
	s_mov_b32 m0, s67
	s_nop 0
	global_load_lds_dwordx4 v[168:169], off
	s_waitcnt vmcnt(8)
	s_waitcnt lgkmcnt(0)
	s_barrier
	v_mfma_i32_16x16x64_i8 v[94:97], v[156:159], v[214:217], v[94:97]
	v_mfma_i32_16x16x64_i8 v[90:93], v[190:193], v[214:217], v[90:93]
	v_mfma_i32_16x16x64_i8 v[86:89], v[156:159], v[226:229], v[86:89]
	v_mfma_i32_16x16x64_i8 v[82:85], v[190:193], v[226:229], v[82:85]
	v_mfma_i32_16x16x64_i8 v[78:81], v[156:159], v[234:237], v[78:81]
	v_mfma_i32_16x16x64_i8 v[74:77], v[190:193], v[234:237], v[74:77]
	v_mfma_i32_16x16x64_i8 v[70:73], v[156:159], v[242:245], v[70:73]
	v_mfma_i32_16x16x64_i8 v[66:69], v[190:193], v[242:245], v[66:69]
	v_mfma_i32_16x16x64_i8 v[94:97], v[172:175], v[222:225], v[94:97]
	v_mfma_i32_16x16x64_i8 v[90:93], v[194:197], v[222:225], v[90:93]
	v_mfma_i32_16x16x64_i8 v[86:89], v[172:175], v[230:233], v[86:89]
	v_mfma_i32_16x16x64_i8 v[82:85], v[194:197], v[230:233], v[82:85]
	v_mfma_i32_16x16x64_i8 v[78:81], v[172:175], v[238:241], v[78:81]
	v_mfma_i32_16x16x64_i8 v[74:77], v[194:197], v[238:241], v[74:77]
	v_mfma_i32_16x16x64_i8 v[70:73], v[172:175], v[246:249], v[70:73]
	v_mfma_i32_16x16x64_i8 v[66:69], v[194:197], v[246:249], v[66:69]
	v_mfma_i32_16x16x64_i8 v[30:33], v[198:201], v[214:217], v[30:33]
	v_mfma_i32_16x16x64_i8 v[26:29], v[206:209], v[214:217], v[26:29]
	v_mfma_i32_16x16x64_i8 v[22:25], v[198:201], v[226:229], v[22:25]
	v_mfma_i32_16x16x64_i8 v[18:21], v[206:209], v[226:229], v[18:21]
	v_mfma_i32_16x16x64_i8 v[14:17], v[198:201], v[234:237], v[14:17]
	v_mfma_i32_16x16x64_i8 v[10:13], v[206:209], v[234:237], v[10:13]
	v_mfma_i32_16x16x64_i8 v[6:9], v[198:201], v[242:245], v[6:9]
	v_mfma_i32_16x16x64_i8 v[2:5], v[206:209], v[242:245], v[2:5]
	v_mfma_i32_16x16x64_i8 v[30:33], v[202:205], v[222:225], v[30:33]
	v_mfma_i32_16x16x64_i8 v[26:29], v[210:213], v[222:225], v[26:29]
	v_mfma_i32_16x16x64_i8 v[22:25], v[202:205], v[230:233], v[22:25]
	v_mfma_i32_16x16x64_i8 v[18:21], v[210:213], v[230:233], v[18:21]
	v_mfma_i32_16x16x64_i8 v[14:17], v[202:205], v[238:241], v[14:17]
	v_mfma_i32_16x16x64_i8 v[10:13], v[210:213], v[238:241], v[10:13]
	v_mfma_i32_16x16x64_i8 v[6:9], v[202:205], v[246:249], v[6:9]
	v_mfma_i32_16x16x64_i8 v[2:5], v[210:213], v[246:249], v[2:5]
	s_barrier
	s_add_i32 s38, 0, 0x18000
	v_add_u32_e32 v140, s38, v149
	s_add_i32 s39, 0, 0x1c000
	ds_read_b128 v[156:159], v140
	ds_read_b128 v[172:175], v140 offset:1024
	ds_read_b128 v[190:193], v140 offset:2048
	ds_read_b128 v[194:197], v140 offset:3072
	v_add_u32_e32 v140, s39, v149
	ds_read_b128 v[198:201], v140
	ds_read_b128 v[202:205], v140 offset:1024
	ds_read_b128 v[206:209], v140 offset:2048
	ds_read_b128 v[210:213], v140 offset:3072
	s_add_u32 s36, s58, 0x40000
	s_addc_u32 s37, s59, 0
	s_mov_b32 m0, s68
	v_lshl_add_u64 v[170:171], s[36:37], 0, v[130:131]
	ds_read_b128 v[214:217], v189 offset:32768
	ds_read_b128 v[222:225], v189 offset:33792
	ds_read_b128 v[226:229], v189 offset:34816
	ds_read_b128 v[230:233], v189 offset:35840
	ds_read_b128 v[234:237], v189 offset:36864
	ds_read_b128 v[238:241], v189 offset:37888
	ds_read_b128 v[242:245], v189 offset:38912
	ds_read_b128 v[246:249], v189 offset:39936
	global_load_lds_dwordx4 v[170:171], off
	v_lshl_add_u64 v[170:171], s[36:37], 0, v[132:133]
	s_mov_b32 m0, s69
	s_nop 0
	global_load_lds_dwordx4 v[170:171], off
	s_waitcnt vmcnt(8)
	s_waitcnt lgkmcnt(0)
	s_barrier
	v_mfma_i32_16x16x64_i8 v[126:129], v[156:159], v[214:217], v[126:129]
	v_mfma_i32_16x16x64_i8 v[122:125], v[190:193], v[214:217], v[122:125]
	v_mfma_i32_16x16x64_i8 v[118:121], v[156:159], v[226:229], v[118:121]
	v_mfma_i32_16x16x64_i8 v[114:117], v[190:193], v[226:229], v[114:117]
	v_mfma_i32_16x16x64_i8 v[110:113], v[156:159], v[234:237], v[110:113]
	v_mfma_i32_16x16x64_i8 v[106:109], v[190:193], v[234:237], v[106:109]
	v_mfma_i32_16x16x64_i8 v[102:105], v[156:159], v[242:245], v[102:105]
	v_mfma_i32_16x16x64_i8 v[98:101], v[190:193], v[242:245], v[98:101]
	v_mfma_i32_16x16x64_i8 v[126:129], v[172:175], v[222:225], v[126:129]
	v_mfma_i32_16x16x64_i8 v[122:125], v[194:197], v[222:225], v[122:125]
	v_mfma_i32_16x16x64_i8 v[118:121], v[172:175], v[230:233], v[118:121]
	v_mfma_i32_16x16x64_i8 v[114:117], v[194:197], v[230:233], v[114:117]
	v_mfma_i32_16x16x64_i8 v[110:113], v[172:175], v[238:241], v[110:113]
	v_mfma_i32_16x16x64_i8 v[106:109], v[194:197], v[238:241], v[106:109]
	v_mfma_i32_16x16x64_i8 v[102:105], v[172:175], v[246:249], v[102:105]
	v_mfma_i32_16x16x64_i8 v[98:101], v[194:197], v[246:249], v[98:101]
	v_mfma_i32_16x16x64_i8 v[62:65], v[198:201], v[214:217], v[62:65]
	v_mfma_i32_16x16x64_i8 v[58:61], v[206:209], v[214:217], v[58:61]
	v_mfma_i32_16x16x64_i8 v[54:57], v[198:201], v[226:229], v[54:57]
	v_mfma_i32_16x16x64_i8 v[50:53], v[206:209], v[226:229], v[50:53]
	v_mfma_i32_16x16x64_i8 v[46:49], v[198:201], v[234:237], v[46:49]
	v_mfma_i32_16x16x64_i8 v[42:45], v[206:209], v[234:237], v[42:45]
	v_mfma_i32_16x16x64_i8 v[38:41], v[198:201], v[242:245], v[38:41]
	v_mfma_i32_16x16x64_i8 v[34:37], v[206:209], v[242:245], v[34:37]
	v_mfma_i32_16x16x64_i8 v[62:65], v[202:205], v[222:225], v[62:65]
	v_mfma_i32_16x16x64_i8 v[58:61], v[210:213], v[222:225], v[58:61]
	v_mfma_i32_16x16x64_i8 v[54:57], v[202:205], v[230:233], v[54:57]
	v_mfma_i32_16x16x64_i8 v[50:53], v[210:213], v[230:233], v[50:53]
	v_mfma_i32_16x16x64_i8 v[46:49], v[202:205], v[238:241], v[46:49]
	v_mfma_i32_16x16x64_i8 v[42:45], v[210:213], v[238:241], v[42:45]
	v_mfma_i32_16x16x64_i8 v[38:41], v[202:205], v[246:249], v[38:41]
	v_mfma_i32_16x16x64_i8 v[34:37], v[210:213], v[246:249], v[34:37]
	s_barrier
	s_add_i32 s36, s38, s23
	v_lshl_add_u64 v[160:161], v[160:161], 0, s[44:45]
	s_mov_b32 m0, s36
	ds_read_b128 v[214:217], v189 offset:49152
	ds_read_b128 v[222:225], v189 offset:50176
	ds_read_b128 v[226:229], v189 offset:51200
	ds_read_b128 v[230:233], v189 offset:52224
	ds_read_b128 v[234:237], v189 offset:53248
	ds_read_b128 v[238:241], v189 offset:54272
	ds_read_b128 v[242:245], v189 offset:55296
	ds_read_b128 v[246:249], v189 offset:56320
	global_load_lds_dwordx4 v[160:161], off
	s_add_i32 m0, s36, 0x2000
	s_add_u32 s36, s56, 0x80080
	v_lshl_add_u64 v[160:161], v[250:251], 0, s[44:45]
	s_addc_u32 s37, s57, 0
	s_add_i32 s38, s39, s23
	global_load_lds_dwordx4 v[160:161], off
	v_lshl_add_u64 v[160:161], s[36:37], 0, v[162:163]
	s_mov_b32 m0, s38
	s_nop 0
	global_load_lds_dwordx4 v[160:161], off
	v_lshl_add_u64 v[160:161], s[36:37], 0, v[134:135]
	s_add_i32 m0, s38, 0x2000
	s_nop 0
	global_load_lds_dwordx4 v[160:161], off
	v_lshl_add_u64 v[160:161], v[252:253], 0, s[44:45]
	s_mov_b32 m0, s71
	s_nop 0
	global_load_lds_dwordx4 v[160:161], off
	v_lshl_add_u64 v[160:161], v[168:169], 0, s[44:45]
	s_mov_b32 m0, s72
	s_nop 0
	global_load_lds_dwordx4 v[160:161], off
	s_waitcnt vmcnt(8)
	s_waitcnt lgkmcnt(0)
	s_barrier
	v_mfma_i32_16x16x64_i8 v[94:97], v[156:159], v[214:217], v[94:97]
	v_mfma_i32_16x16x64_i8 v[90:93], v[190:193], v[214:217], v[90:93]
	v_mfma_i32_16x16x64_i8 v[86:89], v[156:159], v[226:229], v[86:89]
	v_mfma_i32_16x16x64_i8 v[82:85], v[190:193], v[226:229], v[82:85]
	v_mfma_i32_16x16x64_i8 v[78:81], v[156:159], v[234:237], v[78:81]
	v_mfma_i32_16x16x64_i8 v[74:77], v[190:193], v[234:237], v[74:77]
	v_mfma_i32_16x16x64_i8 v[70:73], v[156:159], v[242:245], v[70:73]
	v_mfma_i32_16x16x64_i8 v[66:69], v[190:193], v[242:245], v[66:69]
	v_mfma_i32_16x16x64_i8 v[94:97], v[172:175], v[222:225], v[94:97]
	v_mfma_i32_16x16x64_i8 v[90:93], v[194:197], v[222:225], v[90:93]
	v_mfma_i32_16x16x64_i8 v[86:89], v[172:175], v[230:233], v[86:89]
	v_mfma_i32_16x16x64_i8 v[82:85], v[194:197], v[230:233], v[82:85]
	v_mfma_i32_16x16x64_i8 v[78:81], v[172:175], v[238:241], v[78:81]
	v_mfma_i32_16x16x64_i8 v[74:77], v[194:197], v[238:241], v[74:77]
	v_mfma_i32_16x16x64_i8 v[70:73], v[172:175], v[246:249], v[70:73]
	v_mfma_i32_16x16x64_i8 v[66:69], v[194:197], v[246:249], v[66:69]
	v_mfma_i32_16x16x64_i8 v[30:33], v[198:201], v[214:217], v[30:33]
	v_mfma_i32_16x16x64_i8 v[26:29], v[206:209], v[214:217], v[26:29]
	v_mfma_i32_16x16x64_i8 v[22:25], v[198:201], v[226:229], v[22:25]
	v_mfma_i32_16x16x64_i8 v[18:21], v[206:209], v[226:229], v[18:21]
	v_mfma_i32_16x16x64_i8 v[14:17], v[198:201], v[234:237], v[14:17]
	v_mfma_i32_16x16x64_i8 v[10:13], v[206:209], v[234:237], v[10:13]
	v_mfma_i32_16x16x64_i8 v[6:9], v[198:201], v[242:245], v[6:9]
	v_mfma_i32_16x16x64_i8 v[2:5], v[206:209], v[242:245], v[2:5]
	v_mfma_i32_16x16x64_i8 v[30:33], v[202:205], v[222:225], v[30:33]
	v_mfma_i32_16x16x64_i8 v[26:29], v[210:213], v[222:225], v[26:29]
	v_mfma_i32_16x16x64_i8 v[22:25], v[202:205], v[230:233], v[22:25]
	v_mfma_i32_16x16x64_i8 v[18:21], v[210:213], v[230:233], v[18:21]
	v_mfma_i32_16x16x64_i8 v[14:17], v[202:205], v[238:241], v[14:17]
	v_mfma_i32_16x16x64_i8 v[10:13], v[210:213], v[238:241], v[10:13]
	v_mfma_i32_16x16x64_i8 v[6:9], v[202:205], v[246:249], v[6:9]
	v_mfma_i32_16x16x64_i8 v[2:5], v[210:213], v[246:249], v[2:5]
	s_barrier
	s_add_i32 s60, s60, 2
	s_add_u32 s15, s15, 0x100
	s_addc_u32 s17, s17, 0
	s_add_u32 s26, s26, 0x100
	s_addc_u32 s27, s27, 0
	s_cmp_gt_u32 s60, 13
	s_cbranch_scc0 .LBB0_696
	s_and_b64 vcc, exec, s[12:13]
	s_cbranch_vccz .LBB0_699
	s_barrier

.LBB0_968:
	s_add_i32 s76, s24, 2
	s_add_u32 s25, s22, 0xfff80080
	s_addc_u32 s26, s23, -1
	s_add_i32 s36, 0, 0x10000
	s_cmp_eq_u32 s56, s24
	s_cselect_b32 s27, s19, s26
	s_cselect_b32 s26, s18, s25
	s_cselect_b32 s25, s21, s75
	s_cselect_b32 s24, s20, s74
	s_add_i32 s38, 0, 0x14000
	v_add_u32_e32 v152, s36, v211
	v_add_u32_e32 v160, s38, v211
	ds_read_b128 v[140:143], v152
	ds_read_b128 v[144:147], v152 offset:1024
	ds_read_b128 v[148:151], v152 offset:2048
	ds_read_b128 v[152:155], v152 offset:3072
	ds_read_b128 v[156:159], v160
	ds_read_b128 v[172:175], v160 offset:1024
	ds_read_b128 v[176:179], v160 offset:2048
	ds_read_b128 v[180:183], v160 offset:3072
	v_lshl_add_u64 v[160:161], s[22:23], 0, v[138:139]
	s_add_i32 m0, s61, 0xc000
	ds_read_b128 v[184:187], v213
	ds_read_b128 v[188:191], v213 offset:1024
	ds_read_b128 v[192:195], v213 offset:2048
	ds_read_b128 v[196:199], v213 offset:3072
	ds_read_b128 v[200:203], v213 offset:4096
	ds_read_b128 v[204:207], v213 offset:5120
	ds_read_b128 v[222:225], v213 offset:6144
	ds_read_b128 v[226:229], v213 offset:7168
	global_load_lds_dwordx4 v[160:161], off
	v_lshl_add_u64 v[160:161], s[22:23], 0, v[136:137]
	s_add_i32 m0, s61, 0xe000
	s_nop 0
	global_load_lds_dwordx4 v[160:161], off
	s_waitcnt vmcnt(8)
	s_waitcnt lgkmcnt(0)
	s_barrier
	v_mfma_f32_16x16x32_bf16 v[126:129], v[140:143], v[184:187], v[126:129]
	v_mfma_f32_16x16x32_bf16 v[122:125], v[148:151], v[184:187], v[122:125]
	v_mfma_f32_16x16x32_bf16 v[118:121], v[140:143], v[192:195], v[118:121]
	v_mfma_f32_16x16x32_bf16 v[114:117], v[148:151], v[192:195], v[114:117]
	v_mfma_f32_16x16x32_bf16 v[110:113], v[140:143], v[200:203], v[110:113]
	v_mfma_f32_16x16x32_bf16 v[106:109], v[148:151], v[200:203], v[106:109]
	v_mfma_f32_16x16x32_bf16 v[102:105], v[140:143], v[222:225], v[102:105]
	v_mfma_f32_16x16x32_bf16 v[98:101], v[148:151], v[222:225], v[98:101]
	v_mfma_f32_16x16x32_bf16 v[126:129], v[144:147], v[188:191], v[126:129]
	v_mfma_f32_16x16x32_bf16 v[122:125], v[152:155], v[188:191], v[122:125]
	v_mfma_f32_16x16x32_bf16 v[118:121], v[144:147], v[196:199], v[118:121]
	v_mfma_f32_16x16x32_bf16 v[114:117], v[152:155], v[196:199], v[114:117]
	v_mfma_f32_16x16x32_bf16 v[110:113], v[144:147], v[204:207], v[110:113]
	v_mfma_f32_16x16x32_bf16 v[106:109], v[152:155], v[204:207], v[106:109]
	v_mfma_f32_16x16x32_bf16 v[102:105], v[144:147], v[226:229], v[102:105]
	v_mfma_f32_16x16x32_bf16 v[98:101], v[152:155], v[226:229], v[98:101]
	v_mfma_f32_16x16x32_bf16 v[94:97], v[156:159], v[184:187], v[94:97]
	v_mfma_f32_16x16x32_bf16 v[90:93], v[176:179], v[184:187], v[90:93]
	v_mfma_f32_16x16x32_bf16 v[86:89], v[156:159], v[192:195], v[86:89]
	v_mfma_f32_16x16x32_bf16 v[82:85], v[176:179], v[192:195], v[82:85]
	v_mfma_f32_16x16x32_bf16 v[78:81], v[156:159], v[200:203], v[78:81]
	v_mfma_f32_16x16x32_bf16 v[74:77], v[176:179], v[200:203], v[74:77]
	v_mfma_f32_16x16x32_bf16 v[70:73], v[156:159], v[222:225], v[70:73]
	v_mfma_f32_16x16x32_bf16 v[66:69], v[176:179], v[222:225], v[66:69]
	v_mfma_f32_16x16x32_bf16 v[94:97], v[172:175], v[188:191], v[94:97]
	v_mfma_f32_16x16x32_bf16 v[90:93], v[180:183], v[188:191], v[90:93]
	v_mfma_f32_16x16x32_bf16 v[86:89], v[172:175], v[196:199], v[86:89]
	v_mfma_f32_16x16x32_bf16 v[82:85], v[180:183], v[196:199], v[82:85]
	v_mfma_f32_16x16x32_bf16 v[78:81], v[172:175], v[204:207], v[78:81]
	v_mfma_f32_16x16x32_bf16 v[74:77], v[180:183], v[204:207], v[74:77]
	v_mfma_f32_16x16x32_bf16 v[70:73], v[172:175], v[226:229], v[70:73]
	v_mfma_f32_16x16x32_bf16 v[66:69], v[180:183], v[226:229], v[66:69]
	s_barrier
	s_add_i32 s36, s36, s60
	v_lshl_add_u64 v[160:161], s[24:25], 0, v[162:163]
	s_mov_b32 m0, s36
	ds_read_b128 v[184:187], v213 offset:16384
	ds_read_b128 v[188:191], v213 offset:17408
	ds_read_b128 v[192:195], v213 offset:18432
	ds_read_b128 v[196:199], v213 offset:19456
	ds_read_b128 v[200:203], v213 offset:20480
	ds_read_b128 v[204:207], v213 offset:21504
	ds_read_b128 v[222:225], v213 offset:22528
	ds_read_b128 v[226:229], v213 offset:23552
	global_load_lds_dwordx4 v[160:161], off
	s_add_i32 m0, s36, 0x2000
	s_add_u32 s36, s24, 0x80000
	v_lshl_add_u64 v[168:169], s[24:25], 0, v[134:135]
	s_addc_u32 s37, s25, 0
	s_add_i32 s38, s38, s60
	global_load_lds_dwordx4 v[168:169], off
	v_lshl_add_u64 v[170:171], s[36:37], 0, v[162:163]
	s_mov_b32 m0, s38
	v_lshl_add_u64 v[208:209], s[26:27], 0, v[132:133]
	global_load_lds_dwordx4 v[170:171], off
	v_lshl_add_u64 v[170:171], s[36:37], 0, v[134:135]
	s_add_i32 m0, s38, 0x2000
	s_nop 0
	global_load_lds_dwordx4 v[170:171], off
	v_lshl_add_u64 v[170:171], s[26:27], 0, v[130:131]
	s_mov_b32 m0, s61
	s_nop 0
	global_load_lds_dwordx4 v[170:171], off
	s_mov_b32 m0, s62
	s_nop 0
	global_load_lds_dwordx4 v[208:209], off
	s_waitcnt vmcnt(8)
	s_waitcnt lgkmcnt(0)
	s_barrier
	v_mfma_f32_16x16x32_bf16 v[62:65], v[140:143], v[184:187], v[62:65]
	v_mfma_f32_16x16x32_bf16 v[58:61], v[148:151], v[184:187], v[58:61]
	v_mfma_f32_16x16x32_bf16 v[54:57], v[140:143], v[192:195], v[54:57]
	v_mfma_f32_16x16x32_bf16 v[50:53], v[148:151], v[192:195], v[50:53]
	v_mfma_f32_16x16x32_bf16 v[46:49], v[140:143], v[200:203], v[46:49]
	v_mfma_f32_16x16x32_bf16 v[42:45], v[148:151], v[200:203], v[42:45]
	v_mfma_f32_16x16x32_bf16 v[38:41], v[140:143], v[222:225], v[38:41]
	v_mfma_f32_16x16x32_bf16 v[34:37], v[148:151], v[222:225], v[34:37]
	v_mfma_f32_16x16x32_bf16 v[62:65], v[144:147], v[188:191], v[62:65]
	v_mfma_f32_16x16x32_bf16 v[58:61], v[152:155], v[188:191], v[58:61]
	v_mfma_f32_16x16x32_bf16 v[54:57], v[144:147], v[196:199], v[54:57]
	v_mfma_f32_16x16x32_bf16 v[50:53], v[152:155], v[196:199], v[50:53]
	v_mfma_f32_16x16x32_bf16 v[46:49], v[144:147], v[204:207], v[46:49]
	v_mfma_f32_16x16x32_bf16 v[42:45], v[152:155], v[204:207], v[42:45]
	v_mfma_f32_16x16x32_bf16 v[38:41], v[144:147], v[226:229], v[38:41]
	v_mfma_f32_16x16x32_bf16 v[34:37], v[152:155], v[226:229], v[34:37]
	v_mfma_f32_16x16x32_bf16 v[30:33], v[156:159], v[184:187], v[30:33]
	v_mfma_f32_16x16x32_bf16 v[26:29], v[176:179], v[184:187], v[26:29]
	v_mfma_f32_16x16x32_bf16 v[22:25], v[156:159], v[192:195], v[22:25]
	v_mfma_f32_16x16x32_bf16 v[18:21], v[176:179], v[192:195], v[18:21]
	v_mfma_f32_16x16x32_bf16 v[14:17], v[156:159], v[200:203], v[14:17]
	v_mfma_f32_16x16x32_bf16 v[10:13], v[176:179], v[200:203], v[10:13]
	v_mfma_f32_16x16x32_bf16 v[6:9], v[156:159], v[222:225], v[6:9]
	v_mfma_f32_16x16x32_bf16 v[2:5], v[176:179], v[222:225], v[2:5]
	v_mfma_f32_16x16x32_bf16 v[30:33], v[172:175], v[188:191], v[30:33]
	v_mfma_f32_16x16x32_bf16 v[26:29], v[180:183], v[188:191], v[26:29]
	v_mfma_f32_16x16x32_bf16 v[22:25], v[172:175], v[196:199], v[22:25]
	v_mfma_f32_16x16x32_bf16 v[18:21], v[180:183], v[196:199], v[18:21]
	v_mfma_f32_16x16x32_bf16 v[14:17], v[172:175], v[204:207], v[14:17]
	v_mfma_f32_16x16x32_bf16 v[10:13], v[180:183], v[204:207], v[10:13]
	v_mfma_f32_16x16x32_bf16 v[6:9], v[172:175], v[226:229], v[6:9]
	v_mfma_f32_16x16x32_bf16 v[2:5], v[180:183], v[226:229], v[2:5]
	s_barrier
	s_add_i32 s36, 0, 0x18000
	s_add_i32 s37, 0, 0x1c000
	v_add_u32_e32 v152, s36, v211
	v_add_u32_e32 v180, s37, v211
	ds_read_b128 v[140:143], v152
	ds_read_b128 v[144:147], v152 offset:1024
	ds_read_b128 v[148:151], v152 offset:2048
	ds_read_b128 v[152:155], v152 offset:3072
	ds_read_b128 v[156:159], v180
	ds_read_b128 v[172:175], v180 offset:1024
	ds_read_b128 v[176:179], v180 offset:2048
	ds_read_b128 v[180:183], v180 offset:3072
	s_add_u32 s26, s26, 0x80000
	s_addc_u32 s27, s27, 0
	s_mov_b32 m0, s63
	v_lshl_add_u64 v[216:217], s[26:27], 0, v[130:131]
	ds_read_b128 v[184:187], v213 offset:32768
	ds_read_b128 v[188:191], v213 offset:33792
	ds_read_b128 v[192:195], v213 offset:34816
	ds_read_b128 v[196:199], v213 offset:35840
	ds_read_b128 v[200:203], v213 offset:36864
	ds_read_b128 v[204:207], v213 offset:37888
	ds_read_b128 v[222:225], v213 offset:38912
	ds_read_b128 v[226:229], v213 offset:39936
	global_load_lds_dwordx4 v[216:217], off
	v_lshl_add_u64 v[216:217], s[26:27], 0, v[132:133]
	s_mov_b32 m0, s64
	s_nop 0
	global_load_lds_dwordx4 v[216:217], off
	s_waitcnt vmcnt(8)
	s_waitcnt lgkmcnt(0)
	s_barrier
	v_mfma_f32_16x16x32_bf16 v[126:129], v[140:143], v[184:187], v[126:129]
	v_mfma_f32_16x16x32_bf16 v[122:125], v[148:151], v[184:187], v[122:125]
	v_mfma_f32_16x16x32_bf16 v[118:121], v[140:143], v[192:195], v[118:121]
	v_mfma_f32_16x16x32_bf16 v[114:117], v[148:151], v[192:195], v[114:117]
	v_mfma_f32_16x16x32_bf16 v[110:113], v[140:143], v[200:203], v[110:113]
	v_mfma_f32_16x16x32_bf16 v[106:109], v[148:151], v[200:203], v[106:109]
	v_mfma_f32_16x16x32_bf16 v[102:105], v[140:143], v[222:225], v[102:105]
	v_mfma_f32_16x16x32_bf16 v[98:101], v[148:151], v[222:225], v[98:101]
	v_mfma_f32_16x16x32_bf16 v[126:129], v[144:147], v[188:191], v[126:129]
	v_mfma_f32_16x16x32_bf16 v[122:125], v[152:155], v[188:191], v[122:125]
	v_mfma_f32_16x16x32_bf16 v[118:121], v[144:147], v[196:199], v[118:121]
	v_mfma_f32_16x16x32_bf16 v[114:117], v[152:155], v[196:199], v[114:117]
	v_mfma_f32_16x16x32_bf16 v[110:113], v[144:147], v[204:207], v[110:113]
	v_mfma_f32_16x16x32_bf16 v[106:109], v[152:155], v[204:207], v[106:109]
	v_mfma_f32_16x16x32_bf16 v[102:105], v[144:147], v[226:229], v[102:105]
	v_mfma_f32_16x16x32_bf16 v[98:101], v[152:155], v[226:229], v[98:101]
	v_mfma_f32_16x16x32_bf16 v[94:97], v[156:159], v[184:187], v[94:97]
	v_mfma_f32_16x16x32_bf16 v[90:93], v[176:179], v[184:187], v[90:93]
	v_mfma_f32_16x16x32_bf16 v[86:89], v[156:159], v[192:195], v[86:89]
	v_mfma_f32_16x16x32_bf16 v[82:85], v[176:179], v[192:195], v[82:85]
	v_mfma_f32_16x16x32_bf16 v[78:81], v[156:159], v[200:203], v[78:81]
	v_mfma_f32_16x16x32_bf16 v[74:77], v[176:179], v[200:203], v[74:77]
	v_mfma_f32_16x16x32_bf16 v[70:73], v[156:159], v[222:225], v[70:73]
	v_mfma_f32_16x16x32_bf16 v[66:69], v[176:179], v[222:225], v[66:69]
	v_mfma_f32_16x16x32_bf16 v[94:97], v[172:175], v[188:191], v[94:97]
	v_mfma_f32_16x16x32_bf16 v[90:93], v[180:183], v[188:191], v[90:93]
	v_mfma_f32_16x16x32_bf16 v[86:89], v[172:175], v[196:199], v[86:89]
	v_mfma_f32_16x16x32_bf16 v[82:85], v[180:183], v[196:199], v[82:85]
	v_mfma_f32_16x16x32_bf16 v[78:81], v[172:175], v[204:207], v[78:81]
	v_mfma_f32_16x16x32_bf16 v[74:77], v[180:183], v[204:207], v[74:77]
	v_mfma_f32_16x16x32_bf16 v[70:73], v[172:175], v[226:229], v[70:73]
	v_mfma_f32_16x16x32_bf16 v[66:69], v[180:183], v[226:229], v[66:69]
	s_barrier
	s_add_i32 s26, s36, s60
	v_lshl_add_u64 v[160:161], v[160:161], 0, s[44:45]
	s_mov_b32 m0, s26
	ds_read_b128 v[184:187], v213 offset:49152
	ds_read_b128 v[188:191], v213 offset:50176
	ds_read_b128 v[192:195], v213 offset:51200
	ds_read_b128 v[196:199], v213 offset:52224
	ds_read_b128 v[200:203], v213 offset:53248
	ds_read_b128 v[204:207], v213 offset:54272
	ds_read_b128 v[222:225], v213 offset:55296
	ds_read_b128 v[226:229], v213 offset:56320
	global_load_lds_dwordx4 v[160:161], off
	s_add_i32 m0, s26, 0x2000
	s_add_u32 s24, s24, 0x80080
	v_lshl_add_u64 v[160:161], v[168:169], 0, s[44:45]
	s_addc_u32 s25, s25, 0
	s_add_i32 s26, s37, s60
	global_load_lds_dwordx4 v[160:161], off
	v_lshl_add_u64 v[160:161], s[24:25], 0, v[162:163]
	s_mov_b32 m0, s26
	s_nop 0
	global_load_lds_dwordx4 v[160:161], off
	v_lshl_add_u64 v[160:161], s[24:25], 0, v[134:135]
	s_add_i32 m0, s26, 0x2000
	s_nop 0
	global_load_lds_dwordx4 v[160:161], off
	v_lshl_add_u64 v[160:161], v[170:171], 0, s[44:45]
	s_mov_b32 m0, s65
	s_nop 0
	global_load_lds_dwordx4 v[160:161], off
	v_lshl_add_u64 v[160:161], v[208:209], 0, s[44:45]
	s_mov_b32 m0, s66
	s_nop 0
	global_load_lds_dwordx4 v[160:161], off
	s_waitcnt vmcnt(8)
	s_waitcnt lgkmcnt(0)
	s_barrier
	v_mfma_f32_16x16x32_bf16 v[62:65], v[140:143], v[184:187], v[62:65]
	v_mfma_f32_16x16x32_bf16 v[58:61], v[148:151], v[184:187], v[58:61]
	v_mfma_f32_16x16x32_bf16 v[54:57], v[140:143], v[192:195], v[54:57]
	v_mfma_f32_16x16x32_bf16 v[50:53], v[148:151], v[192:195], v[50:53]
	v_mfma_f32_16x16x32_bf16 v[46:49], v[140:143], v[200:203], v[46:49]
	v_mfma_f32_16x16x32_bf16 v[42:45], v[148:151], v[200:203], v[42:45]
	v_mfma_f32_16x16x32_bf16 v[38:41], v[140:143], v[222:225], v[38:41]
	v_mfma_f32_16x16x32_bf16 v[34:37], v[148:151], v[222:225], v[34:37]
	v_mfma_f32_16x16x32_bf16 v[62:65], v[144:147], v[188:191], v[62:65]
	v_mfma_f32_16x16x32_bf16 v[58:61], v[152:155], v[188:191], v[58:61]
	v_mfma_f32_16x16x32_bf16 v[54:57], v[144:147], v[196:199], v[54:57]
	v_mfma_f32_16x16x32_bf16 v[50:53], v[152:155], v[196:199], v[50:53]
	v_mfma_f32_16x16x32_bf16 v[46:49], v[144:147], v[204:207], v[46:49]
	v_mfma_f32_16x16x32_bf16 v[42:45], v[152:155], v[204:207], v[42:45]
	v_mfma_f32_16x16x32_bf16 v[38:41], v[144:147], v[226:229], v[38:41]
	v_mfma_f32_16x16x32_bf16 v[34:37], v[152:155], v[226:229], v[34:37]
	v_mfma_f32_16x16x32_bf16 v[30:33], v[156:159], v[184:187], v[30:33]
	v_mfma_f32_16x16x32_bf16 v[26:29], v[176:179], v[184:187], v[26:29]
	v_mfma_f32_16x16x32_bf16 v[22:25], v[156:159], v[192:195], v[22:25]
	v_mfma_f32_16x16x32_bf16 v[18:21], v[176:179], v[192:195], v[18:21]
	v_mfma_f32_16x16x32_bf16 v[14:17], v[156:159], v[200:203], v[14:17]
	v_mfma_f32_16x16x32_bf16 v[10:13], v[176:179], v[200:203], v[10:13]
	v_mfma_f32_16x16x32_bf16 v[6:9], v[156:159], v[222:225], v[6:9]
	v_mfma_f32_16x16x32_bf16 v[2:5], v[176:179], v[222:225], v[2:5]
	v_mfma_f32_16x16x32_bf16 v[30:33], v[172:175], v[188:191], v[30:33]
	v_mfma_f32_16x16x32_bf16 v[26:29], v[180:183], v[188:191], v[26:29]
	v_mfma_f32_16x16x32_bf16 v[22:25], v[172:175], v[196:199], v[22:25]
	v_mfma_f32_16x16x32_bf16 v[18:21], v[180:183], v[196:199], v[18:21]
	v_mfma_f32_16x16x32_bf16 v[14:17], v[172:175], v[204:207], v[14:17]
	v_mfma_f32_16x16x32_bf16 v[10:13], v[180:183], v[204:207], v[10:13]
	v_mfma_f32_16x16x32_bf16 v[6:9], v[172:175], v[226:229], v[6:9]
	v_mfma_f32_16x16x32_bf16 v[2:5], v[180:183], v[226:229], v[2:5]
	s_barrier
	s_add_u32 s74, s74, 0x100
	s_addc_u32 s75, s75, 0
	s_add_u32 s22, s22, 0x100
	s_addc_u32 s23, s23, 0
	s_cmp_ge_i32 s76, s9
	s_mov_b32 s24, s76
	s_cbranch_scc0 .LBB0_968
	s_and_b64 vcc, exec, s[14:15]
	s_cbranch_vccz .LBB0_971
	s_barrier

.LBB0_1211:
	s_add_u32 s36, s56, 0xfff80080
	s_addc_u32 s37, s57, -1
	s_add_i32 s38, 0, 0x10000
	s_cmp_eq_u32 s78, 28
	s_cselect_b32 s61, s21, s37
	s_cselect_b32 s60, s20, s36
	s_cselect_b32 s59, s23, s62
	s_cselect_b32 s58, s22, s25
	s_add_i32 s39, 0, 0x14000
	v_add_u32_e32 v142, s38, v201
	v_add_u32_e32 v168, s39, v201
	ds_read_b128 v[110:113], v142
	ds_read_b128 v[118:121], v142 offset:1024
	ds_read_b128 v[138:141], v142 offset:2048
	ds_read_b128 v[142:145], v142 offset:3072
	ds_read_b128 v[146:149], v168
	ds_read_b128 v[150:153], v168 offset:1024
	ds_read_b128 v[174:177], v168 offset:2048
	ds_read_b128 v[178:181], v168 offset:3072
	v_lshl_add_u64 v[168:169], s[56:57], 0, v[172:173]
	s_add_i32 m0, s66, 0xc000
	ds_read_b128 v[182:185], v203
	ds_read_b128 v[186:189], v203 offset:1024
	ds_read_b128 v[190:193], v203 offset:2048
	ds_read_b128 v[194:197], v203 offset:3072
	ds_read_b128 v[204:207], v203 offset:4096
	ds_read_b128 v[208:211], v203 offset:5120
	ds_read_b128 v[212:215], v203 offset:6144
	ds_read_b128 v[222:225], v203 offset:7168
	global_load_lds_dwordx4 v[168:169], off
	v_lshl_add_u64 v[168:169], s[56:57], 0, v[160:161]
	s_add_i32 m0, s66, 0xe000
	s_nop 0
	global_load_lds_dwordx4 v[168:169], off
	s_waitcnt vmcnt(8)
	s_waitcnt lgkmcnt(0)
	s_barrier
	v_mfma_f32_16x16x32_bf16 v[134:137], v[110:113], v[182:185], v[134:137]
	v_mfma_f32_16x16x32_bf16 v[130:133], v[138:141], v[182:185], v[130:133]
	v_mfma_f32_16x16x32_bf16 v[114:117], v[110:113], v[190:193], v[114:117]
	v_mfma_f32_16x16x32_bf16 v[106:109], v[138:141], v[190:193], v[106:109]
	v_mfma_f32_16x16x32_bf16 v[94:97], v[110:113], v[204:207], v[94:97]
	v_mfma_f32_16x16x32_bf16 v[90:93], v[138:141], v[204:207], v[90:93]
	v_mfma_f32_16x16x32_bf16 v[78:81], v[110:113], v[212:215], v[78:81]
	v_mfma_f32_16x16x32_bf16 v[74:77], v[138:141], v[212:215], v[74:77]
	v_mfma_f32_16x16x32_bf16 v[134:137], v[118:121], v[186:189], v[134:137]
	v_mfma_f32_16x16x32_bf16 v[130:133], v[142:145], v[186:189], v[130:133]
	v_mfma_f32_16x16x32_bf16 v[114:117], v[118:121], v[194:197], v[114:117]
	v_mfma_f32_16x16x32_bf16 v[106:109], v[142:145], v[194:197], v[106:109]
	v_mfma_f32_16x16x32_bf16 v[94:97], v[118:121], v[208:211], v[94:97]
	v_mfma_f32_16x16x32_bf16 v[90:93], v[142:145], v[208:211], v[90:93]
	v_mfma_f32_16x16x32_bf16 v[78:81], v[118:121], v[222:225], v[78:81]
	v_mfma_f32_16x16x32_bf16 v[74:77], v[142:145], v[222:225], v[74:77]
	v_mfma_f32_16x16x32_bf16 v[126:129], v[146:149], v[182:185], v[126:129]
	v_mfma_f32_16x16x32_bf16 v[122:125], v[174:177], v[182:185], v[122:125]
	v_mfma_f32_16x16x32_bf16 v[102:105], v[146:149], v[190:193], v[102:105]
	v_mfma_f32_16x16x32_bf16 v[98:101], v[174:177], v[190:193], v[98:101]
	v_mfma_f32_16x16x32_bf16 v[86:89], v[146:149], v[204:207], v[86:89]
	v_mfma_f32_16x16x32_bf16 v[82:85], v[174:177], v[204:207], v[82:85]
	v_mfma_f32_16x16x32_bf16 v[70:73], v[146:149], v[212:215], v[70:73]
	v_mfma_f32_16x16x32_bf16 v[66:69], v[174:177], v[212:215], v[66:69]
	v_mfma_f32_16x16x32_bf16 v[126:129], v[150:153], v[186:189], v[126:129]
	v_mfma_f32_16x16x32_bf16 v[122:125], v[178:181], v[186:189], v[122:125]
	v_mfma_f32_16x16x32_bf16 v[102:105], v[150:153], v[194:197], v[102:105]
	v_mfma_f32_16x16x32_bf16 v[98:101], v[178:181], v[194:197], v[98:101]
	v_mfma_f32_16x16x32_bf16 v[86:89], v[150:153], v[208:211], v[86:89]
	v_mfma_f32_16x16x32_bf16 v[82:85], v[178:181], v[208:211], v[82:85]
	v_mfma_f32_16x16x32_bf16 v[70:73], v[150:153], v[222:225], v[70:73]
	v_mfma_f32_16x16x32_bf16 v[66:69], v[178:181], v[222:225], v[66:69]
	s_barrier
	s_add_i32 s36, s38, s27
	v_lshl_add_u64 v[168:169], s[58:59], 0, v[162:163]
	s_mov_b32 m0, s36
	ds_read_b128 v[182:185], v203 offset:16384
	ds_read_b128 v[186:189], v203 offset:17408
	ds_read_b128 v[190:193], v203 offset:18432
	ds_read_b128 v[194:197], v203 offset:19456
	ds_read_b128 v[204:207], v203 offset:20480
	ds_read_b128 v[208:211], v203 offset:21504
	ds_read_b128 v[212:215], v203 offset:22528
	ds_read_b128 v[222:225], v203 offset:23552
	global_load_lds_dwordx4 v[168:169], off
	s_add_i32 m0, s36, 0x2000
	s_add_u32 s36, s58, 0x80000
	v_lshl_add_u64 v[170:171], s[58:59], 0, v[158:159]
	s_addc_u32 s37, s59, 0
	s_add_i32 s38, s39, s27
	global_load_lds_dwordx4 v[170:171], off
	v_lshl_add_u64 v[198:199], s[36:37], 0, v[162:163]
	s_mov_b32 m0, s38
	v_lshl_add_u64 v[216:217], s[60:61], 0, v[156:157]
	global_load_lds_dwordx4 v[198:199], off
	v_lshl_add_u64 v[198:199], s[36:37], 0, v[158:159]
	s_add_i32 m0, s38, 0x2000
	s_nop 0
	global_load_lds_dwordx4 v[198:199], off
	v_lshl_add_u64 v[198:199], s[60:61], 0, v[154:155]
	s_mov_b32 m0, s66
	s_nop 0
	global_load_lds_dwordx4 v[198:199], off
	s_mov_b32 m0, s67
	s_nop 0
	global_load_lds_dwordx4 v[216:217], off
	s_waitcnt vmcnt(8)
	s_waitcnt lgkmcnt(0)
	s_barrier
	v_mfma_f32_16x16x32_bf16 v[62:65], v[110:113], v[182:185], v[62:65]
	v_mfma_f32_16x16x32_bf16 v[58:61], v[138:141], v[182:185], v[58:61]
	v_mfma_f32_16x16x32_bf16 v[46:49], v[110:113], v[190:193], v[46:49]
	v_mfma_f32_16x16x32_bf16 v[42:45], v[138:141], v[190:193], v[42:45]
	v_mfma_f32_16x16x32_bf16 v[30:33], v[110:113], v[204:207], v[30:33]
	v_mfma_f32_16x16x32_bf16 v[26:29], v[138:141], v[204:207], v[26:29]
	v_mfma_f32_16x16x32_bf16 v[14:17], v[110:113], v[212:215], v[14:17]
	v_mfma_f32_16x16x32_bf16 v[10:13], v[138:141], v[212:215], v[10:13]
	v_mfma_f32_16x16x32_bf16 v[62:65], v[118:121], v[186:189], v[62:65]
	v_mfma_f32_16x16x32_bf16 v[58:61], v[142:145], v[186:189], v[58:61]
	v_mfma_f32_16x16x32_bf16 v[46:49], v[118:121], v[194:197], v[46:49]
	v_mfma_f32_16x16x32_bf16 v[42:45], v[142:145], v[194:197], v[42:45]
	v_mfma_f32_16x16x32_bf16 v[30:33], v[118:121], v[208:211], v[30:33]
	v_mfma_f32_16x16x32_bf16 v[26:29], v[142:145], v[208:211], v[26:29]
	v_mfma_f32_16x16x32_bf16 v[14:17], v[118:121], v[222:225], v[14:17]
	v_mfma_f32_16x16x32_bf16 v[10:13], v[142:145], v[222:225], v[10:13]
	v_mfma_f32_16x16x32_bf16 v[54:57], v[146:149], v[182:185], v[54:57]
	v_mfma_f32_16x16x32_bf16 v[50:53], v[174:177], v[182:185], v[50:53]
	v_mfma_f32_16x16x32_bf16 v[38:41], v[146:149], v[190:193], v[38:41]
	v_mfma_f32_16x16x32_bf16 v[34:37], v[174:177], v[190:193], v[34:37]
	v_mfma_f32_16x16x32_bf16 v[22:25], v[146:149], v[204:207], v[22:25]
	v_mfma_f32_16x16x32_bf16 v[18:21], v[174:177], v[204:207], v[18:21]
	v_mfma_f32_16x16x32_bf16 v[6:9], v[146:149], v[212:215], v[6:9]
	v_mfma_f32_16x16x32_bf16 v[2:5], v[174:177], v[212:215], v[2:5]
	v_mfma_f32_16x16x32_bf16 v[54:57], v[150:153], v[186:189], v[54:57]
	v_mfma_f32_16x16x32_bf16 v[50:53], v[178:181], v[186:189], v[50:53]
	v_mfma_f32_16x16x32_bf16 v[38:41], v[150:153], v[194:197], v[38:41]
	v_mfma_f32_16x16x32_bf16 v[34:37], v[178:181], v[194:197], v[34:37]
	v_mfma_f32_16x16x32_bf16 v[22:25], v[150:153], v[208:211], v[22:25]
	v_mfma_f32_16x16x32_bf16 v[18:21], v[178:181], v[208:211], v[18:21]
	v_mfma_f32_16x16x32_bf16 v[6:9], v[150:153], v[222:225], v[6:9]
	v_mfma_f32_16x16x32_bf16 v[2:5], v[178:181], v[222:225], v[2:5]
	s_barrier
	s_add_i32 s38, 0, 0x18000
	s_add_i32 s39, 0, 0x1c000
	v_add_u32_e32 v142, s38, v201
	v_add_u32_e32 v178, s39, v201
	ds_read_b128 v[110:113], v142
	ds_read_b128 v[118:121], v142 offset:1024
	ds_read_b128 v[138:141], v142 offset:2048
	ds_read_b128 v[142:145], v142 offset:3072
	ds_read_b128 v[146:149], v178
	ds_read_b128 v[150:153], v178 offset:1024
	ds_read_b128 v[174:177], v178 offset:2048
	ds_read_b128 v[178:181], v178 offset:3072
	s_add_u32 s36, s60, 0x80000
	s_addc_u32 s37, s61, 0
	s_mov_b32 m0, s68
	v_lshl_add_u64 v[226:227], s[36:37], 0, v[154:155]
	ds_read_b128 v[182:185], v203 offset:32768
	ds_read_b128 v[186:189], v203 offset:33792
	ds_read_b128 v[190:193], v203 offset:34816
	ds_read_b128 v[194:197], v203 offset:35840
	ds_read_b128 v[204:207], v203 offset:36864
	ds_read_b128 v[208:211], v203 offset:37888
	ds_read_b128 v[212:215], v203 offset:38912
	ds_read_b128 v[222:225], v203 offset:39936
	global_load_lds_dwordx4 v[226:227], off
	v_lshl_add_u64 v[226:227], s[36:37], 0, v[156:157]
	s_mov_b32 m0, s69
	s_nop 0
	global_load_lds_dwordx4 v[226:227], off
	s_waitcnt vmcnt(8)
	s_waitcnt lgkmcnt(0)
	s_barrier
	v_mfma_f32_16x16x32_bf16 v[134:137], v[110:113], v[182:185], v[134:137]
	v_mfma_f32_16x16x32_bf16 v[130:133], v[138:141], v[182:185], v[130:133]
	v_mfma_f32_16x16x32_bf16 v[114:117], v[110:113], v[190:193], v[114:117]
	v_mfma_f32_16x16x32_bf16 v[106:109], v[138:141], v[190:193], v[106:109]
	v_mfma_f32_16x16x32_bf16 v[94:97], v[110:113], v[204:207], v[94:97]
	v_mfma_f32_16x16x32_bf16 v[90:93], v[138:141], v[204:207], v[90:93]
	v_mfma_f32_16x16x32_bf16 v[78:81], v[110:113], v[212:215], v[78:81]
	v_mfma_f32_16x16x32_bf16 v[74:77], v[138:141], v[212:215], v[74:77]
	v_mfma_f32_16x16x32_bf16 v[134:137], v[118:121], v[186:189], v[134:137]
	v_mfma_f32_16x16x32_bf16 v[130:133], v[142:145], v[186:189], v[130:133]
	v_mfma_f32_16x16x32_bf16 v[114:117], v[118:121], v[194:197], v[114:117]
	v_mfma_f32_16x16x32_bf16 v[106:109], v[142:145], v[194:197], v[106:109]
	v_mfma_f32_16x16x32_bf16 v[94:97], v[118:121], v[208:211], v[94:97]
	v_mfma_f32_16x16x32_bf16 v[90:93], v[142:145], v[208:211], v[90:93]
	v_mfma_f32_16x16x32_bf16 v[78:81], v[118:121], v[222:225], v[78:81]
	v_mfma_f32_16x16x32_bf16 v[74:77], v[142:145], v[222:225], v[74:77]
	v_mfma_f32_16x16x32_bf16 v[126:129], v[146:149], v[182:185], v[126:129]
	v_mfma_f32_16x16x32_bf16 v[122:125], v[174:177], v[182:185], v[122:125]
	v_mfma_f32_16x16x32_bf16 v[102:105], v[146:149], v[190:193], v[102:105]
	v_mfma_f32_16x16x32_bf16 v[98:101], v[174:177], v[190:193], v[98:101]
	v_mfma_f32_16x16x32_bf16 v[86:89], v[146:149], v[204:207], v[86:89]
	v_mfma_f32_16x16x32_bf16 v[82:85], v[174:177], v[204:207], v[82:85]
	v_mfma_f32_16x16x32_bf16 v[70:73], v[146:149], v[212:215], v[70:73]
	v_mfma_f32_16x16x32_bf16 v[66:69], v[174:177], v[212:215], v[66:69]
	v_mfma_f32_16x16x32_bf16 v[126:129], v[150:153], v[186:189], v[126:129]
	v_mfma_f32_16x16x32_bf16 v[122:125], v[178:181], v[186:189], v[122:125]
	v_mfma_f32_16x16x32_bf16 v[102:105], v[150:153], v[194:197], v[102:105]
	v_mfma_f32_16x16x32_bf16 v[98:101], v[178:181], v[194:197], v[98:101]
	v_mfma_f32_16x16x32_bf16 v[86:89], v[150:153], v[208:211], v[86:89]
	v_mfma_f32_16x16x32_bf16 v[82:85], v[178:181], v[208:211], v[82:85]
	v_mfma_f32_16x16x32_bf16 v[70:73], v[150:153], v[222:225], v[70:73]
	v_mfma_f32_16x16x32_bf16 v[66:69], v[178:181], v[222:225], v[66:69]
	s_barrier
	s_add_i32 s36, s38, s27
	v_lshl_add_u64 v[168:169], v[168:169], 0, s[44:45]
	s_mov_b32 m0, s36
	ds_read_b128 v[182:185], v203 offset:49152
	ds_read_b128 v[186:189], v203 offset:50176
	ds_read_b128 v[190:193], v203 offset:51200
	ds_read_b128 v[194:197], v203 offset:52224
	ds_read_b128 v[204:207], v203 offset:53248
	ds_read_b128 v[208:211], v203 offset:54272
	ds_read_b128 v[212:215], v203 offset:55296
	ds_read_b128 v[222:225], v203 offset:56320
	global_load_lds_dwordx4 v[168:169], off
	s_add_i32 m0, s36, 0x2000
	s_add_u32 s36, s58, 0x80080
	v_lshl_add_u64 v[168:169], v[170:171], 0, s[44:45]
	s_addc_u32 s37, s59, 0
	s_add_i32 s38, s39, s27
	global_load_lds_dwordx4 v[168:169], off
	v_lshl_add_u64 v[168:169], s[36:37], 0, v[162:163]
	s_mov_b32 m0, s38
	s_nop 0
	global_load_lds_dwordx4 v[168:169], off
	v_lshl_add_u64 v[168:169], s[36:37], 0, v[158:159]
	s_add_i32 m0, s38, 0x2000
	s_nop 0
	global_load_lds_dwordx4 v[168:169], off
	v_lshl_add_u64 v[168:169], v[198:199], 0, s[44:45]
	s_mov_b32 m0, s70
	s_nop 0
	global_load_lds_dwordx4 v[168:169], off
	v_lshl_add_u64 v[168:169], v[216:217], 0, s[44:45]
	s_mov_b32 m0, s71
	s_nop 0
	global_load_lds_dwordx4 v[168:169], off
	s_waitcnt vmcnt(8)
	s_waitcnt lgkmcnt(0)
	s_barrier
	v_mfma_f32_16x16x32_bf16 v[62:65], v[110:113], v[182:185], v[62:65]
	v_mfma_f32_16x16x32_bf16 v[58:61], v[138:141], v[182:185], v[58:61]
	v_mfma_f32_16x16x32_bf16 v[46:49], v[110:113], v[190:193], v[46:49]
	v_mfma_f32_16x16x32_bf16 v[42:45], v[138:141], v[190:193], v[42:45]
	v_mfma_f32_16x16x32_bf16 v[30:33], v[110:113], v[204:207], v[30:33]
	v_mfma_f32_16x16x32_bf16 v[26:29], v[138:141], v[204:207], v[26:29]
	v_mfma_f32_16x16x32_bf16 v[14:17], v[110:113], v[212:215], v[14:17]
	v_mfma_f32_16x16x32_bf16 v[10:13], v[138:141], v[212:215], v[10:13]
	v_mfma_f32_16x16x32_bf16 v[62:65], v[118:121], v[186:189], v[62:65]
	v_mfma_f32_16x16x32_bf16 v[58:61], v[142:145], v[186:189], v[58:61]
	v_mfma_f32_16x16x32_bf16 v[46:49], v[118:121], v[194:197], v[46:49]
	v_mfma_f32_16x16x32_bf16 v[42:45], v[142:145], v[194:197], v[42:45]
	v_mfma_f32_16x16x32_bf16 v[30:33], v[118:121], v[208:211], v[30:33]
	v_mfma_f32_16x16x32_bf16 v[26:29], v[142:145], v[208:211], v[26:29]
	v_mfma_f32_16x16x32_bf16 v[14:17], v[118:121], v[222:225], v[14:17]
	v_mfma_f32_16x16x32_bf16 v[10:13], v[142:145], v[222:225], v[10:13]
	v_mfma_f32_16x16x32_bf16 v[54:57], v[146:149], v[182:185], v[54:57]
	v_mfma_f32_16x16x32_bf16 v[50:53], v[174:177], v[182:185], v[50:53]
	v_mfma_f32_16x16x32_bf16 v[38:41], v[146:149], v[190:193], v[38:41]
	v_mfma_f32_16x16x32_bf16 v[34:37], v[174:177], v[190:193], v[34:37]
	v_mfma_f32_16x16x32_bf16 v[22:25], v[146:149], v[204:207], v[22:25]
	v_mfma_f32_16x16x32_bf16 v[18:21], v[174:177], v[204:207], v[18:21]
	v_mfma_f32_16x16x32_bf16 v[6:9], v[146:149], v[212:215], v[6:9]
	v_mfma_f32_16x16x32_bf16 v[2:5], v[174:177], v[212:215], v[2:5]
	v_mfma_f32_16x16x32_bf16 v[54:57], v[150:153], v[186:189], v[54:57]
	v_mfma_f32_16x16x32_bf16 v[50:53], v[178:181], v[186:189], v[50:53]
	v_mfma_f32_16x16x32_bf16 v[38:41], v[150:153], v[194:197], v[38:41]
	v_mfma_f32_16x16x32_bf16 v[34:37], v[178:181], v[194:197], v[34:37]
	v_mfma_f32_16x16x32_bf16 v[22:25], v[150:153], v[208:211], v[22:25]
	v_mfma_f32_16x16x32_bf16 v[18:21], v[178:181], v[208:211], v[18:21]
	v_mfma_f32_16x16x32_bf16 v[6:9], v[150:153], v[222:225], v[6:9]
	v_mfma_f32_16x16x32_bf16 v[2:5], v[178:181], v[222:225], v[2:5]
	s_barrier
	s_add_i32 s78, s78, 2
	s_add_u32 s25, s25, 0x100
	s_addc_u32 s62, s62, 0
	s_add_u32 s56, s56, 0x100
	s_addc_u32 s57, s57, 0
	s_cmp_gt_u32 s78, 29
	s_cbranch_scc0 .LBB0_1211
	s_and_b64 vcc, exec, s[18:19]
	s_cbranch_vccz .LBB0_1214
	s_barrier

.LBB0_1332:
	s_add_u32 s26, s24, 0xfffc0080
	s_addc_u32 s27, s25, -1
	s_add_i32 s36, 0, 0x10000
	s_cmp_eq_u32 s21, 12
	s_cselect_b32 s57, s17, s27
	s_cselect_b32 s56, s16, s26
	v_add_u32_e32 v142, s36, v161
	s_cselect_b32 s27, s19, s15
	s_cselect_b32 s26, s18, s13
	s_add_i32 s38, 0, 0x14000
	ds_read_b128 v[144:147], v142
	ds_read_b128 v[148:151], v142 offset:1024
	ds_read_b128 v[152:155], v142 offset:2048
	ds_read_b128 v[178:181], v142 offset:3072
	v_add_u32_e32 v142, s38, v161
	ds_read_b128 v[182:185], v142
	ds_read_b128 v[186:189], v142 offset:1024
	ds_read_b128 v[190:193], v142 offset:2048
	ds_read_b128 v[194:197], v142 offset:3072
	v_lshl_add_u64 v[156:157], s[24:25], 0, v[140:141]
	s_add_i32 m0, s69, 0xc000
	ds_read_b128 v[198:201], v177
	ds_read_b128 v[202:205], v177 offset:1024
	ds_read_b128 v[206:209], v177 offset:2048
	ds_read_b128 v[210:213], v177 offset:3072
	ds_read_b128 v[214:217], v177 offset:4096
	ds_read_b128 v[222:225], v177 offset:5120
	ds_read_b128 v[226:229], v177 offset:6144
	ds_read_b128 v[230:233], v177 offset:7168
	global_load_lds_dwordx4 v[156:157], off
	v_lshl_add_u64 v[156:157], s[24:25], 0, v[138:139]
	s_add_i32 m0, s69, 0xe000
	s_nop 0
	global_load_lds_dwordx4 v[156:157], off
	s_waitcnt vmcnt(8)
	s_waitcnt lgkmcnt(0)
	s_barrier
	v_mfma_i32_16x16x64_i8 v[126:129], v[144:147], v[198:201], v[126:129]
	v_mfma_i32_16x16x64_i8 v[118:121], v[152:155], v[198:201], v[118:121]
	v_mfma_i32_16x16x64_i8 v[110:113], v[144:147], v[206:209], v[110:113]
	v_mfma_i32_16x16x64_i8 v[102:105], v[152:155], v[206:209], v[102:105]
	v_mfma_i32_16x16x64_i8 v[94:97], v[144:147], v[214:217], v[94:97]
	v_mfma_i32_16x16x64_i8 v[86:89], v[152:155], v[214:217], v[86:89]
	v_mfma_i32_16x16x64_i8 v[78:81], v[144:147], v[226:229], v[78:81]
	v_mfma_i32_16x16x64_i8 v[70:73], v[152:155], v[226:229], v[70:73]
	v_mfma_i32_16x16x64_i8 v[126:129], v[148:151], v[202:205], v[126:129]
	v_mfma_i32_16x16x64_i8 v[118:121], v[178:181], v[202:205], v[118:121]
	v_mfma_i32_16x16x64_i8 v[110:113], v[148:151], v[210:213], v[110:113]
	v_mfma_i32_16x16x64_i8 v[102:105], v[178:181], v[210:213], v[102:105]
	v_mfma_i32_16x16x64_i8 v[94:97], v[148:151], v[222:225], v[94:97]
	v_mfma_i32_16x16x64_i8 v[86:89], v[178:181], v[222:225], v[86:89]
	v_mfma_i32_16x16x64_i8 v[78:81], v[148:151], v[230:233], v[78:81]
	v_mfma_i32_16x16x64_i8 v[70:73], v[178:181], v[230:233], v[70:73]
	v_mfma_i32_16x16x64_i8 v[122:125], v[182:185], v[198:201], v[122:125]
	v_mfma_i32_16x16x64_i8 v[114:117], v[190:193], v[198:201], v[114:117]
	v_mfma_i32_16x16x64_i8 v[106:109], v[182:185], v[206:209], v[106:109]
	v_mfma_i32_16x16x64_i8 v[98:101], v[190:193], v[206:209], v[98:101]
	v_mfma_i32_16x16x64_i8 v[90:93], v[182:185], v[214:217], v[90:93]
	v_mfma_i32_16x16x64_i8 v[82:85], v[190:193], v[214:217], v[82:85]
	v_mfma_i32_16x16x64_i8 v[74:77], v[182:185], v[226:229], v[74:77]
	v_mfma_i32_16x16x64_i8 v[66:69], v[190:193], v[226:229], v[66:69]
	v_mfma_i32_16x16x64_i8 v[122:125], v[186:189], v[202:205], v[122:125]
	v_mfma_i32_16x16x64_i8 v[114:117], v[194:197], v[202:205], v[114:117]
	v_mfma_i32_16x16x64_i8 v[106:109], v[186:189], v[210:213], v[106:109]
	v_mfma_i32_16x16x64_i8 v[98:101], v[194:197], v[210:213], v[98:101]
	v_mfma_i32_16x16x64_i8 v[90:93], v[186:189], v[222:225], v[90:93]
	v_mfma_i32_16x16x64_i8 v[82:85], v[194:197], v[222:225], v[82:85]
	v_mfma_i32_16x16x64_i8 v[74:77], v[186:189], v[230:233], v[74:77]
	v_mfma_i32_16x16x64_i8 v[66:69], v[194:197], v[230:233], v[66:69]
	s_barrier
	s_add_i32 s36, s36, s23
	v_lshl_add_u64 v[156:157], s[26:27], 0, v[162:163]
	s_mov_b32 m0, s36
	ds_read_b128 v[198:201], v177 offset:16384
	ds_read_b128 v[202:205], v177 offset:17408
	ds_read_b128 v[206:209], v177 offset:18432
	ds_read_b128 v[210:213], v177 offset:19456
	ds_read_b128 v[214:217], v177 offset:20480
	ds_read_b128 v[222:225], v177 offset:21504
	ds_read_b128 v[226:229], v177 offset:22528
	ds_read_b128 v[230:233], v177 offset:23552
	global_load_lds_dwordx4 v[156:157], off
	s_add_i32 m0, s36, 0x2000
	s_add_u32 s36, s26, 0x80000
	v_lshl_add_u64 v[168:169], s[26:27], 0, v[134:135]
	s_addc_u32 s37, s27, 0
	s_add_i32 s38, s38, s23
	global_load_lds_dwordx4 v[168:169], off
	v_lshl_add_u64 v[170:171], s[36:37], 0, v[162:163]
	s_mov_b32 m0, s38
	v_lshl_add_u64 v[174:175], s[56:57], 0, v[132:133]
	global_load_lds_dwordx4 v[170:171], off
	v_lshl_add_u64 v[170:171], s[36:37], 0, v[134:135]
	s_add_i32 m0, s38, 0x2000
	s_nop 0
	global_load_lds_dwordx4 v[170:171], off
	v_lshl_add_u64 v[170:171], s[56:57], 0, v[130:131]
	s_mov_b32 m0, s69
	s_nop 0
	global_load_lds_dwordx4 v[170:171], off
	s_mov_b32 m0, s70
	s_nop 0
	global_load_lds_dwordx4 v[174:175], off
	s_waitcnt vmcnt(8)
	s_waitcnt lgkmcnt(0)
	s_barrier
	v_mfma_i32_16x16x64_i8 v[62:65], v[144:147], v[198:201], v[62:65]
	v_mfma_i32_16x16x64_i8 v[54:57], v[152:155], v[198:201], v[54:57]
	v_mfma_i32_16x16x64_i8 v[46:49], v[144:147], v[206:209], v[46:49]
	v_mfma_i32_16x16x64_i8 v[38:41], v[152:155], v[206:209], v[38:41]
	v_mfma_i32_16x16x64_i8 v[30:33], v[144:147], v[214:217], v[30:33]
	v_mfma_i32_16x16x64_i8 v[22:25], v[152:155], v[214:217], v[22:25]
	v_mfma_i32_16x16x64_i8 v[14:17], v[144:147], v[226:229], v[14:17]
	v_mfma_i32_16x16x64_i8 v[6:9], v[152:155], v[226:229], v[6:9]
	v_mfma_i32_16x16x64_i8 v[62:65], v[148:151], v[202:205], v[62:65]
	v_mfma_i32_16x16x64_i8 v[54:57], v[178:181], v[202:205], v[54:57]
	v_mfma_i32_16x16x64_i8 v[46:49], v[148:151], v[210:213], v[46:49]
	v_mfma_i32_16x16x64_i8 v[38:41], v[178:181], v[210:213], v[38:41]
	v_mfma_i32_16x16x64_i8 v[30:33], v[148:151], v[222:225], v[30:33]
	v_mfma_i32_16x16x64_i8 v[22:25], v[178:181], v[222:225], v[22:25]
	v_mfma_i32_16x16x64_i8 v[14:17], v[148:151], v[230:233], v[14:17]
	v_mfma_i32_16x16x64_i8 v[6:9], v[178:181], v[230:233], v[6:9]
	v_mfma_i32_16x16x64_i8 v[58:61], v[182:185], v[198:201], v[58:61]
	v_mfma_i32_16x16x64_i8 v[50:53], v[190:193], v[198:201], v[50:53]
	v_mfma_i32_16x16x64_i8 v[42:45], v[182:185], v[206:209], v[42:45]
	v_mfma_i32_16x16x64_i8 v[34:37], v[190:193], v[206:209], v[34:37]
	v_mfma_i32_16x16x64_i8 v[26:29], v[182:185], v[214:217], v[26:29]
	v_mfma_i32_16x16x64_i8 v[18:21], v[190:193], v[214:217], v[18:21]
	v_mfma_i32_16x16x64_i8 v[10:13], v[182:185], v[226:229], v[10:13]
	v_mfma_i32_16x16x64_i8 v[2:5], v[190:193], v[226:229], v[2:5]
	v_mfma_i32_16x16x64_i8 v[58:61], v[186:189], v[202:205], v[58:61]
	v_mfma_i32_16x16x64_i8 v[50:53], v[194:197], v[202:205], v[50:53]
	v_mfma_i32_16x16x64_i8 v[42:45], v[186:189], v[210:213], v[42:45]
	v_mfma_i32_16x16x64_i8 v[34:37], v[194:197], v[210:213], v[34:37]
	v_mfma_i32_16x16x64_i8 v[26:29], v[186:189], v[222:225], v[26:29]
	v_mfma_i32_16x16x64_i8 v[18:21], v[194:197], v[222:225], v[18:21]
	v_mfma_i32_16x16x64_i8 v[10:13], v[186:189], v[230:233], v[10:13]
	v_mfma_i32_16x16x64_i8 v[2:5], v[194:197], v[230:233], v[2:5]
	s_barrier
	s_add_i32 s38, 0, 0x18000
	v_add_u32_e32 v142, s38, v161
	s_add_i32 s39, 0, 0x1c000
	ds_read_b128 v[144:147], v142
	ds_read_b128 v[148:151], v142 offset:1024
	ds_read_b128 v[152:155], v142 offset:2048
	ds_read_b128 v[178:181], v142 offset:3072
	v_add_u32_e32 v142, s39, v161
	ds_read_b128 v[182:185], v142
	ds_read_b128 v[186:189], v142 offset:1024
	ds_read_b128 v[190:193], v142 offset:2048
	ds_read_b128 v[194:197], v142 offset:3072
	s_add_u32 s36, s56, 0x40000
	s_addc_u32 s37, s57, 0
	s_mov_b32 m0, s71
	v_lshl_add_u64 v[234:235], s[36:37], 0, v[130:131]
	ds_read_b128 v[198:201], v177 offset:32768
	ds_read_b128 v[202:205], v177 offset:33792
	ds_read_b128 v[206:209], v177 offset:34816
	ds_read_b128 v[210:213], v177 offset:35840
	ds_read_b128 v[214:217], v177 offset:36864
	ds_read_b128 v[222:225], v177 offset:37888
	ds_read_b128 v[226:229], v177 offset:38912
	ds_read_b128 v[230:233], v177 offset:39936
	global_load_lds_dwordx4 v[234:235], off
	v_lshl_add_u64 v[234:235], s[36:37], 0, v[132:133]
	s_mov_b32 m0, s72
	s_nop 0
	global_load_lds_dwordx4 v[234:235], off
	s_waitcnt vmcnt(8)
	s_waitcnt lgkmcnt(0)
	s_barrier
	v_mfma_i32_16x16x64_i8 v[126:129], v[144:147], v[198:201], v[126:129]
	v_mfma_i32_16x16x64_i8 v[118:121], v[152:155], v[198:201], v[118:121]
	v_mfma_i32_16x16x64_i8 v[110:113], v[144:147], v[206:209], v[110:113]
	v_mfma_i32_16x16x64_i8 v[102:105], v[152:155], v[206:209], v[102:105]
	v_mfma_i32_16x16x64_i8 v[94:97], v[144:147], v[214:217], v[94:97]
	v_mfma_i32_16x16x64_i8 v[86:89], v[152:155], v[214:217], v[86:89]
	v_mfma_i32_16x16x64_i8 v[78:81], v[144:147], v[226:229], v[78:81]
	v_mfma_i32_16x16x64_i8 v[70:73], v[152:155], v[226:229], v[70:73]
	v_mfma_i32_16x16x64_i8 v[126:129], v[148:151], v[202:205], v[126:129]
	v_mfma_i32_16x16x64_i8 v[118:121], v[178:181], v[202:205], v[118:121]
	v_mfma_i32_16x16x64_i8 v[110:113], v[148:151], v[210:213], v[110:113]
	v_mfma_i32_16x16x64_i8 v[102:105], v[178:181], v[210:213], v[102:105]
	v_mfma_i32_16x16x64_i8 v[94:97], v[148:151], v[222:225], v[94:97]
	v_mfma_i32_16x16x64_i8 v[86:89], v[178:181], v[222:225], v[86:89]
	v_mfma_i32_16x16x64_i8 v[78:81], v[148:151], v[230:233], v[78:81]
	v_mfma_i32_16x16x64_i8 v[70:73], v[178:181], v[230:233], v[70:73]
	v_mfma_i32_16x16x64_i8 v[122:125], v[182:185], v[198:201], v[122:125]
	v_mfma_i32_16x16x64_i8 v[114:117], v[190:193], v[198:201], v[114:117]
	v_mfma_i32_16x16x64_i8 v[106:109], v[182:185], v[206:209], v[106:109]
	v_mfma_i32_16x16x64_i8 v[98:101], v[190:193], v[206:209], v[98:101]
	v_mfma_i32_16x16x64_i8 v[90:93], v[182:185], v[214:217], v[90:93]
	v_mfma_i32_16x16x64_i8 v[82:85], v[190:193], v[214:217], v[82:85]
	v_mfma_i32_16x16x64_i8 v[74:77], v[182:185], v[226:229], v[74:77]
	v_mfma_i32_16x16x64_i8 v[66:69], v[190:193], v[226:229], v[66:69]
	v_mfma_i32_16x16x64_i8 v[122:125], v[186:189], v[202:205], v[122:125]
	v_mfma_i32_16x16x64_i8 v[114:117], v[194:197], v[202:205], v[114:117]
	v_mfma_i32_16x16x64_i8 v[106:109], v[186:189], v[210:213], v[106:109]
	v_mfma_i32_16x16x64_i8 v[98:101], v[194:197], v[210:213], v[98:101]
	v_mfma_i32_16x16x64_i8 v[90:93], v[186:189], v[222:225], v[90:93]
	v_mfma_i32_16x16x64_i8 v[82:85], v[194:197], v[222:225], v[82:85]
	v_mfma_i32_16x16x64_i8 v[74:77], v[186:189], v[230:233], v[74:77]
	v_mfma_i32_16x16x64_i8 v[66:69], v[194:197], v[230:233], v[66:69]
	s_barrier
	s_add_i32 s36, s38, s23
	v_lshl_add_u64 v[156:157], v[156:157], 0, s[44:45]
	s_mov_b32 m0, s36
	ds_read_b128 v[198:201], v177 offset:49152
	ds_read_b128 v[202:205], v177 offset:50176
	ds_read_b128 v[206:209], v177 offset:51200
	ds_read_b128 v[210:213], v177 offset:52224
	ds_read_b128 v[214:217], v177 offset:53248
	ds_read_b128 v[222:225], v177 offset:54272
	ds_read_b128 v[226:229], v177 offset:55296
	ds_read_b128 v[230:233], v177 offset:56320
	global_load_lds_dwordx4 v[156:157], off
	s_add_i32 m0, s36, 0x2000
	s_add_u32 s26, s26, 0x80080
	v_lshl_add_u64 v[156:157], v[168:169], 0, s[44:45]
	s_addc_u32 s27, s27, 0
	s_add_i32 s36, s39, s23
	global_load_lds_dwordx4 v[156:157], off
	v_lshl_add_u64 v[156:157], s[26:27], 0, v[162:163]
	s_mov_b32 m0, s36
	s_nop 0
	global_load_lds_dwordx4 v[156:157], off
	v_lshl_add_u64 v[156:157], s[26:27], 0, v[134:135]
	s_add_i32 m0, s36, 0x2000
	s_nop 0
	global_load_lds_dwordx4 v[156:157], off
	v_lshl_add_u64 v[156:157], v[170:171], 0, s[44:45]
	s_mov_b32 m0, s73
	s_nop 0
	global_load_lds_dwordx4 v[156:157], off
	v_lshl_add_u64 v[156:157], v[174:175], 0, s[44:45]
	s_mov_b32 m0, s74
	s_nop 0
	global_load_lds_dwordx4 v[156:157], off
	s_waitcnt vmcnt(8)
	s_waitcnt lgkmcnt(0)
	s_barrier
	v_mfma_i32_16x16x64_i8 v[62:65], v[144:147], v[198:201], v[62:65]
	v_mfma_i32_16x16x64_i8 v[54:57], v[152:155], v[198:201], v[54:57]
	v_mfma_i32_16x16x64_i8 v[46:49], v[144:147], v[206:209], v[46:49]
	v_mfma_i32_16x16x64_i8 v[38:41], v[152:155], v[206:209], v[38:41]
	v_mfma_i32_16x16x64_i8 v[30:33], v[144:147], v[214:217], v[30:33]
	v_mfma_i32_16x16x64_i8 v[22:25], v[152:155], v[214:217], v[22:25]
	v_mfma_i32_16x16x64_i8 v[14:17], v[144:147], v[226:229], v[14:17]
	v_mfma_i32_16x16x64_i8 v[6:9], v[152:155], v[226:229], v[6:9]
	v_mfma_i32_16x16x64_i8 v[62:65], v[148:151], v[202:205], v[62:65]
	v_mfma_i32_16x16x64_i8 v[54:57], v[178:181], v[202:205], v[54:57]
	v_mfma_i32_16x16x64_i8 v[46:49], v[148:151], v[210:213], v[46:49]
	v_mfma_i32_16x16x64_i8 v[38:41], v[178:181], v[210:213], v[38:41]
	v_mfma_i32_16x16x64_i8 v[30:33], v[148:151], v[222:225], v[30:33]
	v_mfma_i32_16x16x64_i8 v[22:25], v[178:181], v[222:225], v[22:25]
	v_mfma_i32_16x16x64_i8 v[14:17], v[148:151], v[230:233], v[14:17]
	v_mfma_i32_16x16x64_i8 v[6:9], v[178:181], v[230:233], v[6:9]
	v_mfma_i32_16x16x64_i8 v[58:61], v[182:185], v[198:201], v[58:61]
	v_mfma_i32_16x16x64_i8 v[50:53], v[190:193], v[198:201], v[50:53]
	v_mfma_i32_16x16x64_i8 v[42:45], v[182:185], v[206:209], v[42:45]
	v_mfma_i32_16x16x64_i8 v[34:37], v[190:193], v[206:209], v[34:37]
	v_mfma_i32_16x16x64_i8 v[26:29], v[182:185], v[214:217], v[26:29]
	v_mfma_i32_16x16x64_i8 v[18:21], v[190:193], v[214:217], v[18:21]
	v_mfma_i32_16x16x64_i8 v[10:13], v[182:185], v[226:229], v[10:13]
	v_mfma_i32_16x16x64_i8 v[2:5], v[190:193], v[226:229], v[2:5]
	v_mfma_i32_16x16x64_i8 v[58:61], v[186:189], v[202:205], v[58:61]
	v_mfma_i32_16x16x64_i8 v[50:53], v[194:197], v[202:205], v[50:53]
	v_mfma_i32_16x16x64_i8 v[42:45], v[186:189], v[210:213], v[42:45]
	v_mfma_i32_16x16x64_i8 v[34:37], v[194:197], v[210:213], v[34:37]
	v_mfma_i32_16x16x64_i8 v[26:29], v[186:189], v[222:225], v[26:29]
	v_mfma_i32_16x16x64_i8 v[18:21], v[194:197], v[222:225], v[18:21]
	v_mfma_i32_16x16x64_i8 v[10:13], v[186:189], v[230:233], v[10:13]
	v_mfma_i32_16x16x64_i8 v[2:5], v[194:197], v[230:233], v[2:5]
	s_barrier
	s_add_i32 s21, s21, 2
	s_add_u32 s13, s13, 0x100
	s_addc_u32 s15, s15, 0
	s_add_u32 s24, s24, 0x100
	s_addc_u32 s25, s25, 0
	s_cmp_gt_u32 s21, 13
	s_cbranch_scc0 .LBB0_1332
	s_and_b64 vcc, exec, s[10:11]
	s_cbranch_vccz .LBB0_1335
	s_barrier

.LBB0_1446:
	s_add_u32 s8, s26, 0x4000
	s_addc_u32 s9, s27, 0
	s_cmpk_eq_i32 s84, 0x54
	s_cselect_b32 s60, s22, s8
	s_cselect_b32 s61, s23, s9
	s_cselect_b32 s58, s24, s82
	s_cselect_b32 s59, s25, s83
	s_add_u32 s56, s60, 0x8000
	s_addc_u32 s57, s61, 0
	s_add_i32 s8, 0, 0x10000
	s_add_i32 s36, 0, 0x14000
	v_add_u32_e32 v142, s8, v201
	v_add_u32_e32 v168, s36, v201
	ds_read_b128 v[110:113], v142
	ds_read_b128 v[118:121], v142 offset:1024
	ds_read_b128 v[138:141], v142 offset:2048
	ds_read_b128 v[142:145], v142 offset:3072
	ds_read_b128 v[146:149], v168
	ds_read_b128 v[150:153], v168 offset:1024
	ds_read_b128 v[174:177], v168 offset:2048
	ds_read_b128 v[178:181], v168 offset:3072
	v_lshl_add_u64 v[168:169], s[26:27], 0, v[172:173]
	s_add_i32 m0, s65, 0xc000
	ds_read_b128 v[182:185], v203
	ds_read_b128 v[186:189], v203 offset:1024
	ds_read_b128 v[190:193], v203 offset:2048
	ds_read_b128 v[194:197], v203 offset:3072
	ds_read_b128 v[204:207], v203 offset:4096
	ds_read_b128 v[208:211], v203 offset:5120
	ds_read_b128 v[212:215], v203 offset:6144
	ds_read_b128 v[222:225], v203 offset:7168
	global_load_lds_dwordx4 v[168:169], off
	v_lshl_add_u64 v[168:169], s[26:27], 0, v[160:161]
	s_add_i32 m0, s65, 0xe000
	s_nop 0
	global_load_lds_dwordx4 v[168:169], off
	s_waitcnt vmcnt(8)
	s_waitcnt lgkmcnt(0)
	s_barrier
	v_mfma_f32_16x16x32_bf16 v[134:137], v[110:113], v[182:185], v[134:137]
	v_mfma_f32_16x16x32_bf16 v[130:133], v[138:141], v[182:185], v[130:133]
	v_mfma_f32_16x16x32_bf16 v[114:117], v[110:113], v[190:193], v[114:117]
	v_mfma_f32_16x16x32_bf16 v[106:109], v[138:141], v[190:193], v[106:109]
	v_mfma_f32_16x16x32_bf16 v[94:97], v[110:113], v[204:207], v[94:97]
	v_mfma_f32_16x16x32_bf16 v[90:93], v[138:141], v[204:207], v[90:93]
	v_mfma_f32_16x16x32_bf16 v[78:81], v[110:113], v[212:215], v[78:81]
	v_mfma_f32_16x16x32_bf16 v[74:77], v[138:141], v[212:215], v[74:77]
	v_mfma_f32_16x16x32_bf16 v[134:137], v[118:121], v[186:189], v[134:137]
	v_mfma_f32_16x16x32_bf16 v[130:133], v[142:145], v[186:189], v[130:133]
	v_mfma_f32_16x16x32_bf16 v[114:117], v[118:121], v[194:197], v[114:117]
	v_mfma_f32_16x16x32_bf16 v[106:109], v[142:145], v[194:197], v[106:109]
	v_mfma_f32_16x16x32_bf16 v[94:97], v[118:121], v[208:211], v[94:97]
	v_mfma_f32_16x16x32_bf16 v[90:93], v[142:145], v[208:211], v[90:93]
	v_mfma_f32_16x16x32_bf16 v[78:81], v[118:121], v[222:225], v[78:81]
	v_mfma_f32_16x16x32_bf16 v[74:77], v[142:145], v[222:225], v[74:77]
	v_mfma_f32_16x16x32_bf16 v[126:129], v[146:149], v[182:185], v[126:129]
	v_mfma_f32_16x16x32_bf16 v[122:125], v[174:177], v[182:185], v[122:125]
	v_mfma_f32_16x16x32_bf16 v[102:105], v[146:149], v[190:193], v[102:105]
	v_mfma_f32_16x16x32_bf16 v[98:101], v[174:177], v[190:193], v[98:101]
	v_mfma_f32_16x16x32_bf16 v[86:89], v[146:149], v[204:207], v[86:89]
	v_mfma_f32_16x16x32_bf16 v[82:85], v[174:177], v[204:207], v[82:85]
	v_mfma_f32_16x16x32_bf16 v[70:73], v[146:149], v[212:215], v[70:73]
	v_mfma_f32_16x16x32_bf16 v[66:69], v[174:177], v[212:215], v[66:69]
	v_mfma_f32_16x16x32_bf16 v[126:129], v[150:153], v[186:189], v[126:129]
	v_mfma_f32_16x16x32_bf16 v[122:125], v[178:181], v[186:189], v[122:125]
	v_mfma_f32_16x16x32_bf16 v[102:105], v[150:153], v[194:197], v[102:105]
	v_mfma_f32_16x16x32_bf16 v[98:101], v[178:181], v[194:197], v[98:101]
	v_mfma_f32_16x16x32_bf16 v[86:89], v[150:153], v[208:211], v[86:89]
	v_mfma_f32_16x16x32_bf16 v[82:85], v[178:181], v[208:211], v[82:85]
	v_mfma_f32_16x16x32_bf16 v[70:73], v[150:153], v[222:225], v[70:73]
	v_mfma_f32_16x16x32_bf16 v[66:69], v[178:181], v[222:225], v[66:69]
	s_barrier
	s_add_i32 s8, s8, s64
	v_lshl_add_u64 v[168:169], s[58:59], 0, v[162:163]
	s_mov_b32 m0, s8
	ds_read_b128 v[182:185], v203 offset:16384
	ds_read_b128 v[186:189], v203 offset:17408
	ds_read_b128 v[190:193], v203 offset:18432
	ds_read_b128 v[194:197], v203 offset:19456
	ds_read_b128 v[204:207], v203 offset:20480
	ds_read_b128 v[208:211], v203 offset:21504
	ds_read_b128 v[212:215], v203 offset:22528
	ds_read_b128 v[222:225], v203 offset:23552
	global_load_lds_dwordx4 v[168:169], off
	s_add_i32 m0, s8, 0x2000
	s_add_u32 s8, s58, 0x160000
	v_lshl_add_u64 v[170:171], s[58:59], 0, v[158:159]
	s_addc_u32 s9, s59, 0
	s_add_i32 s36, s36, s64
	global_load_lds_dwordx4 v[170:171], off
	v_lshl_add_u64 v[198:199], s[8:9], 0, v[162:163]
	s_mov_b32 m0, s36
	s_nop 0
	global_load_lds_dwordx4 v[198:199], off
	v_lshl_add_u64 v[198:199], s[8:9], 0, v[158:159]
	s_add_i32 m0, s36, 0x2000
	s_nop 0
	global_load_lds_dwordx4 v[198:199], off
	v_lshl_add_u64 v[198:199], s[60:61], 0, v[154:155]
	s_mov_b32 m0, s65
	s_nop 0
	global_load_lds_dwordx4 v[198:199], off
	v_lshl_add_u64 v[198:199], s[60:61], 0, v[156:157]
	s_mov_b32 m0, s66
	s_nop 0
	global_load_lds_dwordx4 v[198:199], off
	s_waitcnt vmcnt(8)
	s_waitcnt lgkmcnt(0)
	s_barrier
	v_mfma_f32_16x16x32_bf16 v[62:65], v[110:113], v[182:185], v[62:65]
	v_mfma_f32_16x16x32_bf16 v[58:61], v[138:141], v[182:185], v[58:61]
	v_mfma_f32_16x16x32_bf16 v[46:49], v[110:113], v[190:193], v[46:49]
	v_mfma_f32_16x16x32_bf16 v[42:45], v[138:141], v[190:193], v[42:45]
	v_mfma_f32_16x16x32_bf16 v[30:33], v[110:113], v[204:207], v[30:33]
	v_mfma_f32_16x16x32_bf16 v[26:29], v[138:141], v[204:207], v[26:29]
	v_mfma_f32_16x16x32_bf16 v[14:17], v[110:113], v[212:215], v[14:17]
	v_mfma_f32_16x16x32_bf16 v[10:13], v[138:141], v[212:215], v[10:13]
	v_mfma_f32_16x16x32_bf16 v[62:65], v[118:121], v[186:189], v[62:65]
	v_mfma_f32_16x16x32_bf16 v[58:61], v[142:145], v[186:189], v[58:61]
	v_mfma_f32_16x16x32_bf16 v[46:49], v[118:121], v[194:197], v[46:49]
	v_mfma_f32_16x16x32_bf16 v[42:45], v[142:145], v[194:197], v[42:45]
	v_mfma_f32_16x16x32_bf16 v[30:33], v[118:121], v[208:211], v[30:33]
	v_mfma_f32_16x16x32_bf16 v[26:29], v[142:145], v[208:211], v[26:29]
	v_mfma_f32_16x16x32_bf16 v[14:17], v[118:121], v[222:225], v[14:17]
	v_mfma_f32_16x16x32_bf16 v[10:13], v[142:145], v[222:225], v[10:13]
	v_mfma_f32_16x16x32_bf16 v[54:57], v[146:149], v[182:185], v[54:57]
	v_mfma_f32_16x16x32_bf16 v[50:53], v[174:177], v[182:185], v[50:53]
	v_mfma_f32_16x16x32_bf16 v[38:41], v[146:149], v[190:193], v[38:41]
	v_mfma_f32_16x16x32_bf16 v[34:37], v[174:177], v[190:193], v[34:37]
	v_mfma_f32_16x16x32_bf16 v[22:25], v[146:149], v[204:207], v[22:25]
	v_mfma_f32_16x16x32_bf16 v[18:21], v[174:177], v[204:207], v[18:21]
	v_mfma_f32_16x16x32_bf16 v[6:9], v[146:149], v[212:215], v[6:9]
	v_mfma_f32_16x16x32_bf16 v[2:5], v[174:177], v[212:215], v[2:5]
	v_mfma_f32_16x16x32_bf16 v[54:57], v[150:153], v[186:189], v[54:57]
	v_mfma_f32_16x16x32_bf16 v[50:53], v[178:181], v[186:189], v[50:53]
	v_mfma_f32_16x16x32_bf16 v[38:41], v[150:153], v[194:197], v[38:41]
	v_mfma_f32_16x16x32_bf16 v[34:37], v[178:181], v[194:197], v[34:37]
	v_mfma_f32_16x16x32_bf16 v[22:25], v[150:153], v[208:211], v[22:25]
	v_mfma_f32_16x16x32_bf16 v[18:21], v[178:181], v[208:211], v[18:21]
	v_mfma_f32_16x16x32_bf16 v[6:9], v[150:153], v[222:225], v[6:9]
	v_mfma_f32_16x16x32_bf16 v[2:5], v[178:181], v[222:225], v[2:5]
	s_barrier
	s_add_i32 s36, 0, 0x18000
	s_add_i32 s37, 0, 0x1c000
	v_add_u32_e32 v142, s36, v201
	v_add_u32_e32 v178, s37, v201
	ds_read_b128 v[110:113], v142
	ds_read_b128 v[118:121], v142 offset:1024
	ds_read_b128 v[138:141], v142 offset:2048
	ds_read_b128 v[142:145], v142 offset:3072
	ds_read_b128 v[146:149], v178
	ds_read_b128 v[150:153], v178 offset:1024
	ds_read_b128 v[174:177], v178 offset:2048
	ds_read_b128 v[178:181], v178 offset:3072
	s_add_u32 s8, s60, 0x4000
	s_addc_u32 s9, s61, 0
	s_mov_b32 m0, s67
	v_lshl_add_u64 v[198:199], s[8:9], 0, v[154:155]
	ds_read_b128 v[182:185], v203 offset:32768
	ds_read_b128 v[186:189], v203 offset:33792
	ds_read_b128 v[190:193], v203 offset:34816
	ds_read_b128 v[194:197], v203 offset:35840
	ds_read_b128 v[204:207], v203 offset:36864
	ds_read_b128 v[208:211], v203 offset:37888
	ds_read_b128 v[212:215], v203 offset:38912
	ds_read_b128 v[222:225], v203 offset:39936
	global_load_lds_dwordx4 v[198:199], off
	v_lshl_add_u64 v[198:199], s[8:9], 0, v[156:157]
	s_mov_b32 m0, s68
	s_nop 0
	global_load_lds_dwordx4 v[198:199], off
	s_waitcnt vmcnt(8)
	s_waitcnt lgkmcnt(0)
	s_barrier
	v_mfma_f32_16x16x32_bf16 v[134:137], v[110:113], v[182:185], v[134:137]
	v_mfma_f32_16x16x32_bf16 v[130:133], v[138:141], v[182:185], v[130:133]
	v_mfma_f32_16x16x32_bf16 v[114:117], v[110:113], v[190:193], v[114:117]
	v_mfma_f32_16x16x32_bf16 v[106:109], v[138:141], v[190:193], v[106:109]
	v_mfma_f32_16x16x32_bf16 v[94:97], v[110:113], v[204:207], v[94:97]
	v_mfma_f32_16x16x32_bf16 v[90:93], v[138:141], v[204:207], v[90:93]
	v_mfma_f32_16x16x32_bf16 v[78:81], v[110:113], v[212:215], v[78:81]
	v_mfma_f32_16x16x32_bf16 v[74:77], v[138:141], v[212:215], v[74:77]
	v_mfma_f32_16x16x32_bf16 v[134:137], v[118:121], v[186:189], v[134:137]
	v_mfma_f32_16x16x32_bf16 v[130:133], v[142:145], v[186:189], v[130:133]
	v_mfma_f32_16x16x32_bf16 v[114:117], v[118:121], v[194:197], v[114:117]
	v_mfma_f32_16x16x32_bf16 v[106:109], v[142:145], v[194:197], v[106:109]
	v_mfma_f32_16x16x32_bf16 v[94:97], v[118:121], v[208:211], v[94:97]
	v_mfma_f32_16x16x32_bf16 v[90:93], v[142:145], v[208:211], v[90:93]
	v_mfma_f32_16x16x32_bf16 v[78:81], v[118:121], v[222:225], v[78:81]
	v_mfma_f32_16x16x32_bf16 v[74:77], v[142:145], v[222:225], v[74:77]
	v_mfma_f32_16x16x32_bf16 v[126:129], v[146:149], v[182:185], v[126:129]
	v_mfma_f32_16x16x32_bf16 v[122:125], v[174:177], v[182:185], v[122:125]
	v_mfma_f32_16x16x32_bf16 v[102:105], v[146:149], v[190:193], v[102:105]
	v_mfma_f32_16x16x32_bf16 v[98:101], v[174:177], v[190:193], v[98:101]
	v_mfma_f32_16x16x32_bf16 v[86:89], v[146:149], v[204:207], v[86:89]
	v_mfma_f32_16x16x32_bf16 v[82:85], v[174:177], v[204:207], v[82:85]
	v_mfma_f32_16x16x32_bf16 v[70:73], v[146:149], v[212:215], v[70:73]
	v_mfma_f32_16x16x32_bf16 v[66:69], v[174:177], v[212:215], v[66:69]
	v_mfma_f32_16x16x32_bf16 v[126:129], v[150:153], v[186:189], v[126:129]
	v_mfma_f32_16x16x32_bf16 v[122:125], v[178:181], v[186:189], v[122:125]
	v_mfma_f32_16x16x32_bf16 v[102:105], v[150:153], v[194:197], v[102:105]
	v_mfma_f32_16x16x32_bf16 v[98:101], v[178:181], v[194:197], v[98:101]
	v_mfma_f32_16x16x32_bf16 v[86:89], v[150:153], v[208:211], v[86:89]
	v_mfma_f32_16x16x32_bf16 v[82:85], v[178:181], v[208:211], v[82:85]
	v_mfma_f32_16x16x32_bf16 v[70:73], v[150:153], v[222:225], v[70:73]
	v_mfma_f32_16x16x32_bf16 v[66:69], v[178:181], v[222:225], v[66:69]
	s_barrier
	s_add_i32 s8, s36, s64
	v_lshl_add_u64 v[168:169], v[168:169], 0, s[44:45]
	s_mov_b32 m0, s8
	ds_read_b128 v[182:185], v203 offset:49152
	ds_read_b128 v[186:189], v203 offset:50176
	ds_read_b128 v[190:193], v203 offset:51200
	ds_read_b128 v[194:197], v203 offset:52224
	ds_read_b128 v[204:207], v203 offset:53248
	ds_read_b128 v[208:211], v203 offset:54272
	ds_read_b128 v[212:215], v203 offset:55296
	ds_read_b128 v[222:225], v203 offset:56320
	global_load_lds_dwordx4 v[168:169], off
	s_add_i32 m0, s8, 0x2000
	s_add_u32 s8, s58, 0x160080
	v_lshl_add_u64 v[168:169], v[170:171], 0, s[44:45]
	s_addc_u32 s9, s59, 0
	s_add_i32 s36, s37, s64
	global_load_lds_dwordx4 v[168:169], off
	v_lshl_add_u64 v[168:169], s[8:9], 0, v[162:163]
	s_mov_b32 m0, s36
	s_nop 0
	global_load_lds_dwordx4 v[168:169], off
	v_lshl_add_u64 v[168:169], s[8:9], 0, v[158:159]
	s_add_i32 m0, s36, 0x2000
	s_nop 0
	global_load_lds_dwordx4 v[168:169], off
	v_lshl_add_u64 v[168:169], s[56:57], 0, v[154:155]
	s_mov_b32 m0, s69
	s_nop 0
	global_load_lds_dwordx4 v[168:169], off
	v_lshl_add_u64 v[168:169], s[56:57], 0, v[156:157]
	s_mov_b32 m0, s70
	s_nop 0
	global_load_lds_dwordx4 v[168:169], off
	s_waitcnt vmcnt(8)
	s_waitcnt lgkmcnt(0)
	s_barrier
	v_mfma_f32_16x16x32_bf16 v[62:65], v[110:113], v[182:185], v[62:65]
	v_mfma_f32_16x16x32_bf16 v[58:61], v[138:141], v[182:185], v[58:61]
	v_mfma_f32_16x16x32_bf16 v[46:49], v[110:113], v[190:193], v[46:49]
	v_mfma_f32_16x16x32_bf16 v[42:45], v[138:141], v[190:193], v[42:45]
	v_mfma_f32_16x16x32_bf16 v[30:33], v[110:113], v[204:207], v[30:33]
	v_mfma_f32_16x16x32_bf16 v[26:29], v[138:141], v[204:207], v[26:29]
	v_mfma_f32_16x16x32_bf16 v[14:17], v[110:113], v[212:215], v[14:17]
	v_mfma_f32_16x16x32_bf16 v[10:13], v[138:141], v[212:215], v[10:13]
	v_mfma_f32_16x16x32_bf16 v[62:65], v[118:121], v[186:189], v[62:65]
	v_mfma_f32_16x16x32_bf16 v[58:61], v[142:145], v[186:189], v[58:61]
	v_mfma_f32_16x16x32_bf16 v[46:49], v[118:121], v[194:197], v[46:49]
	v_mfma_f32_16x16x32_bf16 v[42:45], v[142:145], v[194:197], v[42:45]
	v_mfma_f32_16x16x32_bf16 v[30:33], v[118:121], v[208:211], v[30:33]
	v_mfma_f32_16x16x32_bf16 v[26:29], v[142:145], v[208:211], v[26:29]
	v_mfma_f32_16x16x32_bf16 v[14:17], v[118:121], v[222:225], v[14:17]
	v_mfma_f32_16x16x32_bf16 v[10:13], v[142:145], v[222:225], v[10:13]
	v_mfma_f32_16x16x32_bf16 v[54:57], v[146:149], v[182:185], v[54:57]
	v_mfma_f32_16x16x32_bf16 v[50:53], v[174:177], v[182:185], v[50:53]
	v_mfma_f32_16x16x32_bf16 v[38:41], v[146:149], v[190:193], v[38:41]
	v_mfma_f32_16x16x32_bf16 v[34:37], v[174:177], v[190:193], v[34:37]
	v_mfma_f32_16x16x32_bf16 v[22:25], v[146:149], v[204:207], v[22:25]
	v_mfma_f32_16x16x32_bf16 v[18:21], v[174:177], v[204:207], v[18:21]
	v_mfma_f32_16x16x32_bf16 v[6:9], v[146:149], v[212:215], v[6:9]
	v_mfma_f32_16x16x32_bf16 v[2:5], v[174:177], v[212:215], v[2:5]
	v_mfma_f32_16x16x32_bf16 v[54:57], v[150:153], v[186:189], v[54:57]
	v_mfma_f32_16x16x32_bf16 v[50:53], v[178:181], v[186:189], v[50:53]
	v_mfma_f32_16x16x32_bf16 v[38:41], v[150:153], v[194:197], v[38:41]
	v_mfma_f32_16x16x32_bf16 v[34:37], v[178:181], v[194:197], v[34:37]
	v_mfma_f32_16x16x32_bf16 v[22:25], v[150:153], v[208:211], v[22:25]
	v_mfma_f32_16x16x32_bf16 v[18:21], v[178:181], v[208:211], v[18:21]
	v_mfma_f32_16x16x32_bf16 v[6:9], v[150:153], v[222:225], v[6:9]
	v_mfma_f32_16x16x32_bf16 v[2:5], v[178:181], v[222:225], v[2:5]
	s_barrier
	s_add_i32 s84, s84, 2
	s_add_u32 s26, s26, 0x10000
	s_addc_u32 s27, s27, 0
	s_add_u32 s82, s82, 0x100
	s_addc_u32 s83, s83, 0
	s_cmpk_gt_u32 s84, 0x55
	s_cbranch_scc0 .LBB0_1446
	s_and_b64 vcc, exec, s[20:21]
	s_cbranch_vccz .LBB0_1449
	s_barrier

.LBB0_1574:
	s_add_u32 s36, s20, s60
	s_addc_u32 s37, s21, 0
	s_add_u32 s38, s36, 0x100
	s_addc_u32 s39, s37, 0
	s_and_b64 s[8:9], s[58:59], exec
	s_cselect_b32 s63, s25, s39
	s_cselect_b32 s62, s24, s38
	s_add_u32 s8, s22, s60
	s_addc_u32 s9, s23, 0
	s_add_u32 s38, s8, 0x100
	s_addc_u32 s39, s9, 0
	s_add_i32 s31, 0, 0x10000
	s_and_b64 s[8:9], s[58:59], exec
	s_cselect_b32 s65, s27, s39
	s_cselect_b32 s64, s26, s38
	s_add_i32 s38, 0, 0x14000
	s_add_u32 vcc_lo, s36, 0x80080
	s_addc_u32 vcc_hi, s37, 0
	s_add_i32 s8, s31, s72
	s_add_i32 m0, s17, 0xc000
	s_add_i32 s39, s17, 0xe000
	s_add_i32 s36, s8, 0x2000
	v_add_u32_e32 v136, s31, v139
	s_add_u32 s66, s64, 0x90000
	ds_read_b128 v[142:145], v136
	ds_read_b128 v[146:149], v136 offset:1024
	ds_read_b128 v[150:153], v136 offset:2048
	ds_read_b128 v[154:157], v136 offset:3072
	v_add_u32_e32 v136, s38, v139
	s_addc_u32 s67, s65, 0
	s_add_i32 s9, s38, s72
	ds_read_b128 v[158:161], v136
	ds_read_b128 v[172:175], v136 offset:1024
	ds_read_b128 v[176:179], v136 offset:2048
	ds_read_b128 v[180:183], v136 offset:3072
	s_add_i32 s43, s9, 0x2000
	s_add_i32 s89, 0, 0x18000
	s_add_i32 s88, 0, 0x1c000
	s_add_u32 s60, s62, 0x80000
	s_addc_u32 s61, s63, 0
	s_add_i32 s87, s89, s72
	s_add_i32 s86, s87, 0x2000
	s_add_u32 s58, s64, 0x90080
	s_addc_u32 s59, s65, 0
	s_add_i32 s38, s88, s72
	s_add_i32 s37, s38, 0x2000
	v_lshl_add_u64 v[136:137], vcc, 0, v[130:131]
	ds_read_b128 v[184:187], v141
	ds_read_b128 v[188:191], v141 offset:1024
	ds_read_b128 v[192:195], v141 offset:2048
	ds_read_b128 v[196:199], v141 offset:3072
	ds_read_b128 v[200:203], v141 offset:4096
	ds_read_b128 v[204:207], v141 offset:5120
	ds_read_b128 v[208:211], v141 offset:6144
	ds_read_b128 v[212:215], v141 offset:7168
	global_load_lds_dwordx4 v[136:137], off
	v_lshl_add_u64 v[136:137], vcc, 0, v[132:133]
	s_mov_b32 m0, s39
	s_nop 0
	global_load_lds_dwordx4 v[136:137], off
	s_waitcnt vmcnt(8)
	s_waitcnt lgkmcnt(0)
	s_barrier
	v_mfma_f32_16x16x32_bf16 v[126:129], v[142:145], v[184:187], v[126:129]
	v_mfma_f32_16x16x32_bf16 v[122:125], v[150:153], v[184:187], v[122:125]
	v_mfma_f32_16x16x32_bf16 v[118:121], v[142:145], v[192:195], v[118:121]
	v_mfma_f32_16x16x32_bf16 v[110:113], v[150:153], v[192:195], v[110:113]
	v_mfma_f32_16x16x32_bf16 v[102:105], v[142:145], v[200:203], v[102:105]
	v_mfma_f32_16x16x32_bf16 v[94:97], v[150:153], v[200:203], v[94:97]
	v_mfma_f32_16x16x32_bf16 v[86:89], v[142:145], v[208:211], v[86:89]
	v_mfma_f32_16x16x32_bf16 v[78:81], v[150:153], v[208:211], v[78:81]
	v_mfma_f32_16x16x32_bf16 v[126:129], v[146:149], v[188:191], v[126:129]
	v_mfma_f32_16x16x32_bf16 v[122:125], v[154:157], v[188:191], v[122:125]
	v_mfma_f32_16x16x32_bf16 v[118:121], v[146:149], v[196:199], v[118:121]
	v_mfma_f32_16x16x32_bf16 v[110:113], v[154:157], v[196:199], v[110:113]
	v_mfma_f32_16x16x32_bf16 v[102:105], v[146:149], v[204:207], v[102:105]
	v_mfma_f32_16x16x32_bf16 v[94:97], v[154:157], v[204:207], v[94:97]
	v_mfma_f32_16x16x32_bf16 v[86:89], v[146:149], v[212:215], v[86:89]
	v_mfma_f32_16x16x32_bf16 v[78:81], v[154:157], v[212:215], v[78:81]
	v_mfma_f32_16x16x32_bf16 v[114:117], v[158:161], v[184:187], v[114:117]
	v_mfma_f32_16x16x32_bf16 v[106:109], v[176:179], v[184:187], v[106:109]
	v_mfma_f32_16x16x32_bf16 v[98:101], v[158:161], v[192:195], v[98:101]
	v_mfma_f32_16x16x32_bf16 v[90:93], v[176:179], v[192:195], v[90:93]
	v_mfma_f32_16x16x32_bf16 v[82:85], v[158:161], v[200:203], v[82:85]
	v_mfma_f32_16x16x32_bf16 v[74:77], v[176:179], v[200:203], v[74:77]
	v_mfma_f32_16x16x32_bf16 v[70:73], v[158:161], v[208:211], v[70:73]
	v_mfma_f32_16x16x32_bf16 v[66:69], v[176:179], v[208:211], v[66:69]
	v_mfma_f32_16x16x32_bf16 v[114:117], v[172:175], v[188:191], v[114:117]
	v_mfma_f32_16x16x32_bf16 v[106:109], v[180:183], v[188:191], v[106:109]
	v_mfma_f32_16x16x32_bf16 v[98:101], v[172:175], v[196:199], v[98:101]
	v_mfma_f32_16x16x32_bf16 v[90:93], v[180:183], v[196:199], v[90:93]
	v_mfma_f32_16x16x32_bf16 v[82:85], v[172:175], v[204:207], v[82:85]
	v_mfma_f32_16x16x32_bf16 v[74:77], v[180:183], v[204:207], v[74:77]
	v_mfma_f32_16x16x32_bf16 v[70:73], v[172:175], v[212:215], v[70:73]
	v_mfma_f32_16x16x32_bf16 v[66:69], v[180:183], v[212:215], v[66:69]
	s_barrier
	s_mov_b32 m0, s8
	v_lshl_add_u64 v[136:137], s[64:65], 0, v[162:163]
	ds_read_b128 v[184:187], v141 offset:16384
	ds_read_b128 v[188:191], v141 offset:17408
	ds_read_b128 v[192:195], v141 offset:18432
	ds_read_b128 v[196:199], v141 offset:19456
	ds_read_b128 v[200:203], v141 offset:20480
	ds_read_b128 v[204:207], v141 offset:21504
	ds_read_b128 v[208:211], v141 offset:22528
	ds_read_b128 v[212:215], v141 offset:23552
	global_load_lds_dwordx4 v[136:137], off
	v_lshl_add_u64 v[168:169], s[64:65], 0, v[134:135]
	s_mov_b32 m0, s36
	v_lshl_add_u64 v[170:171], s[66:67], 0, v[162:163]
	global_load_lds_dwordx4 v[168:169], off
	s_mov_b32 m0, s9
	v_lshl_add_u64 v[216:217], s[62:63], 0, v[132:133]
	global_load_lds_dwordx4 v[170:171], off
	v_lshl_add_u64 v[170:171], s[66:67], 0, v[134:135]
	s_mov_b32 m0, s43
	s_nop 0
	global_load_lds_dwordx4 v[170:171], off
	v_lshl_add_u64 v[170:171], s[62:63], 0, v[130:131]
	s_mov_b32 m0, s17
	s_nop 0
	global_load_lds_dwordx4 v[170:171], off
	s_mov_b32 m0, s73
	s_nop 0
	global_load_lds_dwordx4 v[216:217], off
	s_waitcnt vmcnt(8)
	s_waitcnt lgkmcnt(0)
	s_barrier
	v_mfma_f32_16x16x32_bf16 v[62:65], v[142:145], v[184:187], v[62:65]
	v_mfma_f32_16x16x32_bf16 v[58:61], v[150:153], v[184:187], v[58:61]
	v_mfma_f32_16x16x32_bf16 v[54:57], v[142:145], v[192:195], v[54:57]
	v_mfma_f32_16x16x32_bf16 v[46:49], v[150:153], v[192:195], v[46:49]
	v_mfma_f32_16x16x32_bf16 v[38:41], v[142:145], v[200:203], v[38:41]
	v_mfma_f32_16x16x32_bf16 v[30:33], v[150:153], v[200:203], v[30:33]
	v_mfma_f32_16x16x32_bf16 v[22:25], v[142:145], v[208:211], v[22:25]
	v_mfma_f32_16x16x32_bf16 v[14:17], v[150:153], v[208:211], v[14:17]
	v_mfma_f32_16x16x32_bf16 v[62:65], v[146:149], v[188:191], v[62:65]
	v_mfma_f32_16x16x32_bf16 v[58:61], v[154:157], v[188:191], v[58:61]
	v_mfma_f32_16x16x32_bf16 v[54:57], v[146:149], v[196:199], v[54:57]
	v_mfma_f32_16x16x32_bf16 v[46:49], v[154:157], v[196:199], v[46:49]
	v_mfma_f32_16x16x32_bf16 v[38:41], v[146:149], v[204:207], v[38:41]
	v_mfma_f32_16x16x32_bf16 v[30:33], v[154:157], v[204:207], v[30:33]
	v_mfma_f32_16x16x32_bf16 v[22:25], v[146:149], v[212:215], v[22:25]
	v_mfma_f32_16x16x32_bf16 v[14:17], v[154:157], v[212:215], v[14:17]
	v_mfma_f32_16x16x32_bf16 v[50:53], v[158:161], v[184:187], v[50:53]
	v_mfma_f32_16x16x32_bf16 v[42:45], v[176:179], v[184:187], v[42:45]
	v_mfma_f32_16x16x32_bf16 v[34:37], v[158:161], v[192:195], v[34:37]
	v_mfma_f32_16x16x32_bf16 v[26:29], v[176:179], v[192:195], v[26:29]
	v_mfma_f32_16x16x32_bf16 v[18:21], v[158:161], v[200:203], v[18:21]
	v_mfma_f32_16x16x32_bf16 v[10:13], v[176:179], v[200:203], v[10:13]
	v_mfma_f32_16x16x32_bf16 v[6:9], v[158:161], v[208:211], v[6:9]
	v_mfma_f32_16x16x32_bf16 v[2:5], v[176:179], v[208:211], v[2:5]
	v_mfma_f32_16x16x32_bf16 v[50:53], v[172:175], v[188:191], v[50:53]
	v_mfma_f32_16x16x32_bf16 v[42:45], v[180:183], v[188:191], v[42:45]
	v_mfma_f32_16x16x32_bf16 v[34:37], v[172:175], v[196:199], v[34:37]
	v_mfma_f32_16x16x32_bf16 v[26:29], v[180:183], v[196:199], v[26:29]
	v_mfma_f32_16x16x32_bf16 v[18:21], v[172:175], v[204:207], v[18:21]
	v_mfma_f32_16x16x32_bf16 v[10:13], v[180:183], v[204:207], v[10:13]
	v_mfma_f32_16x16x32_bf16 v[6:9], v[172:175], v[212:215], v[6:9]
	v_mfma_f32_16x16x32_bf16 v[2:5], v[180:183], v[212:215], v[2:5]
	s_barrier
	v_add_u32_e32 v154, s89, v139
	v_add_u32_e32 v180, s88, v139
	ds_read_b128 v[142:145], v154
	ds_read_b128 v[146:149], v154 offset:1024
	ds_read_b128 v[150:153], v154 offset:2048
	ds_read_b128 v[154:157], v154 offset:3072
	ds_read_b128 v[158:161], v180
	ds_read_b128 v[172:175], v180 offset:1024
	ds_read_b128 v[176:179], v180 offset:2048
	ds_read_b128 v[180:183], v180 offset:3072
	s_mov_b32 m0, s74
	v_lshl_add_u64 v[222:223], s[60:61], 0, v[130:131]
	ds_read_b128 v[184:187], v141 offset:32768
	ds_read_b128 v[188:191], v141 offset:33792
	ds_read_b128 v[192:195], v141 offset:34816
	ds_read_b128 v[196:199], v141 offset:35840
	ds_read_b128 v[200:203], v141 offset:36864
	ds_read_b128 v[204:207], v141 offset:37888
	ds_read_b128 v[208:211], v141 offset:38912
	ds_read_b128 v[212:215], v141 offset:39936
	global_load_lds_dwordx4 v[222:223], off
	v_lshl_add_u64 v[222:223], s[60:61], 0, v[132:133]
	s_mov_b32 m0, s75
	s_nop 0
	global_load_lds_dwordx4 v[222:223], off
	s_waitcnt vmcnt(8)
	s_waitcnt lgkmcnt(0)
	s_barrier
	v_mfma_f32_16x16x32_bf16 v[126:129], v[142:145], v[184:187], v[126:129]
	v_mfma_f32_16x16x32_bf16 v[122:125], v[150:153], v[184:187], v[122:125]
	v_mfma_f32_16x16x32_bf16 v[118:121], v[142:145], v[192:195], v[118:121]
	v_mfma_f32_16x16x32_bf16 v[110:113], v[150:153], v[192:195], v[110:113]
	v_mfma_f32_16x16x32_bf16 v[102:105], v[142:145], v[200:203], v[102:105]
	v_mfma_f32_16x16x32_bf16 v[94:97], v[150:153], v[200:203], v[94:97]
	v_mfma_f32_16x16x32_bf16 v[86:89], v[142:145], v[208:211], v[86:89]
	v_mfma_f32_16x16x32_bf16 v[78:81], v[150:153], v[208:211], v[78:81]
	v_mfma_f32_16x16x32_bf16 v[126:129], v[146:149], v[188:191], v[126:129]
	v_mfma_f32_16x16x32_bf16 v[122:125], v[154:157], v[188:191], v[122:125]
	v_mfma_f32_16x16x32_bf16 v[118:121], v[146:149], v[196:199], v[118:121]
	v_mfma_f32_16x16x32_bf16 v[110:113], v[154:157], v[196:199], v[110:113]
	v_mfma_f32_16x16x32_bf16 v[102:105], v[146:149], v[204:207], v[102:105]
	v_mfma_f32_16x16x32_bf16 v[94:97], v[154:157], v[204:207], v[94:97]
	v_mfma_f32_16x16x32_bf16 v[86:89], v[146:149], v[212:215], v[86:89]
	v_mfma_f32_16x16x32_bf16 v[78:81], v[154:157], v[212:215], v[78:81]
	v_mfma_f32_16x16x32_bf16 v[114:117], v[158:161], v[184:187], v[114:117]
	v_mfma_f32_16x16x32_bf16 v[106:109], v[176:179], v[184:187], v[106:109]
	v_mfma_f32_16x16x32_bf16 v[98:101], v[158:161], v[192:195], v[98:101]
	v_mfma_f32_16x16x32_bf16 v[90:93], v[176:179], v[192:195], v[90:93]
	v_mfma_f32_16x16x32_bf16 v[82:85], v[158:161], v[200:203], v[82:85]
	v_mfma_f32_16x16x32_bf16 v[74:77], v[176:179], v[200:203], v[74:77]
	v_mfma_f32_16x16x32_bf16 v[70:73], v[158:161], v[208:211], v[70:73]
	v_mfma_f32_16x16x32_bf16 v[66:69], v[176:179], v[208:211], v[66:69]
	v_mfma_f32_16x16x32_bf16 v[114:117], v[172:175], v[188:191], v[114:117]
	v_mfma_f32_16x16x32_bf16 v[106:109], v[180:183], v[188:191], v[106:109]
	v_mfma_f32_16x16x32_bf16 v[98:101], v[172:175], v[196:199], v[98:101]
	v_mfma_f32_16x16x32_bf16 v[90:93], v[180:183], v[196:199], v[90:93]
	v_mfma_f32_16x16x32_bf16 v[82:85], v[172:175], v[204:207], v[82:85]
	v_mfma_f32_16x16x32_bf16 v[74:77], v[180:183], v[204:207], v[74:77]
	v_mfma_f32_16x16x32_bf16 v[70:73], v[172:175], v[212:215], v[70:73]
	v_mfma_f32_16x16x32_bf16 v[66:69], v[180:183], v[212:215], v[66:69]
	s_barrier
	s_mov_b32 m0, s87
	v_lshl_add_u64 v[136:137], v[136:137], 0, s[44:45]
	ds_read_b128 v[184:187], v141 offset:49152
	ds_read_b128 v[188:191], v141 offset:50176
	ds_read_b128 v[192:195], v141 offset:51200
	ds_read_b128 v[196:199], v141 offset:52224
	ds_read_b128 v[200:203], v141 offset:53248
	ds_read_b128 v[204:207], v141 offset:54272
	ds_read_b128 v[208:211], v141 offset:55296
	ds_read_b128 v[212:215], v141 offset:56320
	global_load_lds_dwordx4 v[136:137], off
	v_lshl_add_u64 v[136:137], v[168:169], 0, s[44:45]
	s_mov_b32 m0, s86
	s_nop 0
	global_load_lds_dwordx4 v[136:137], off
	v_lshl_add_u64 v[136:137], s[58:59], 0, v[162:163]
	s_mov_b32 m0, s38
	s_nop 0
	global_load_lds_dwordx4 v[136:137], off
	v_lshl_add_u64 v[136:137], s[58:59], 0, v[134:135]
	s_mov_b32 m0, s37
	s_nop 0
	global_load_lds_dwordx4 v[136:137], off
	v_lshl_add_u64 v[136:137], v[170:171], 0, s[44:45]
	s_mov_b32 m0, s76
	s_nop 0
	global_load_lds_dwordx4 v[136:137], off
	v_lshl_add_u64 v[136:137], v[216:217], 0, s[44:45]
	s_mov_b32 m0, s77
	s_nop 0
	global_load_lds_dwordx4 v[136:137], off
	s_waitcnt vmcnt(8)
	s_waitcnt lgkmcnt(0)
	s_barrier
	v_mfma_f32_16x16x32_bf16 v[62:65], v[142:145], v[184:187], v[62:65]
	v_mfma_f32_16x16x32_bf16 v[58:61], v[150:153], v[184:187], v[58:61]
	v_mfma_f32_16x16x32_bf16 v[54:57], v[142:145], v[192:195], v[54:57]
	v_mfma_f32_16x16x32_bf16 v[46:49], v[150:153], v[192:195], v[46:49]
	v_mfma_f32_16x16x32_bf16 v[38:41], v[142:145], v[200:203], v[38:41]
	v_mfma_f32_16x16x32_bf16 v[30:33], v[150:153], v[200:203], v[30:33]
	v_mfma_f32_16x16x32_bf16 v[22:25], v[142:145], v[208:211], v[22:25]
	v_mfma_f32_16x16x32_bf16 v[14:17], v[150:153], v[208:211], v[14:17]
	v_mfma_f32_16x16x32_bf16 v[62:65], v[146:149], v[188:191], v[62:65]
	v_mfma_f32_16x16x32_bf16 v[58:61], v[154:157], v[188:191], v[58:61]
	v_mfma_f32_16x16x32_bf16 v[54:57], v[146:149], v[196:199], v[54:57]
	v_mfma_f32_16x16x32_bf16 v[46:49], v[154:157], v[196:199], v[46:49]
	v_mfma_f32_16x16x32_bf16 v[38:41], v[146:149], v[204:207], v[38:41]
	v_mfma_f32_16x16x32_bf16 v[30:33], v[154:157], v[204:207], v[30:33]
	v_mfma_f32_16x16x32_bf16 v[22:25], v[146:149], v[212:215], v[22:25]
	v_mfma_f32_16x16x32_bf16 v[14:17], v[154:157], v[212:215], v[14:17]
	v_mfma_f32_16x16x32_bf16 v[50:53], v[158:161], v[184:187], v[50:53]
	v_mfma_f32_16x16x32_bf16 v[42:45], v[176:179], v[184:187], v[42:45]
	v_mfma_f32_16x16x32_bf16 v[34:37], v[158:161], v[192:195], v[34:37]
	v_mfma_f32_16x16x32_bf16 v[26:29], v[176:179], v[192:195], v[26:29]
	v_mfma_f32_16x16x32_bf16 v[18:21], v[158:161], v[200:203], v[18:21]
	v_mfma_f32_16x16x32_bf16 v[10:13], v[176:179], v[200:203], v[10:13]
	v_mfma_f32_16x16x32_bf16 v[6:9], v[158:161], v[208:211], v[6:9]
	v_mfma_f32_16x16x32_bf16 v[2:5], v[176:179], v[208:211], v[2:5]
	v_mfma_f32_16x16x32_bf16 v[50:53], v[172:175], v[188:191], v[50:53]
	v_mfma_f32_16x16x32_bf16 v[42:45], v[180:183], v[188:191], v[42:45]
	v_mfma_f32_16x16x32_bf16 v[34:37], v[172:175], v[196:199], v[34:37]
	v_mfma_f32_16x16x32_bf16 v[26:29], v[180:183], v[196:199], v[26:29]
	v_mfma_f32_16x16x32_bf16 v[18:21], v[172:175], v[204:207], v[18:21]
	v_mfma_f32_16x16x32_bf16 v[10:13], v[180:183], v[204:207], v[10:13]
	v_mfma_f32_16x16x32_bf16 v[6:9], v[172:175], v[212:215], v[6:9]
	v_mfma_f32_16x16x32_bf16 v[2:5], v[180:183], v[212:215], v[2:5]
	s_barrier
	s_movk_i32 s60, 0x100
	s_andn2_b64 vcc, exec, s[56:57]
	s_mov_b64 s[58:59], -1
	s_mov_b64 s[56:57], 0
	s_cbranch_vccz .LBB0_1574
	s_and_b64 vcc, exec, s[18:19]
	s_cbranch_vccz .LBB0_1577
	s_barrier

.LBB0_1615:
	s_add_u32 s31, s64, 0xfffc0080
	s_addc_u32 s36, s65, -1
	s_add_i32 s37, 0, 0x10000
	s_cmp_eq_u32 s27, 12
	s_cselect_b32 vcc_hi, s57, s36
	s_cselect_b32 vcc_lo, s56, s31
	s_cselect_b32 s67, s59, s26
	s_cselect_b32 s66, s58, s25
	s_add_i32 s31, 0, 0x14000
	v_add_u32_e32 v142, s37, v201
	v_add_u32_e32 v158, s31, v201
	ds_read_b128 v[66:69], v142
	ds_read_b128 v[70:73], v142 offset:1024
	ds_read_b128 v[138:141], v142 offset:2048
	ds_read_b128 v[142:145], v142 offset:3072
	ds_read_b128 v[146:149], v158
	ds_read_b128 v[150:153], v158 offset:1024
	ds_read_b128 v[154:157], v158 offset:2048
	ds_read_b128 v[158:161], v158 offset:3072
	v_lshl_add_u64 v[168:169], s[64:65], 0, v[180:181]
	s_add_i32 m0, s63, 0xc000
	ds_read_b128 v[182:185], v222
	ds_read_b128 v[186:189], v222 offset:1024
	ds_read_b128 v[190:193], v222 offset:2048
	ds_read_b128 v[202:205], v222 offset:3072
	ds_read_b128 v[206:209], v222 offset:4096
	ds_read_b128 v[210:213], v222 offset:5120
	ds_read_b128 v[224:227], v222 offset:6144
	ds_read_b128 v[228:231], v222 offset:7168
	global_load_lds_dwordx4 v[168:169], off
	v_lshl_add_u64 v[168:169], s[64:65], 0, v[178:179]
	s_add_i32 m0, s63, 0xe000
	s_nop 0
	global_load_lds_dwordx4 v[168:169], off
	s_waitcnt vmcnt(8)
	s_waitcnt lgkmcnt(0)
	s_barrier
	v_mfma_i32_16x16x64_i8 v[134:137], v[66:69], v[182:185], v[134:137]
	v_mfma_i32_16x16x64_i8 v[130:133], v[138:141], v[182:185], v[130:133]
	v_mfma_i32_16x16x64_i8 v[126:129], v[66:69], v[190:193], v[126:129]
	v_mfma_i32_16x16x64_i8 v[122:125], v[138:141], v[190:193], v[122:125]
	v_mfma_i32_16x16x64_i8 v[118:121], v[66:69], v[206:209], v[118:121]
	v_mfma_i32_16x16x64_i8 v[114:117], v[138:141], v[206:209], v[114:117]
	v_mfma_i32_16x16x64_i8 v[78:81], v[66:69], v[224:227], v[78:81]
	v_mfma_i32_16x16x64_i8 v[74:77], v[138:141], v[224:227], v[74:77]
	v_mfma_i32_16x16x64_i8 v[134:137], v[70:73], v[186:189], v[134:137]
	v_mfma_i32_16x16x64_i8 v[130:133], v[142:145], v[186:189], v[130:133]
	v_mfma_i32_16x16x64_i8 v[126:129], v[70:73], v[202:205], v[126:129]
	v_mfma_i32_16x16x64_i8 v[122:125], v[142:145], v[202:205], v[122:125]
	v_mfma_i32_16x16x64_i8 v[118:121], v[70:73], v[210:213], v[118:121]
	v_mfma_i32_16x16x64_i8 v[114:117], v[142:145], v[210:213], v[114:117]
	v_mfma_i32_16x16x64_i8 v[78:81], v[70:73], v[228:231], v[78:81]
	v_mfma_i32_16x16x64_i8 v[74:77], v[142:145], v[228:231], v[74:77]
	v_mfma_i32_16x16x64_i8 v[110:113], v[146:149], v[182:185], v[110:113]
	v_mfma_i32_16x16x64_i8 v[106:109], v[154:157], v[182:185], v[106:109]
	v_mfma_i32_16x16x64_i8 v[102:105], v[146:149], v[190:193], v[102:105]
	v_mfma_i32_16x16x64_i8 v[98:101], v[154:157], v[190:193], v[98:101]
	v_mfma_i32_16x16x64_i8 v[94:97], v[146:149], v[206:209], v[94:97]
	v_mfma_i32_16x16x64_i8 v[90:93], v[154:157], v[206:209], v[90:93]
	v_mfma_i32_16x16x64_i8 v[86:89], v[146:149], v[224:227], v[86:89]
	v_mfma_i32_16x16x64_i8 v[82:85], v[154:157], v[224:227], v[82:85]
	v_mfma_i32_16x16x64_i8 v[110:113], v[150:153], v[186:189], v[110:113]
	v_mfma_i32_16x16x64_i8 v[106:109], v[158:161], v[186:189], v[106:109]
	v_mfma_i32_16x16x64_i8 v[102:105], v[150:153], v[202:205], v[102:105]
	v_mfma_i32_16x16x64_i8 v[98:101], v[158:161], v[202:205], v[98:101]
	v_mfma_i32_16x16x64_i8 v[94:97], v[150:153], v[210:213], v[94:97]
	v_mfma_i32_16x16x64_i8 v[90:93], v[158:161], v[210:213], v[90:93]
	v_mfma_i32_16x16x64_i8 v[86:89], v[150:153], v[228:231], v[86:89]
	v_mfma_i32_16x16x64_i8 v[82:85], v[158:161], v[228:231], v[82:85]
	s_barrier
	s_add_i32 s36, s37, s61
	v_lshl_add_u64 v[168:169], s[66:67], 0, v[162:163]
	s_mov_b32 m0, s36
	ds_read_b128 v[182:185], v222 offset:16384
	ds_read_b128 v[186:189], v222 offset:17408
	ds_read_b128 v[190:193], v222 offset:18432
	ds_read_b128 v[202:205], v222 offset:19456
	ds_read_b128 v[206:209], v222 offset:20480
	ds_read_b128 v[210:213], v222 offset:21504
	ds_read_b128 v[224:227], v222 offset:22528
	ds_read_b128 v[228:231], v222 offset:23552
	global_load_lds_dwordx4 v[168:169], off
	s_add_i32 m0, s36, 0x2000
	s_add_u32 s36, s66, 0x90000
	v_lshl_add_u64 v[170:171], s[66:67], 0, v[176:177]
	s_addc_u32 s37, s67, 0
	s_add_i32 s31, s31, s61
	global_load_lds_dwordx4 v[170:171], off
	v_lshl_add_u64 v[214:215], s[36:37], 0, v[162:163]
	s_mov_b32 m0, s31
	v_lshl_add_u64 v[232:233], vcc, 0, v[174:175]
	global_load_lds_dwordx4 v[214:215], off
	v_lshl_add_u64 v[214:215], s[36:37], 0, v[176:177]
	s_add_i32 m0, s31, 0x2000
	s_nop 0
	global_load_lds_dwordx4 v[214:215], off
	v_lshl_add_u64 v[214:215], vcc, 0, v[172:173]
	s_mov_b32 m0, s63
	s_nop 0
	global_load_lds_dwordx4 v[214:215], off
	s_mov_b32 m0, s78
	s_nop 0
	global_load_lds_dwordx4 v[232:233], off
	s_waitcnt vmcnt(8)
	s_waitcnt lgkmcnt(0)
	s_barrier
	v_mfma_i32_16x16x64_i8 v[62:65], v[66:69], v[182:185], v[62:65]
	v_mfma_i32_16x16x64_i8 v[58:61], v[138:141], v[182:185], v[58:61]
	v_mfma_i32_16x16x64_i8 v[54:57], v[66:69], v[190:193], v[54:57]
	v_mfma_i32_16x16x64_i8 v[50:53], v[138:141], v[190:193], v[50:53]
	v_mfma_i32_16x16x64_i8 v[46:49], v[66:69], v[206:209], v[46:49]
	v_mfma_i32_16x16x64_i8 v[42:45], v[138:141], v[206:209], v[42:45]
	v_mfma_i32_16x16x64_i8 v[38:41], v[66:69], v[224:227], v[38:41]
	v_mfma_i32_16x16x64_i8 v[34:37], v[138:141], v[224:227], v[34:37]
	v_mfma_i32_16x16x64_i8 v[62:65], v[70:73], v[186:189], v[62:65]
	v_mfma_i32_16x16x64_i8 v[58:61], v[142:145], v[186:189], v[58:61]
	v_mfma_i32_16x16x64_i8 v[54:57], v[70:73], v[202:205], v[54:57]
	v_mfma_i32_16x16x64_i8 v[50:53], v[142:145], v[202:205], v[50:53]
	v_mfma_i32_16x16x64_i8 v[46:49], v[70:73], v[210:213], v[46:49]
	v_mfma_i32_16x16x64_i8 v[42:45], v[142:145], v[210:213], v[42:45]
	v_mfma_i32_16x16x64_i8 v[38:41], v[70:73], v[228:231], v[38:41]
	v_mfma_i32_16x16x64_i8 v[34:37], v[142:145], v[228:231], v[34:37]
	v_mfma_i32_16x16x64_i8 v[30:33], v[146:149], v[182:185], v[30:33]
	v_mfma_i32_16x16x64_i8 v[26:29], v[154:157], v[182:185], v[26:29]
	v_mfma_i32_16x16x64_i8 v[22:25], v[146:149], v[190:193], v[22:25]
	v_mfma_i32_16x16x64_i8 v[18:21], v[154:157], v[190:193], v[18:21]
	v_mfma_i32_16x16x64_i8 v[14:17], v[146:149], v[206:209], v[14:17]
	v_mfma_i32_16x16x64_i8 v[10:13], v[154:157], v[206:209], v[10:13]
	v_mfma_i32_16x16x64_i8 v[6:9], v[146:149], v[224:227], v[6:9]
	v_mfma_i32_16x16x64_i8 v[2:5], v[154:157], v[224:227], v[2:5]
	v_mfma_i32_16x16x64_i8 v[30:33], v[150:153], v[186:189], v[30:33]
	v_mfma_i32_16x16x64_i8 v[26:29], v[158:161], v[186:189], v[26:29]
	v_mfma_i32_16x16x64_i8 v[22:25], v[150:153], v[202:205], v[22:25]
	v_mfma_i32_16x16x64_i8 v[18:21], v[158:161], v[202:205], v[18:21]
	v_mfma_i32_16x16x64_i8 v[14:17], v[150:153], v[210:213], v[14:17]
	v_mfma_i32_16x16x64_i8 v[10:13], v[158:161], v[210:213], v[10:13]
	v_mfma_i32_16x16x64_i8 v[6:9], v[150:153], v[228:231], v[6:9]
	v_mfma_i32_16x16x64_i8 v[2:5], v[158:161], v[228:231], v[2:5]
	s_barrier
	s_add_i32 s31, 0, 0x18000
	s_add_i32 s38, 0, 0x1c000
	v_add_u32_e32 v142, s31, v201
	v_add_u32_e32 v158, s38, v201
	ds_read_b128 v[66:69], v142
	ds_read_b128 v[70:73], v142 offset:1024
	ds_read_b128 v[138:141], v142 offset:2048
	ds_read_b128 v[142:145], v142 offset:3072
	ds_read_b128 v[146:149], v158
	ds_read_b128 v[150:153], v158 offset:1024
	ds_read_b128 v[154:157], v158 offset:2048
	ds_read_b128 v[158:161], v158 offset:3072
	s_add_u32 s36, vcc_lo, 0x40000
	s_addc_u32 s37, vcc_hi, 0
	s_mov_b32 m0, s79
	v_lshl_add_u64 v[234:235], s[36:37], 0, v[172:173]
	ds_read_b128 v[182:185], v222 offset:32768
	ds_read_b128 v[186:189], v222 offset:33792
	ds_read_b128 v[190:193], v222 offset:34816
	ds_read_b128 v[202:205], v222 offset:35840
	ds_read_b128 v[206:209], v222 offset:36864
	ds_read_b128 v[210:213], v222 offset:37888
	ds_read_b128 v[224:227], v222 offset:38912
	ds_read_b128 v[228:231], v222 offset:39936
	global_load_lds_dwordx4 v[234:235], off
	v_lshl_add_u64 v[234:235], s[36:37], 0, v[174:175]
	s_mov_b32 m0, s80
	s_nop 0
	global_load_lds_dwordx4 v[234:235], off
	s_waitcnt vmcnt(8)
	s_waitcnt lgkmcnt(0)
	s_barrier
	v_mfma_i32_16x16x64_i8 v[134:137], v[66:69], v[182:185], v[134:137]
	v_mfma_i32_16x16x64_i8 v[130:133], v[138:141], v[182:185], v[130:133]
	v_mfma_i32_16x16x64_i8 v[126:129], v[66:69], v[190:193], v[126:129]
	v_mfma_i32_16x16x64_i8 v[122:125], v[138:141], v[190:193], v[122:125]
	v_mfma_i32_16x16x64_i8 v[118:121], v[66:69], v[206:209], v[118:121]
	v_mfma_i32_16x16x64_i8 v[114:117], v[138:141], v[206:209], v[114:117]
	v_mfma_i32_16x16x64_i8 v[78:81], v[66:69], v[224:227], v[78:81]
	v_mfma_i32_16x16x64_i8 v[74:77], v[138:141], v[224:227], v[74:77]
	v_mfma_i32_16x16x64_i8 v[134:137], v[70:73], v[186:189], v[134:137]
	v_mfma_i32_16x16x64_i8 v[130:133], v[142:145], v[186:189], v[130:133]
	v_mfma_i32_16x16x64_i8 v[126:129], v[70:73], v[202:205], v[126:129]
	v_mfma_i32_16x16x64_i8 v[122:125], v[142:145], v[202:205], v[122:125]
	v_mfma_i32_16x16x64_i8 v[118:121], v[70:73], v[210:213], v[118:121]
	v_mfma_i32_16x16x64_i8 v[114:117], v[142:145], v[210:213], v[114:117]
	v_mfma_i32_16x16x64_i8 v[78:81], v[70:73], v[228:231], v[78:81]
	v_mfma_i32_16x16x64_i8 v[74:77], v[142:145], v[228:231], v[74:77]
	v_mfma_i32_16x16x64_i8 v[110:113], v[146:149], v[182:185], v[110:113]
	v_mfma_i32_16x16x64_i8 v[106:109], v[154:157], v[182:185], v[106:109]
	v_mfma_i32_16x16x64_i8 v[102:105], v[146:149], v[190:193], v[102:105]
	v_mfma_i32_16x16x64_i8 v[98:101], v[154:157], v[190:193], v[98:101]
	v_mfma_i32_16x16x64_i8 v[94:97], v[146:149], v[206:209], v[94:97]
	v_mfma_i32_16x16x64_i8 v[90:93], v[154:157], v[206:209], v[90:93]
	v_mfma_i32_16x16x64_i8 v[86:89], v[146:149], v[224:227], v[86:89]
	v_mfma_i32_16x16x64_i8 v[82:85], v[154:157], v[224:227], v[82:85]
	v_mfma_i32_16x16x64_i8 v[110:113], v[150:153], v[186:189], v[110:113]
	v_mfma_i32_16x16x64_i8 v[106:109], v[158:161], v[186:189], v[106:109]
	v_mfma_i32_16x16x64_i8 v[102:105], v[150:153], v[202:205], v[102:105]
	v_mfma_i32_16x16x64_i8 v[98:101], v[158:161], v[202:205], v[98:101]
	v_mfma_i32_16x16x64_i8 v[94:97], v[150:153], v[210:213], v[94:97]
	v_mfma_i32_16x16x64_i8 v[90:93], v[158:161], v[210:213], v[90:93]
	v_mfma_i32_16x16x64_i8 v[86:89], v[150:153], v[228:231], v[86:89]
	v_mfma_i32_16x16x64_i8 v[82:85], v[158:161], v[228:231], v[82:85]
	s_barrier
	s_add_i32 s31, s31, s61
	v_lshl_add_u64 v[168:169], v[168:169], 0, s[44:45]
	s_mov_b32 m0, s31
	ds_read_b128 v[182:185], v222 offset:49152
	ds_read_b128 v[186:189], v222 offset:50176
	ds_read_b128 v[190:193], v222 offset:51200
	ds_read_b128 v[202:205], v222 offset:52224
	ds_read_b128 v[206:209], v222 offset:53248
	ds_read_b128 v[210:213], v222 offset:54272
	ds_read_b128 v[224:227], v222 offset:55296
	ds_read_b128 v[228:231], v222 offset:56320
	global_load_lds_dwordx4 v[168:169], off
	s_add_i32 m0, s31, 0x2000
	s_add_u32 s36, s66, 0x90080
	v_lshl_add_u64 v[168:169], v[170:171], 0, s[44:45]
	s_addc_u32 s37, s67, 0
	s_add_i32 s31, s38, s61
	global_load_lds_dwordx4 v[168:169], off
	v_lshl_add_u64 v[168:169], s[36:37], 0, v[162:163]
	s_mov_b32 m0, s31
	s_nop 0
	global_load_lds_dwordx4 v[168:169], off
	v_lshl_add_u64 v[168:169], s[36:37], 0, v[176:177]
	s_add_i32 m0, s31, 0x2000
	s_nop 0
	global_load_lds_dwordx4 v[168:169], off
	v_lshl_add_u64 v[168:169], v[214:215], 0, s[44:45]
	s_mov_b32 m0, s82
	s_nop 0
	global_load_lds_dwordx4 v[168:169], off
	v_lshl_add_u64 v[168:169], v[232:233], 0, s[44:45]
	s_mov_b32 m0, s83
	s_nop 0
	global_load_lds_dwordx4 v[168:169], off
	s_waitcnt vmcnt(8)
	s_waitcnt lgkmcnt(0)
	s_barrier
	v_mfma_i32_16x16x64_i8 v[62:65], v[66:69], v[182:185], v[62:65]
	v_mfma_i32_16x16x64_i8 v[58:61], v[138:141], v[182:185], v[58:61]
	v_mfma_i32_16x16x64_i8 v[54:57], v[66:69], v[190:193], v[54:57]
	v_mfma_i32_16x16x64_i8 v[50:53], v[138:141], v[190:193], v[50:53]
	v_mfma_i32_16x16x64_i8 v[46:49], v[66:69], v[206:209], v[46:49]
	v_mfma_i32_16x16x64_i8 v[42:45], v[138:141], v[206:209], v[42:45]
	v_mfma_i32_16x16x64_i8 v[38:41], v[66:69], v[224:227], v[38:41]
	v_mfma_i32_16x16x64_i8 v[34:37], v[138:141], v[224:227], v[34:37]
	v_mfma_i32_16x16x64_i8 v[62:65], v[70:73], v[186:189], v[62:65]
	v_mfma_i32_16x16x64_i8 v[58:61], v[142:145], v[186:189], v[58:61]
	v_mfma_i32_16x16x64_i8 v[54:57], v[70:73], v[202:205], v[54:57]
	v_mfma_i32_16x16x64_i8 v[50:53], v[142:145], v[202:205], v[50:53]
	v_mfma_i32_16x16x64_i8 v[46:49], v[70:73], v[210:213], v[46:49]
	v_mfma_i32_16x16x64_i8 v[42:45], v[142:145], v[210:213], v[42:45]
	v_mfma_i32_16x16x64_i8 v[38:41], v[70:73], v[228:231], v[38:41]
	v_mfma_i32_16x16x64_i8 v[34:37], v[142:145], v[228:231], v[34:37]
	v_mfma_i32_16x16x64_i8 v[30:33], v[146:149], v[182:185], v[30:33]
	v_mfma_i32_16x16x64_i8 v[26:29], v[154:157], v[182:185], v[26:29]
	v_mfma_i32_16x16x64_i8 v[22:25], v[146:149], v[190:193], v[22:25]
	v_mfma_i32_16x16x64_i8 v[18:21], v[154:157], v[190:193], v[18:21]
	v_mfma_i32_16x16x64_i8 v[14:17], v[146:149], v[206:209], v[14:17]
	v_mfma_i32_16x16x64_i8 v[10:13], v[154:157], v[206:209], v[10:13]
	v_mfma_i32_16x16x64_i8 v[6:9], v[146:149], v[224:227], v[6:9]
	v_mfma_i32_16x16x64_i8 v[2:5], v[154:157], v[224:227], v[2:5]
	v_mfma_i32_16x16x64_i8 v[30:33], v[150:153], v[186:189], v[30:33]
	v_mfma_i32_16x16x64_i8 v[26:29], v[158:161], v[186:189], v[26:29]
	v_mfma_i32_16x16x64_i8 v[22:25], v[150:153], v[202:205], v[22:25]
	v_mfma_i32_16x16x64_i8 v[18:21], v[158:161], v[202:205], v[18:21]
	v_mfma_i32_16x16x64_i8 v[14:17], v[150:153], v[210:213], v[14:17]
	v_mfma_i32_16x16x64_i8 v[10:13], v[158:161], v[210:213], v[10:13]
	v_mfma_i32_16x16x64_i8 v[6:9], v[150:153], v[228:231], v[6:9]
	v_mfma_i32_16x16x64_i8 v[2:5], v[158:161], v[228:231], v[2:5]
	s_barrier
	s_add_i32 s27, s27, 2
	s_add_u32 s25, s25, 0x100
	s_addc_u32 s26, s26, 0
	s_add_u32 s64, s64, 0x100
	s_addc_u32 s65, s65, 0
	s_cmp_gt_u32 s27, 13
	s_cbranch_scc0 .LBB0_1615
	s_and_b64 vcc, exec, s[22:23]
	s_cbranch_vccz .LBB0_1618
	s_barrier
